# phase-1 load segment: the eight B-fragment ds_reads hoisted above the scalar pointer selects (all 16 fragment reads issue back to back)
# baseline (speedup 1.0000x reference)
.LBB0_141:
	s_lshl_b32 s34, s11, 8
	s_ashr_i32 s35, s34, 31
	s_lshl_b64 s[34:35], s[34:35], 11
	s_add_u32 s82, s49, s34
	s_addc_u32 s83, s53, s35
	s_and_b64 s[34:35], s[0:1], exec
	s_cselect_b32 s5, s83, s7
	s_cselect_b32 s22, s82, s6
	s_ashr_i32 s81, s80, 31
	s_lshl_b64 s[34:35], s[80:81], 19
	s_add_u32 s84, s55, s34
	s_addc_u32 s85, s57, s35
	s_and_b64 s[34:35], s[0:1], exec
	s_cselect_b32 s34, s85, s9
	s_cselect_b32 s35, s84, s8
	s_add_u32 s40, s8, 0x100
	s_addc_u32 s41, s9, 0
	s_mov_b32 s50, -2
	s_waitcnt vmcnt(0)
	s_waitcnt lgkmcnt(0)
	ds_read_b128 v[128:131], v175
	ds_read_b128 v[132:135], v175 offset:1024
	ds_read_b128 v[136:139], v175 offset:2048
	ds_read_b128 v[140:143], v175 offset:3072
	ds_read_b128 v[166:169], v176
	ds_read_b128 v[170:173], v176 offset:1024
	ds_read_b128 v[182:185], v176 offset:2048
	ds_read_b128 v[186:189], v176 offset:3072
	ds_read_b128 v[190:193], v177
	ds_read_b128 v[194:197], v177 offset:1024
	ds_read_b128 v[198:201], v177 offset:2048
	ds_read_b128 v[202:205], v177 offset:3072
	ds_read_b128 v[206:209], v177 offset:4096
	ds_read_b128 v[210:213], v177 offset:5120
	ds_read_b128 v[214:217], v177 offset:6144
	ds_read_b128 v[224:227], v177 offset:7168
	s_add_u32 s8, s6, 0x100
	s_addc_u32 s9, s7, 0
	s_cmp_eq_u32 s50, 12
	s_cselect_b32 s89, s5, s9
	s_cselect_b32 s88, s22, s8
	s_cselect_b32 s87, s34, s41
	s_cselect_b32 s86, s35, s40
	s_add_i32 m0, s61, 0xc000
	v_lshl_add_u64 v[220:221], s[6:7], 0, v[158:159]
	global_load_lds_dwordx4 v[220:221], off
	s_add_i32 m0, s61, 0xe000
	v_lshl_add_u64 v[220:221], s[6:7], 0, v[160:161]
	global_load_lds_dwordx4 v[220:221], off
	s_waitcnt vmcnt(8) lgkmcnt(0)
	s_setprio 1
	s_barrier
	v_mfma_f32_16x16x32_bf16 v[124:127], v[128:131], v[190:193], 0
	v_mfma_f32_16x16x32_bf16 v[120:123], v[136:139], v[190:193], 0
	v_mfma_f32_16x16x32_bf16 v[108:111], v[128:131], v[198:201], 0
	v_mfma_f32_16x16x32_bf16 v[104:107], v[136:139], v[198:201], 0
	v_mfma_f32_16x16x32_bf16 v[92:95], v[128:131], v[206:209], 0
	v_mfma_f32_16x16x32_bf16 v[88:91], v[136:139], v[206:209], 0
	v_mfma_f32_16x16x32_bf16 v[76:79], v[128:131], v[214:217], 0
	v_mfma_f32_16x16x32_bf16 v[72:75], v[136:139], v[214:217], 0
	v_mfma_f32_16x16x32_bf16 v[124:127], v[132:135], v[194:197], v[124:127]
	v_mfma_f32_16x16x32_bf16 v[120:123], v[140:143], v[194:197], v[120:123]
	v_mfma_f32_16x16x32_bf16 v[108:111], v[132:135], v[202:205], v[108:111]
	v_mfma_f32_16x16x32_bf16 v[104:107], v[140:143], v[202:205], v[104:107]
	v_mfma_f32_16x16x32_bf16 v[92:95], v[132:135], v[210:213], v[92:95]
	v_mfma_f32_16x16x32_bf16 v[88:91], v[140:143], v[210:213], v[88:91]
	v_mfma_f32_16x16x32_bf16 v[76:79], v[132:135], v[224:227], v[76:79]
	v_mfma_f32_16x16x32_bf16 v[72:75], v[140:143], v[224:227], v[72:75]
	v_mfma_f32_16x16x32_bf16 v[116:119], v[166:169], v[190:193], 0
	v_mfma_f32_16x16x32_bf16 v[112:115], v[182:185], v[190:193], 0
	v_mfma_f32_16x16x32_bf16 v[100:103], v[166:169], v[198:201], 0
	v_mfma_f32_16x16x32_bf16 v[96:99], v[182:185], v[198:201], 0
	v_mfma_f32_16x16x32_bf16 v[84:87], v[166:169], v[206:209], 0
	v_mfma_f32_16x16x32_bf16 v[80:83], v[182:185], v[206:209], 0
	v_mfma_f32_16x16x32_bf16 v[68:71], v[166:169], v[214:217], 0
	v_mfma_f32_16x16x32_bf16 v[64:67], v[182:185], v[214:217], 0
	v_mfma_f32_16x16x32_bf16 v[116:119], v[170:173], v[194:197], v[116:119]
	v_mfma_f32_16x16x32_bf16 v[112:115], v[186:189], v[194:197], v[112:115]
	v_mfma_f32_16x16x32_bf16 v[100:103], v[170:173], v[202:205], v[100:103]
	v_mfma_f32_16x16x32_bf16 v[96:99], v[186:189], v[202:205], v[96:99]
	v_mfma_f32_16x16x32_bf16 v[84:87], v[170:173], v[210:213], v[84:87]
	v_mfma_f32_16x16x32_bf16 v[80:83], v[186:189], v[210:213], v[80:83]
	v_mfma_f32_16x16x32_bf16 v[68:71], v[170:173], v[224:227], v[68:71]
	v_mfma_f32_16x16x32_bf16 v[64:67], v[186:189], v[224:227], v[64:67]
	s_barrier
	s_setprio 0
	s_add_i32 s6, s37, s59
	v_lshl_add_u64 v[220:221], s[86:87], 0, v[148:149]
	s_mov_b32 m0, s6
	ds_read_b128 v[190:193], v177 offset:16384
	ds_read_b128 v[194:197], v177 offset:17408
	ds_read_b128 v[198:201], v177 offset:18432
	ds_read_b128 v[202:205], v177 offset:19456
	ds_read_b128 v[206:209], v177 offset:20480
	ds_read_b128 v[210:213], v177 offset:21504
	ds_read_b128 v[214:217], v177 offset:22528
	ds_read_b128 v[224:227], v177 offset:23552
	global_load_lds_dwordx4 v[220:221], off
	s_add_i32 m0, s6, 0x2000
	s_add_u32 s6, s86, 0x40000
	v_lshl_add_u64 v[228:229], s[86:87], 0, v[152:153]
	s_addc_u32 s7, s87, 0
	s_add_i32 s51, s97, s59
	global_load_lds_dwordx4 v[228:229], off
	v_lshl_add_u64 v[230:231], s[6:7], 0, v[148:149]
	s_mov_b32 m0, s51
	v_lshl_add_u64 v[232:233], s[88:89], 0, v[150:151]
	global_load_lds_dwordx4 v[230:231], off
	v_lshl_add_u64 v[230:231], s[6:7], 0, v[152:153]
	s_add_i32 m0, s51, 0x2000
	v_lshl_add_u64 v[234:235], v[232:233], 0, s[68:69]
	global_load_lds_dwordx4 v[230:231], off
	s_mov_b32 m0, s61
	v_lshl_add_u64 v[230:231], s[88:89], 0, v[146:147]
	global_load_lds_dwordx4 v[230:231], off
	s_mov_b32 m0, s63
	s_nop 0
	global_load_lds_dwordx4 v[234:235], off
	s_waitcnt vmcnt(8) lgkmcnt(0)
	s_setprio 1
	s_barrier
	v_mfma_f32_16x16x32_bf16 v[60:63], v[128:131], v[190:193], 0
	v_mfma_f32_16x16x32_bf16 v[56:59], v[136:139], v[190:193], 0
	v_mfma_f32_16x16x32_bf16 v[44:47], v[128:131], v[198:201], 0
	v_mfma_f32_16x16x32_bf16 v[40:43], v[136:139], v[198:201], 0
	v_mfma_f32_16x16x32_bf16 v[28:31], v[128:131], v[206:209], 0
	v_mfma_f32_16x16x32_bf16 v[24:27], v[136:139], v[206:209], 0
	v_mfma_f32_16x16x32_bf16 v[12:15], v[128:131], v[214:217], 0
	v_mfma_f32_16x16x32_bf16 v[8:11], v[136:139], v[214:217], 0
	v_mfma_f32_16x16x32_bf16 v[60:63], v[132:135], v[194:197], v[60:63]
	v_mfma_f32_16x16x32_bf16 v[56:59], v[140:143], v[194:197], v[56:59]
	v_mfma_f32_16x16x32_bf16 v[44:47], v[132:135], v[202:205], v[44:47]
	v_mfma_f32_16x16x32_bf16 v[40:43], v[140:143], v[202:205], v[40:43]
	v_mfma_f32_16x16x32_bf16 v[28:31], v[132:135], v[210:213], v[28:31]
	v_mfma_f32_16x16x32_bf16 v[24:27], v[140:143], v[210:213], v[24:27]
	v_mfma_f32_16x16x32_bf16 v[12:15], v[132:135], v[224:227], v[12:15]
	v_mfma_f32_16x16x32_bf16 v[8:11], v[140:143], v[224:227], v[8:11]
	v_mfma_f32_16x16x32_bf16 v[52:55], v[166:169], v[190:193], 0
	v_mfma_f32_16x16x32_bf16 v[48:51], v[182:185], v[190:193], 0
	v_mfma_f32_16x16x32_bf16 v[36:39], v[166:169], v[198:201], 0
	v_mfma_f32_16x16x32_bf16 v[32:35], v[182:185], v[198:201], 0
	v_mfma_f32_16x16x32_bf16 v[20:23], v[166:169], v[206:209], 0
	v_mfma_f32_16x16x32_bf16 v[16:19], v[182:185], v[206:209], 0
	v_mfma_f32_16x16x32_bf16 v[4:7], v[166:169], v[214:217], 0
	v_mfma_f32_16x16x32_bf16 v[0:3], v[182:185], v[214:217], 0
	v_mfma_f32_16x16x32_bf16 v[52:55], v[170:173], v[194:197], v[52:55]
	v_mfma_f32_16x16x32_bf16 v[48:51], v[186:189], v[194:197], v[48:51]
	v_mfma_f32_16x16x32_bf16 v[36:39], v[170:173], v[202:205], v[36:39]
	v_mfma_f32_16x16x32_bf16 v[32:35], v[186:189], v[202:205], v[32:35]
	v_mfma_f32_16x16x32_bf16 v[20:23], v[170:173], v[210:213], v[20:23]
	v_mfma_f32_16x16x32_bf16 v[16:19], v[186:189], v[210:213], v[16:19]
	v_mfma_f32_16x16x32_bf16 v[4:7], v[170:173], v[224:227], v[4:7]
	v_mfma_f32_16x16x32_bf16 v[0:3], v[186:189], v[224:227], v[0:3]
	s_barrier
	s_setprio 0
	s_add_i32 s6, 0, 0x18000
	s_add_i32 s51, 0, 0x1c000
	v_add_u32_e32 v140, s6, v174
	v_add_u32_e32 v154, s51, v174
	ds_read_b128 v[128:131], v140
	ds_read_b128 v[132:135], v140 offset:1024
	ds_read_b128 v[136:139], v140 offset:2048
	ds_read_b128 v[140:143], v140 offset:3072
	ds_read_b128 v[166:169], v154
	ds_read_b128 v[170:173], v154 offset:1024
	ds_read_b128 v[182:185], v154 offset:2048
	ds_read_b128 v[186:189], v154 offset:3072
	s_mov_b32 m0, s65
	v_lshl_add_u64 v[234:235], v[230:231], 0, s[66:67]
	ds_read_b128 v[190:193], v177 offset:32768
	ds_read_b128 v[194:197], v177 offset:33792
	ds_read_b128 v[198:201], v177 offset:34816
	ds_read_b128 v[202:205], v177 offset:35840
	ds_read_b128 v[206:209], v177 offset:36864
	ds_read_b128 v[210:213], v177 offset:37888
	ds_read_b128 v[214:217], v177 offset:38912
	ds_read_b128 v[224:227], v177 offset:39936
	global_load_lds_dwordx4 v[234:235], off
	s_mov_b32 m0, s77
	v_lshl_add_u64 v[234:235], v[232:233], 0, s[46:47]
	global_load_lds_dwordx4 v[234:235], off
	s_waitcnt vmcnt(8) lgkmcnt(0)
	s_setprio 1
	s_barrier
	v_mfma_f32_16x16x32_bf16 v[124:127], v[128:131], v[190:193], v[124:127]
	v_mfma_f32_16x16x32_bf16 v[120:123], v[136:139], v[190:193], v[120:123]
	v_mfma_f32_16x16x32_bf16 v[108:111], v[128:131], v[198:201], v[108:111]
	v_mfma_f32_16x16x32_bf16 v[104:107], v[136:139], v[198:201], v[104:107]
	v_mfma_f32_16x16x32_bf16 v[92:95], v[128:131], v[206:209], v[92:95]
	v_mfma_f32_16x16x32_bf16 v[88:91], v[136:139], v[206:209], v[88:91]
	v_mfma_f32_16x16x32_bf16 v[76:79], v[128:131], v[214:217], v[76:79]
	v_mfma_f32_16x16x32_bf16 v[72:75], v[136:139], v[214:217], v[72:75]
	v_mfma_f32_16x16x32_bf16 v[124:127], v[132:135], v[194:197], v[124:127]
	v_mfma_f32_16x16x32_bf16 v[120:123], v[140:143], v[194:197], v[120:123]
	v_mfma_f32_16x16x32_bf16 v[108:111], v[132:135], v[202:205], v[108:111]
	v_mfma_f32_16x16x32_bf16 v[104:107], v[140:143], v[202:205], v[104:107]
	v_mfma_f32_16x16x32_bf16 v[92:95], v[132:135], v[210:213], v[92:95]
	v_mfma_f32_16x16x32_bf16 v[88:91], v[140:143], v[210:213], v[88:91]
	v_mfma_f32_16x16x32_bf16 v[76:79], v[132:135], v[224:227], v[76:79]
	v_mfma_f32_16x16x32_bf16 v[72:75], v[140:143], v[224:227], v[72:75]
	v_mfma_f32_16x16x32_bf16 v[116:119], v[166:169], v[190:193], v[116:119]
	v_mfma_f32_16x16x32_bf16 v[112:115], v[182:185], v[190:193], v[112:115]
	v_mfma_f32_16x16x32_bf16 v[100:103], v[166:169], v[198:201], v[100:103]
	v_mfma_f32_16x16x32_bf16 v[96:99], v[182:185], v[198:201], v[96:99]
	v_mfma_f32_16x16x32_bf16 v[84:87], v[166:169], v[206:209], v[84:87]
	v_mfma_f32_16x16x32_bf16 v[80:83], v[182:185], v[206:209], v[80:83]
	v_mfma_f32_16x16x32_bf16 v[68:71], v[166:169], v[214:217], v[68:71]
	v_mfma_f32_16x16x32_bf16 v[64:67], v[182:185], v[214:217], v[64:67]
	v_mfma_f32_16x16x32_bf16 v[116:119], v[170:173], v[194:197], v[116:119]
	v_mfma_f32_16x16x32_bf16 v[112:115], v[186:189], v[194:197], v[112:115]
	v_mfma_f32_16x16x32_bf16 v[100:103], v[170:173], v[202:205], v[100:103]
	v_mfma_f32_16x16x32_bf16 v[96:99], v[186:189], v[202:205], v[96:99]
	v_mfma_f32_16x16x32_bf16 v[84:87], v[170:173], v[210:213], v[84:87]
	v_mfma_f32_16x16x32_bf16 v[80:83], v[186:189], v[210:213], v[80:83]
	v_mfma_f32_16x16x32_bf16 v[68:71], v[170:173], v[224:227], v[68:71]
	v_mfma_f32_16x16x32_bf16 v[64:67], v[186:189], v[224:227], v[64:67]
	s_barrier
	s_setprio 0
	s_add_i32 s6, s6, s59
	v_lshl_add_u64 v[220:221], v[220:221], 0, s[42:43]
	s_mov_b32 m0, s6
	ds_read_b128 v[190:193], v177 offset:49152
	ds_read_b128 v[194:197], v177 offset:50176
	ds_read_b128 v[198:201], v177 offset:51200
	ds_read_b128 v[202:205], v177 offset:52224
	ds_read_b128 v[206:209], v177 offset:53248
	ds_read_b128 v[210:213], v177 offset:54272
	ds_read_b128 v[214:217], v177 offset:55296
	ds_read_b128 v[224:227], v177 offset:56320
	global_load_lds_dwordx4 v[220:221], off
	s_add_i32 m0, s6, 0x2000
	s_add_u32 s6, s86, 0x40080
	v_lshl_add_u64 v[220:221], v[228:229], 0, s[42:43]
	s_addc_u32 s7, s87, 0
	s_add_i32 s51, s51, s59
	global_load_lds_dwordx4 v[220:221], off
	s_mov_b32 m0, s51
	v_lshl_add_u64 v[220:221], s[6:7], 0, v[148:149]
	global_load_lds_dwordx4 v[220:221], off
	s_add_i32 m0, s51, 0x2000
	v_lshl_add_u64 v[220:221], s[6:7], 0, v[152:153]
	global_load_lds_dwordx4 v[220:221], off
	s_mov_b32 m0, s91
	v_lshl_add_u64 v[220:221], v[230:231], 0, s[42:43]
	global_load_lds_dwordx4 v[220:221], off
	s_mov_b32 m0, s92
	v_lshl_add_u64 v[220:221], v[232:233], 0, s[44:45]
	global_load_lds_dwordx4 v[220:221], off
	s_waitcnt vmcnt(8) lgkmcnt(0)
	s_setprio 1
	s_barrier
	v_mfma_f32_16x16x32_bf16 v[60:63], v[128:131], v[190:193], v[60:63]
	v_mfma_f32_16x16x32_bf16 v[56:59], v[136:139], v[190:193], v[56:59]
	v_mfma_f32_16x16x32_bf16 v[44:47], v[128:131], v[198:201], v[44:47]
	v_mfma_f32_16x16x32_bf16 v[40:43], v[136:139], v[198:201], v[40:43]
	v_mfma_f32_16x16x32_bf16 v[28:31], v[128:131], v[206:209], v[28:31]
	v_mfma_f32_16x16x32_bf16 v[24:27], v[136:139], v[206:209], v[24:27]
	v_mfma_f32_16x16x32_bf16 v[12:15], v[128:131], v[214:217], v[12:15]
	v_mfma_f32_16x16x32_bf16 v[8:11], v[136:139], v[214:217], v[8:11]
	v_mfma_f32_16x16x32_bf16 v[60:63], v[132:135], v[194:197], v[60:63]
	v_mfma_f32_16x16x32_bf16 v[56:59], v[140:143], v[194:197], v[56:59]
	v_mfma_f32_16x16x32_bf16 v[44:47], v[132:135], v[202:205], v[44:47]
	v_mfma_f32_16x16x32_bf16 v[40:43], v[140:143], v[202:205], v[40:43]
	v_mfma_f32_16x16x32_bf16 v[28:31], v[132:135], v[210:213], v[28:31]
	v_mfma_f32_16x16x32_bf16 v[24:27], v[140:143], v[210:213], v[24:27]
	v_mfma_f32_16x16x32_bf16 v[12:15], v[132:135], v[224:227], v[12:15]
	v_mfma_f32_16x16x32_bf16 v[8:11], v[140:143], v[224:227], v[8:11]
	v_mfma_f32_16x16x32_bf16 v[52:55], v[166:169], v[190:193], v[52:55]
	v_mfma_f32_16x16x32_bf16 v[48:51], v[182:185], v[190:193], v[48:51]
	v_mfma_f32_16x16x32_bf16 v[36:39], v[166:169], v[198:201], v[36:39]
	v_mfma_f32_16x16x32_bf16 v[32:35], v[182:185], v[198:201], v[32:35]
	v_mfma_f32_16x16x32_bf16 v[20:23], v[166:169], v[206:209], v[20:23]
	v_mfma_f32_16x16x32_bf16 v[16:19], v[182:185], v[206:209], v[16:19]
	v_mfma_f32_16x16x32_bf16 v[4:7], v[166:169], v[214:217], v[4:7]
	v_mfma_f32_16x16x32_bf16 v[0:3], v[182:185], v[214:217], v[0:3]
	v_mfma_f32_16x16x32_bf16 v[52:55], v[170:173], v[194:197], v[52:55]
	v_mfma_f32_16x16x32_bf16 v[48:51], v[186:189], v[194:197], v[48:51]
	v_mfma_f32_16x16x32_bf16 v[36:39], v[170:173], v[202:205], v[36:39]
	v_mfma_f32_16x16x32_bf16 v[32:35], v[186:189], v[202:205], v[32:35]
	v_mfma_f32_16x16x32_bf16 v[20:23], v[170:173], v[210:213], v[20:23]
	v_mfma_f32_16x16x32_bf16 v[16:19], v[186:189], v[210:213], v[16:19]
	v_mfma_f32_16x16x32_bf16 v[4:7], v[170:173], v[224:227], v[4:7]
	v_mfma_f32_16x16x32_bf16 v[0:3], v[186:189], v[224:227], v[0:3]
	s_barrier
	s_setprio 0
	s_add_i32 s50, s50, 2
	s_add_u32 s40, s40, 0x100
	s_addc_u32 s41, s41, 0
	s_cmp_gt_u32 s50, 13
	s_mov_b64 s[6:7], s[8:9]
.LBB0_142:
	ds_read_b128 v[128:131], v175
	ds_read_b128 v[132:135], v175 offset:1024
	ds_read_b128 v[136:139], v175 offset:2048
	ds_read_b128 v[140:143], v175 offset:3072
	ds_read_b128 v[166:169], v176
	ds_read_b128 v[170:173], v176 offset:1024
	ds_read_b128 v[182:185], v176 offset:2048
	ds_read_b128 v[186:189], v176 offset:3072
	ds_read_b128 v[190:193], v177
	ds_read_b128 v[194:197], v177 offset:1024
	ds_read_b128 v[198:201], v177 offset:2048
	ds_read_b128 v[202:205], v177 offset:3072
	ds_read_b128 v[206:209], v177 offset:4096
	ds_read_b128 v[210:213], v177 offset:5120
	ds_read_b128 v[214:217], v177 offset:6144
	ds_read_b128 v[224:227], v177 offset:7168
	s_add_u32 s8, s6, 0x100
	s_addc_u32 s9, s7, 0
	s_cmp_eq_u32 s50, 12
	s_cselect_b32 s89, s5, s9
	s_cselect_b32 s88, s22, s8
	s_cselect_b32 s87, s34, s41
	s_cselect_b32 s86, s35, s40
	s_add_i32 m0, s61, 0xc000
	v_lshl_add_u64 v[220:221], s[6:7], 0, v[158:159]
	global_load_lds_dwordx4 v[220:221], off
	s_add_i32 m0, s61, 0xe000
	v_lshl_add_u64 v[220:221], s[6:7], 0, v[160:161]
	global_load_lds_dwordx4 v[220:221], off
	s_waitcnt vmcnt(8) lgkmcnt(0)
	s_setprio 1
	s_barrier
	v_mfma_f32_16x16x32_bf16 v[124:127], v[128:131], v[190:193], v[124:127]
	v_mfma_f32_16x16x32_bf16 v[120:123], v[136:139], v[190:193], v[120:123]
	v_mfma_f32_16x16x32_bf16 v[108:111], v[128:131], v[198:201], v[108:111]
	v_mfma_f32_16x16x32_bf16 v[104:107], v[136:139], v[198:201], v[104:107]
	v_mfma_f32_16x16x32_bf16 v[92:95], v[128:131], v[206:209], v[92:95]
	v_mfma_f32_16x16x32_bf16 v[88:91], v[136:139], v[206:209], v[88:91]
	v_mfma_f32_16x16x32_bf16 v[76:79], v[128:131], v[214:217], v[76:79]
	v_mfma_f32_16x16x32_bf16 v[72:75], v[136:139], v[214:217], v[72:75]
	v_mfma_f32_16x16x32_bf16 v[124:127], v[132:135], v[194:197], v[124:127]
	v_mfma_f32_16x16x32_bf16 v[120:123], v[140:143], v[194:197], v[120:123]
	v_mfma_f32_16x16x32_bf16 v[108:111], v[132:135], v[202:205], v[108:111]
	v_mfma_f32_16x16x32_bf16 v[104:107], v[140:143], v[202:205], v[104:107]
	v_mfma_f32_16x16x32_bf16 v[92:95], v[132:135], v[210:213], v[92:95]
	v_mfma_f32_16x16x32_bf16 v[88:91], v[140:143], v[210:213], v[88:91]
	v_mfma_f32_16x16x32_bf16 v[76:79], v[132:135], v[224:227], v[76:79]
	v_mfma_f32_16x16x32_bf16 v[72:75], v[140:143], v[224:227], v[72:75]
	v_mfma_f32_16x16x32_bf16 v[116:119], v[166:169], v[190:193], v[116:119]
	v_mfma_f32_16x16x32_bf16 v[112:115], v[182:185], v[190:193], v[112:115]
	v_mfma_f32_16x16x32_bf16 v[100:103], v[166:169], v[198:201], v[100:103]
	v_mfma_f32_16x16x32_bf16 v[96:99], v[182:185], v[198:201], v[96:99]
	v_mfma_f32_16x16x32_bf16 v[84:87], v[166:169], v[206:209], v[84:87]
	v_mfma_f32_16x16x32_bf16 v[80:83], v[182:185], v[206:209], v[80:83]
	v_mfma_f32_16x16x32_bf16 v[68:71], v[166:169], v[214:217], v[68:71]
	v_mfma_f32_16x16x32_bf16 v[64:67], v[182:185], v[214:217], v[64:67]
	v_mfma_f32_16x16x32_bf16 v[116:119], v[170:173], v[194:197], v[116:119]
	v_mfma_f32_16x16x32_bf16 v[112:115], v[186:189], v[194:197], v[112:115]
	v_mfma_f32_16x16x32_bf16 v[100:103], v[170:173], v[202:205], v[100:103]
	v_mfma_f32_16x16x32_bf16 v[96:99], v[186:189], v[202:205], v[96:99]
	v_mfma_f32_16x16x32_bf16 v[84:87], v[170:173], v[210:213], v[84:87]
	v_mfma_f32_16x16x32_bf16 v[80:83], v[186:189], v[210:213], v[80:83]
	v_mfma_f32_16x16x32_bf16 v[68:71], v[170:173], v[224:227], v[68:71]
	v_mfma_f32_16x16x32_bf16 v[64:67], v[186:189], v[224:227], v[64:67]
	s_barrier
	s_setprio 0
	s_add_i32 s6, s37, s59
	v_lshl_add_u64 v[220:221], s[86:87], 0, v[148:149]
	s_mov_b32 m0, s6
	ds_read_b128 v[190:193], v177 offset:16384
	ds_read_b128 v[194:197], v177 offset:17408
	ds_read_b128 v[198:201], v177 offset:18432
	ds_read_b128 v[202:205], v177 offset:19456
	ds_read_b128 v[206:209], v177 offset:20480
	ds_read_b128 v[210:213], v177 offset:21504
	ds_read_b128 v[214:217], v177 offset:22528
	ds_read_b128 v[224:227], v177 offset:23552
	global_load_lds_dwordx4 v[220:221], off
	s_add_i32 m0, s6, 0x2000
	s_add_u32 s6, s86, 0x40000
	v_lshl_add_u64 v[228:229], s[86:87], 0, v[152:153]
	s_addc_u32 s7, s87, 0
	s_add_i32 s51, s97, s59
	global_load_lds_dwordx4 v[228:229], off
	v_lshl_add_u64 v[230:231], s[6:7], 0, v[148:149]
	s_mov_b32 m0, s51
	v_lshl_add_u64 v[232:233], s[88:89], 0, v[150:151]
	global_load_lds_dwordx4 v[230:231], off
	v_lshl_add_u64 v[230:231], s[6:7], 0, v[152:153]
	s_add_i32 m0, s51, 0x2000
	v_lshl_add_u64 v[234:235], v[232:233], 0, s[68:69]
	global_load_lds_dwordx4 v[230:231], off
	s_mov_b32 m0, s61
	v_lshl_add_u64 v[230:231], s[88:89], 0, v[146:147]
	global_load_lds_dwordx4 v[230:231], off
	s_mov_b32 m0, s63
	s_nop 0
	global_load_lds_dwordx4 v[234:235], off
	s_waitcnt vmcnt(8) lgkmcnt(0)
	s_setprio 1
	s_barrier
	v_mfma_f32_16x16x32_bf16 v[60:63], v[128:131], v[190:193], v[60:63]
	v_mfma_f32_16x16x32_bf16 v[56:59], v[136:139], v[190:193], v[56:59]
	v_mfma_f32_16x16x32_bf16 v[44:47], v[128:131], v[198:201], v[44:47]
	v_mfma_f32_16x16x32_bf16 v[40:43], v[136:139], v[198:201], v[40:43]
	v_mfma_f32_16x16x32_bf16 v[28:31], v[128:131], v[206:209], v[28:31]
	v_mfma_f32_16x16x32_bf16 v[24:27], v[136:139], v[206:209], v[24:27]
	v_mfma_f32_16x16x32_bf16 v[12:15], v[128:131], v[214:217], v[12:15]
	v_mfma_f32_16x16x32_bf16 v[8:11], v[136:139], v[214:217], v[8:11]
	v_mfma_f32_16x16x32_bf16 v[60:63], v[132:135], v[194:197], v[60:63]
	v_mfma_f32_16x16x32_bf16 v[56:59], v[140:143], v[194:197], v[56:59]
	v_mfma_f32_16x16x32_bf16 v[44:47], v[132:135], v[202:205], v[44:47]
	v_mfma_f32_16x16x32_bf16 v[40:43], v[140:143], v[202:205], v[40:43]
	v_mfma_f32_16x16x32_bf16 v[28:31], v[132:135], v[210:213], v[28:31]
	v_mfma_f32_16x16x32_bf16 v[24:27], v[140:143], v[210:213], v[24:27]
	v_mfma_f32_16x16x32_bf16 v[12:15], v[132:135], v[224:227], v[12:15]
	v_mfma_f32_16x16x32_bf16 v[8:11], v[140:143], v[224:227], v[8:11]
	v_mfma_f32_16x16x32_bf16 v[52:55], v[166:169], v[190:193], v[52:55]
	v_mfma_f32_16x16x32_bf16 v[48:51], v[182:185], v[190:193], v[48:51]
	v_mfma_f32_16x16x32_bf16 v[36:39], v[166:169], v[198:201], v[36:39]
	v_mfma_f32_16x16x32_bf16 v[32:35], v[182:185], v[198:201], v[32:35]
	v_mfma_f32_16x16x32_bf16 v[20:23], v[166:169], v[206:209], v[20:23]
	v_mfma_f32_16x16x32_bf16 v[16:19], v[182:185], v[206:209], v[16:19]
	v_mfma_f32_16x16x32_bf16 v[4:7], v[166:169], v[214:217], v[4:7]
	v_mfma_f32_16x16x32_bf16 v[0:3], v[182:185], v[214:217], v[0:3]
	v_mfma_f32_16x16x32_bf16 v[52:55], v[170:173], v[194:197], v[52:55]
	v_mfma_f32_16x16x32_bf16 v[48:51], v[186:189], v[194:197], v[48:51]
	v_mfma_f32_16x16x32_bf16 v[36:39], v[170:173], v[202:205], v[36:39]
	v_mfma_f32_16x16x32_bf16 v[32:35], v[186:189], v[202:205], v[32:35]
	v_mfma_f32_16x16x32_bf16 v[20:23], v[170:173], v[210:213], v[20:23]
	v_mfma_f32_16x16x32_bf16 v[16:19], v[186:189], v[210:213], v[16:19]
	v_mfma_f32_16x16x32_bf16 v[4:7], v[170:173], v[224:227], v[4:7]
	v_mfma_f32_16x16x32_bf16 v[0:3], v[186:189], v[224:227], v[0:3]
	s_barrier
	s_setprio 0
	s_add_i32 s6, 0, 0x18000
	s_add_i32 s51, 0, 0x1c000
	v_add_u32_e32 v140, s6, v174
	v_add_u32_e32 v154, s51, v174
	ds_read_b128 v[128:131], v140
	ds_read_b128 v[132:135], v140 offset:1024
	ds_read_b128 v[136:139], v140 offset:2048
	ds_read_b128 v[140:143], v140 offset:3072
	ds_read_b128 v[166:169], v154
	ds_read_b128 v[170:173], v154 offset:1024
	ds_read_b128 v[182:185], v154 offset:2048
	ds_read_b128 v[186:189], v154 offset:3072
	s_mov_b32 m0, s65
	v_lshl_add_u64 v[234:235], v[230:231], 0, s[66:67]
	ds_read_b128 v[190:193], v177 offset:32768
	ds_read_b128 v[194:197], v177 offset:33792
	ds_read_b128 v[198:201], v177 offset:34816
	ds_read_b128 v[202:205], v177 offset:35840
	ds_read_b128 v[206:209], v177 offset:36864
	ds_read_b128 v[210:213], v177 offset:37888
	ds_read_b128 v[214:217], v177 offset:38912
	ds_read_b128 v[224:227], v177 offset:39936
	global_load_lds_dwordx4 v[234:235], off
	s_mov_b32 m0, s77
	v_lshl_add_u64 v[234:235], v[232:233], 0, s[46:47]
	global_load_lds_dwordx4 v[234:235], off
	s_waitcnt vmcnt(8) lgkmcnt(0)
	s_setprio 1
	s_barrier
	v_mfma_f32_16x16x32_bf16 v[124:127], v[128:131], v[190:193], v[124:127]
	v_mfma_f32_16x16x32_bf16 v[120:123], v[136:139], v[190:193], v[120:123]
	v_mfma_f32_16x16x32_bf16 v[108:111], v[128:131], v[198:201], v[108:111]
	v_mfma_f32_16x16x32_bf16 v[104:107], v[136:139], v[198:201], v[104:107]
	v_mfma_f32_16x16x32_bf16 v[92:95], v[128:131], v[206:209], v[92:95]
	v_mfma_f32_16x16x32_bf16 v[88:91], v[136:139], v[206:209], v[88:91]
	v_mfma_f32_16x16x32_bf16 v[76:79], v[128:131], v[214:217], v[76:79]
	v_mfma_f32_16x16x32_bf16 v[72:75], v[136:139], v[214:217], v[72:75]
	v_mfma_f32_16x16x32_bf16 v[124:127], v[132:135], v[194:197], v[124:127]
	v_mfma_f32_16x16x32_bf16 v[120:123], v[140:143], v[194:197], v[120:123]
	v_mfma_f32_16x16x32_bf16 v[108:111], v[132:135], v[202:205], v[108:111]
	v_mfma_f32_16x16x32_bf16 v[104:107], v[140:143], v[202:205], v[104:107]
	v_mfma_f32_16x16x32_bf16 v[92:95], v[132:135], v[210:213], v[92:95]
	v_mfma_f32_16x16x32_bf16 v[88:91], v[140:143], v[210:213], v[88:91]
	v_mfma_f32_16x16x32_bf16 v[76:79], v[132:135], v[224:227], v[76:79]
	v_mfma_f32_16x16x32_bf16 v[72:75], v[140:143], v[224:227], v[72:75]
	v_mfma_f32_16x16x32_bf16 v[116:119], v[166:169], v[190:193], v[116:119]
	v_mfma_f32_16x16x32_bf16 v[112:115], v[182:185], v[190:193], v[112:115]
	v_mfma_f32_16x16x32_bf16 v[100:103], v[166:169], v[198:201], v[100:103]
	v_mfma_f32_16x16x32_bf16 v[96:99], v[182:185], v[198:201], v[96:99]
	v_mfma_f32_16x16x32_bf16 v[84:87], v[166:169], v[206:209], v[84:87]
	v_mfma_f32_16x16x32_bf16 v[80:83], v[182:185], v[206:209], v[80:83]
	v_mfma_f32_16x16x32_bf16 v[68:71], v[166:169], v[214:217], v[68:71]
	v_mfma_f32_16x16x32_bf16 v[64:67], v[182:185], v[214:217], v[64:67]
	v_mfma_f32_16x16x32_bf16 v[116:119], v[170:173], v[194:197], v[116:119]
	v_mfma_f32_16x16x32_bf16 v[112:115], v[186:189], v[194:197], v[112:115]
	v_mfma_f32_16x16x32_bf16 v[100:103], v[170:173], v[202:205], v[100:103]
	v_mfma_f32_16x16x32_bf16 v[96:99], v[186:189], v[202:205], v[96:99]
	v_mfma_f32_16x16x32_bf16 v[84:87], v[170:173], v[210:213], v[84:87]
	v_mfma_f32_16x16x32_bf16 v[80:83], v[186:189], v[210:213], v[80:83]
	v_mfma_f32_16x16x32_bf16 v[68:71], v[170:173], v[224:227], v[68:71]
	v_mfma_f32_16x16x32_bf16 v[64:67], v[186:189], v[224:227], v[64:67]
	s_barrier
	s_setprio 0
	s_add_i32 s6, s6, s59
	v_lshl_add_u64 v[220:221], v[220:221], 0, s[42:43]
	s_mov_b32 m0, s6
	ds_read_b128 v[190:193], v177 offset:49152
	ds_read_b128 v[194:197], v177 offset:50176
	ds_read_b128 v[198:201], v177 offset:51200
	ds_read_b128 v[202:205], v177 offset:52224
	ds_read_b128 v[206:209], v177 offset:53248
	ds_read_b128 v[210:213], v177 offset:54272
	ds_read_b128 v[214:217], v177 offset:55296
	ds_read_b128 v[224:227], v177 offset:56320
	global_load_lds_dwordx4 v[220:221], off
	s_add_i32 m0, s6, 0x2000
	s_add_u32 s6, s86, 0x40080
	v_lshl_add_u64 v[220:221], v[228:229], 0, s[42:43]
	s_addc_u32 s7, s87, 0
	s_add_i32 s51, s51, s59
	global_load_lds_dwordx4 v[220:221], off
	s_mov_b32 m0, s51
	v_lshl_add_u64 v[220:221], s[6:7], 0, v[148:149]
	global_load_lds_dwordx4 v[220:221], off
	s_add_i32 m0, s51, 0x2000
	v_lshl_add_u64 v[220:221], s[6:7], 0, v[152:153]
	global_load_lds_dwordx4 v[220:221], off
	s_mov_b32 m0, s91
	v_lshl_add_u64 v[220:221], v[230:231], 0, s[42:43]
	global_load_lds_dwordx4 v[220:221], off
	s_mov_b32 m0, s92
	v_lshl_add_u64 v[220:221], v[232:233], 0, s[44:45]
	global_load_lds_dwordx4 v[220:221], off
	s_waitcnt vmcnt(8) lgkmcnt(0)
	s_setprio 1
	s_barrier
	v_mfma_f32_16x16x32_bf16 v[60:63], v[128:131], v[190:193], v[60:63]
	v_mfma_f32_16x16x32_bf16 v[56:59], v[136:139], v[190:193], v[56:59]
	v_mfma_f32_16x16x32_bf16 v[44:47], v[128:131], v[198:201], v[44:47]
	v_mfma_f32_16x16x32_bf16 v[40:43], v[136:139], v[198:201], v[40:43]
	v_mfma_f32_16x16x32_bf16 v[28:31], v[128:131], v[206:209], v[28:31]
	v_mfma_f32_16x16x32_bf16 v[24:27], v[136:139], v[206:209], v[24:27]
	v_mfma_f32_16x16x32_bf16 v[12:15], v[128:131], v[214:217], v[12:15]
	v_mfma_f32_16x16x32_bf16 v[8:11], v[136:139], v[214:217], v[8:11]
	v_mfma_f32_16x16x32_bf16 v[60:63], v[132:135], v[194:197], v[60:63]
	v_mfma_f32_16x16x32_bf16 v[56:59], v[140:143], v[194:197], v[56:59]
	v_mfma_f32_16x16x32_bf16 v[44:47], v[132:135], v[202:205], v[44:47]
	v_mfma_f32_16x16x32_bf16 v[40:43], v[140:143], v[202:205], v[40:43]
	v_mfma_f32_16x16x32_bf16 v[28:31], v[132:135], v[210:213], v[28:31]
	v_mfma_f32_16x16x32_bf16 v[24:27], v[140:143], v[210:213], v[24:27]
	v_mfma_f32_16x16x32_bf16 v[12:15], v[132:135], v[224:227], v[12:15]
	v_mfma_f32_16x16x32_bf16 v[8:11], v[140:143], v[224:227], v[8:11]
	v_mfma_f32_16x16x32_bf16 v[52:55], v[166:169], v[190:193], v[52:55]
	v_mfma_f32_16x16x32_bf16 v[48:51], v[182:185], v[190:193], v[48:51]
	v_mfma_f32_16x16x32_bf16 v[36:39], v[166:169], v[198:201], v[36:39]
	v_mfma_f32_16x16x32_bf16 v[32:35], v[182:185], v[198:201], v[32:35]
	v_mfma_f32_16x16x32_bf16 v[20:23], v[166:169], v[206:209], v[20:23]
	v_mfma_f32_16x16x32_bf16 v[16:19], v[182:185], v[206:209], v[16:19]
	v_mfma_f32_16x16x32_bf16 v[4:7], v[166:169], v[214:217], v[4:7]
	v_mfma_f32_16x16x32_bf16 v[0:3], v[182:185], v[214:217], v[0:3]
	v_mfma_f32_16x16x32_bf16 v[52:55], v[170:173], v[194:197], v[52:55]
	v_mfma_f32_16x16x32_bf16 v[48:51], v[186:189], v[194:197], v[48:51]
	v_mfma_f32_16x16x32_bf16 v[36:39], v[170:173], v[202:205], v[36:39]
	v_mfma_f32_16x16x32_bf16 v[32:35], v[186:189], v[202:205], v[32:35]
	v_mfma_f32_16x16x32_bf16 v[20:23], v[170:173], v[210:213], v[20:23]
	v_mfma_f32_16x16x32_bf16 v[16:19], v[186:189], v[210:213], v[16:19]
	v_mfma_f32_16x16x32_bf16 v[4:7], v[170:173], v[224:227], v[4:7]
	v_mfma_f32_16x16x32_bf16 v[0:3], v[186:189], v[224:227], v[0:3]
	s_barrier
	s_setprio 0
	s_add_i32 s50, s50, 2
	s_add_u32 s40, s40, 0x100
	s_addc_u32 s41, s41, 0
	s_cmp_gt_u32 s50, 13
	s_mov_b64 s[6:7], s[8:9]
	s_cbranch_scc0 .LBB0_142
	v_readlane_b32 s6, v249, 60
	v_readlane_b32 s7, v249, 61
	s_and_b64 vcc, exec, s[6:7]
	s_cbranch_vccz .LBB0_145
	s_barrier

.LBB0_392:
	s_lshl_b32 s40, s65, 8
	v_readlane_b32 s72, v249, 0
	s_ashr_i32 s41, s40, 31
	v_readlane_b32 s84, v249, 12
	v_readlane_b32 s85, v249, 13
	s_lshl_b64 s[40:41], s[40:41], 10
	v_readlane_b32 s86, v249, 14
	v_readlane_b32 s87, v249, 15
	s_mov_b64 s[28:29], s[84:85]
	s_add_u32 s40, s28, s40
	s_addc_u32 s41, s29, s41
	s_and_b64 s[42:43], s[0:1], exec
	s_cselect_b32 s67, s41, s45
	s_cselect_b32 s72, s40, s44
	s_ashr_i32 s39, s38, 31
	s_lshl_b64 s[42:43], s[38:39], 18
	s_add_u32 s42, s10, s42
	s_addc_u32 s43, s11, s43
	s_and_b64 s[48:49], s[0:1], exec
	v_readlane_b32 s73, v249, 1
	v_readlane_b32 s74, v249, 2
	s_cselect_b32 s39, s43, s47
	s_cselect_b32 s50, s42, s46
	s_add_u32 s51, s46, 0x100
	s_addc_u32 s73, s47, 0
	s_mov_b32 s74, -2
	s_waitcnt vmcnt(0)
	s_waitcnt lgkmcnt(0)
	v_readlane_b32 s75, v249, 3
	v_readlane_b32 s76, v249, 4
	v_readlane_b32 s77, v249, 5
	v_readlane_b32 s78, v249, 6
	v_readlane_b32 s79, v249, 7
	v_readlane_b32 s80, v249, 8
	v_readlane_b32 s81, v249, 9
	v_readlane_b32 s82, v249, 10
	v_readlane_b32 s83, v249, 11
	s_mov_b64 s[30:31], s[86:87]
	ds_read_b128 v[144:147], v153
	ds_read_b128 v[156:159], v153 offset:1024
	ds_read_b128 v[160:163], v153 offset:2048
	ds_read_b128 v[164:167], v153 offset:3072
	ds_read_b128 v[168:171], v154
	ds_read_b128 v[172:175], v154 offset:1024
	ds_read_b128 v[176:179], v154 offset:2048
	ds_read_b128 v[180:183], v154 offset:3072
	ds_read_b128 v[184:187], v155
	ds_read_b128 v[188:191], v155 offset:1024
	ds_read_b128 v[192:195], v155 offset:2048
	ds_read_b128 v[196:199], v155 offset:3072
	ds_read_b128 v[200:203], v155 offset:4096
	ds_read_b128 v[204:207], v155 offset:5120
	ds_read_b128 v[208:211], v155 offset:6144
	ds_read_b128 v[212:215], v155 offset:7168
	s_add_u32 s46, s44, 0x100
	s_addc_u32 s47, s45, 0
	s_cmp_eq_u32 s74, 4
	s_cselect_b32 s77, s67, s47
	s_cselect_b32 s76, s72, s46
	s_cselect_b32 s49, s39, s73
	s_cselect_b32 s48, s50, s51
	s_add_i32 m0, s52, 0xc000
	v_lshl_add_u64 v[148:149], s[44:45], 0, v[136:137]
	global_load_lds_dwordx4 v[148:149], off
	s_add_i32 m0, s52, 0xe000
	v_lshl_add_u64 v[148:149], s[44:45], 0, v[138:139]
	global_load_lds_dwordx4 v[148:149], off
	s_waitcnt vmcnt(8) lgkmcnt(0)
	s_setprio 1
	s_barrier
	v_mfma_f32_16x16x32_bf16 v[124:127], v[144:147], v[184:187], 0
	v_mfma_f32_16x16x32_bf16 v[120:123], v[160:163], v[184:187], 0
	v_mfma_f32_16x16x32_bf16 v[108:111], v[144:147], v[192:195], 0
	v_mfma_f32_16x16x32_bf16 v[104:107], v[160:163], v[192:195], 0
	v_mfma_f32_16x16x32_bf16 v[92:95], v[144:147], v[200:203], 0
	v_mfma_f32_16x16x32_bf16 v[88:91], v[160:163], v[200:203], 0
	v_mfma_f32_16x16x32_bf16 v[76:79], v[144:147], v[208:211], 0
	v_mfma_f32_16x16x32_bf16 v[72:75], v[160:163], v[208:211], 0
	v_mfma_f32_16x16x32_bf16 v[124:127], v[156:159], v[188:191], v[124:127]
	v_mfma_f32_16x16x32_bf16 v[120:123], v[164:167], v[188:191], v[120:123]
	v_mfma_f32_16x16x32_bf16 v[108:111], v[156:159], v[196:199], v[108:111]
	v_mfma_f32_16x16x32_bf16 v[104:107], v[164:167], v[196:199], v[104:107]
	v_mfma_f32_16x16x32_bf16 v[92:95], v[156:159], v[204:207], v[92:95]
	v_mfma_f32_16x16x32_bf16 v[88:91], v[164:167], v[204:207], v[88:91]
	v_mfma_f32_16x16x32_bf16 v[76:79], v[156:159], v[212:215], v[76:79]
	v_mfma_f32_16x16x32_bf16 v[72:75], v[164:167], v[212:215], v[72:75]
	v_mfma_f32_16x16x32_bf16 v[116:119], v[168:171], v[184:187], 0
	v_mfma_f32_16x16x32_bf16 v[112:115], v[176:179], v[184:187], 0
	v_mfma_f32_16x16x32_bf16 v[100:103], v[168:171], v[192:195], 0
	v_mfma_f32_16x16x32_bf16 v[96:99], v[176:179], v[192:195], 0
	v_mfma_f32_16x16x32_bf16 v[84:87], v[168:171], v[200:203], 0
	v_mfma_f32_16x16x32_bf16 v[80:83], v[176:179], v[200:203], 0
	v_mfma_f32_16x16x32_bf16 v[68:71], v[168:171], v[208:211], 0
	v_mfma_f32_16x16x32_bf16 v[64:67], v[176:179], v[208:211], 0
	v_mfma_f32_16x16x32_bf16 v[116:119], v[172:175], v[188:191], v[116:119]
	v_mfma_f32_16x16x32_bf16 v[112:115], v[180:183], v[188:191], v[112:115]
	v_mfma_f32_16x16x32_bf16 v[100:103], v[172:175], v[196:199], v[100:103]
	v_mfma_f32_16x16x32_bf16 v[96:99], v[180:183], v[196:199], v[96:99]
	v_mfma_f32_16x16x32_bf16 v[84:87], v[172:175], v[204:207], v[84:87]
	v_mfma_f32_16x16x32_bf16 v[80:83], v[180:183], v[204:207], v[80:83]
	v_mfma_f32_16x16x32_bf16 v[68:71], v[172:175], v[212:215], v[68:71]
	v_mfma_f32_16x16x32_bf16 v[64:67], v[180:183], v[212:215], v[64:67]
	s_barrier
	s_setprio 0
	s_add_i32 s44, s61, s33
	v_lshl_add_u64 v[148:149], s[48:49], 0, v[132:133]
	s_mov_b32 m0, s44
	ds_read_b128 v[184:187], v155 offset:16384
	ds_read_b128 v[188:191], v155 offset:17408
	ds_read_b128 v[192:195], v155 offset:18432
	ds_read_b128 v[196:199], v155 offset:19456
	ds_read_b128 v[200:203], v155 offset:20480
	ds_read_b128 v[204:207], v155 offset:21504
	ds_read_b128 v[208:211], v155 offset:22528
	ds_read_b128 v[212:215], v155 offset:23552
	global_load_lds_dwordx4 v[148:149], off
	s_add_i32 m0, s44, 0x2000
	s_add_u32 s44, s48, 0x20000
	v_lshl_add_u64 v[216:217], s[48:49], 0, v[128:129]
	s_addc_u32 s45, s49, 0
	s_add_i32 s68, s62, s33
	global_load_lds_dwordx4 v[216:217], off
	v_lshl_add_u64 v[220:221], s[44:45], 0, v[132:133]
	s_mov_b32 m0, s68
	v_lshl_add_u64 v[224:225], s[76:77], 0, v[130:131]
	global_load_lds_dwordx4 v[220:221], off
	v_lshl_add_u64 v[220:221], s[44:45], 0, v[128:129]
	s_add_i32 m0, s68, 0x2000
	v_lshl_add_u64 v[226:227], v[224:225], 0, s[8:9]
	global_load_lds_dwordx4 v[220:221], off
	s_mov_b32 m0, s52
	v_lshl_add_u64 v[220:221], s[76:77], 0, v[134:135]
	global_load_lds_dwordx4 v[220:221], off
	s_mov_b32 m0, s53
	s_nop 0
	global_load_lds_dwordx4 v[226:227], off
	s_waitcnt vmcnt(8) lgkmcnt(0)
	s_setprio 1
	s_barrier
	v_mfma_f32_16x16x32_bf16 v[60:63], v[144:147], v[184:187], 0
	v_mfma_f32_16x16x32_bf16 v[56:59], v[160:163], v[184:187], 0
	v_mfma_f32_16x16x32_bf16 v[44:47], v[144:147], v[192:195], 0
	v_mfma_f32_16x16x32_bf16 v[40:43], v[160:163], v[192:195], 0
	v_mfma_f32_16x16x32_bf16 v[28:31], v[144:147], v[200:203], 0
	v_mfma_f32_16x16x32_bf16 v[24:27], v[160:163], v[200:203], 0
	v_mfma_f32_16x16x32_bf16 v[12:15], v[144:147], v[208:211], 0
	v_mfma_f32_16x16x32_bf16 v[8:11], v[160:163], v[208:211], 0
	v_mfma_f32_16x16x32_bf16 v[60:63], v[156:159], v[188:191], v[60:63]
	v_mfma_f32_16x16x32_bf16 v[56:59], v[164:167], v[188:191], v[56:59]
	v_mfma_f32_16x16x32_bf16 v[44:47], v[156:159], v[196:199], v[44:47]
	v_mfma_f32_16x16x32_bf16 v[40:43], v[164:167], v[196:199], v[40:43]
	v_mfma_f32_16x16x32_bf16 v[28:31], v[156:159], v[204:207], v[28:31]
	v_mfma_f32_16x16x32_bf16 v[24:27], v[164:167], v[204:207], v[24:27]
	v_mfma_f32_16x16x32_bf16 v[12:15], v[156:159], v[212:215], v[12:15]
	v_mfma_f32_16x16x32_bf16 v[8:11], v[164:167], v[212:215], v[8:11]
	v_mfma_f32_16x16x32_bf16 v[52:55], v[168:171], v[184:187], 0
	v_mfma_f32_16x16x32_bf16 v[48:51], v[176:179], v[184:187], 0
	v_mfma_f32_16x16x32_bf16 v[36:39], v[168:171], v[192:195], 0
	v_mfma_f32_16x16x32_bf16 v[32:35], v[176:179], v[192:195], 0
	v_mfma_f32_16x16x32_bf16 v[20:23], v[168:171], v[200:203], 0
	v_mfma_f32_16x16x32_bf16 v[16:19], v[176:179], v[200:203], 0
	v_mfma_f32_16x16x32_bf16 v[4:7], v[168:171], v[208:211], 0
	v_mfma_f32_16x16x32_bf16 v[0:3], v[176:179], v[208:211], 0
	v_mfma_f32_16x16x32_bf16 v[52:55], v[172:175], v[188:191], v[52:55]
	v_mfma_f32_16x16x32_bf16 v[48:51], v[180:183], v[188:191], v[48:51]
	v_mfma_f32_16x16x32_bf16 v[36:39], v[172:175], v[196:199], v[36:39]
	v_mfma_f32_16x16x32_bf16 v[32:35], v[180:183], v[196:199], v[32:35]
	v_mfma_f32_16x16x32_bf16 v[20:23], v[172:175], v[204:207], v[20:23]
	v_mfma_f32_16x16x32_bf16 v[16:19], v[180:183], v[204:207], v[16:19]
	v_mfma_f32_16x16x32_bf16 v[4:7], v[172:175], v[212:215], v[4:7]
	v_mfma_f32_16x16x32_bf16 v[0:3], v[180:183], v[212:215], v[0:3]
	s_barrier
	s_setprio 0
	s_add_i32 s44, 0, 0x18000
	s_add_i32 s68, 0, 0x1c000
	v_add_u32_e32 v164, s44, v151
	v_add_u32_e32 v180, s68, v151
	ds_read_b128 v[144:147], v164
	ds_read_b128 v[156:159], v164 offset:1024
	ds_read_b128 v[160:163], v164 offset:2048
	ds_read_b128 v[164:167], v164 offset:3072
	ds_read_b128 v[168:171], v180
	ds_read_b128 v[172:175], v180 offset:1024
	ds_read_b128 v[176:179], v180 offset:2048
	ds_read_b128 v[180:183], v180 offset:3072
	s_mov_b32 m0, s54
	v_lshl_add_u64 v[226:227], v[220:221], 0, s[6:7]
	ds_read_b128 v[184:187], v155 offset:32768
	ds_read_b128 v[188:191], v155 offset:33792
	ds_read_b128 v[192:195], v155 offset:34816
	ds_read_b128 v[196:199], v155 offset:35840
	ds_read_b128 v[200:203], v155 offset:36864
	ds_read_b128 v[204:207], v155 offset:37888
	ds_read_b128 v[208:211], v155 offset:38912
	ds_read_b128 v[212:215], v155 offset:39936
	global_load_lds_dwordx4 v[226:227], off
	s_mov_b32 m0, s55
	v_lshl_add_u64 v[226:227], v[224:225], 0, s[12:13]
	global_load_lds_dwordx4 v[226:227], off
	s_waitcnt vmcnt(8) lgkmcnt(0)
	s_setprio 1
	s_barrier
	v_mfma_f32_16x16x32_bf16 v[124:127], v[144:147], v[184:187], v[124:127]
	v_mfma_f32_16x16x32_bf16 v[120:123], v[160:163], v[184:187], v[120:123]
	v_mfma_f32_16x16x32_bf16 v[108:111], v[144:147], v[192:195], v[108:111]
	v_mfma_f32_16x16x32_bf16 v[104:107], v[160:163], v[192:195], v[104:107]
	v_mfma_f32_16x16x32_bf16 v[92:95], v[144:147], v[200:203], v[92:95]
	v_mfma_f32_16x16x32_bf16 v[88:91], v[160:163], v[200:203], v[88:91]
	v_mfma_f32_16x16x32_bf16 v[76:79], v[144:147], v[208:211], v[76:79]
	v_mfma_f32_16x16x32_bf16 v[72:75], v[160:163], v[208:211], v[72:75]
	v_mfma_f32_16x16x32_bf16 v[124:127], v[156:159], v[188:191], v[124:127]
	v_mfma_f32_16x16x32_bf16 v[120:123], v[164:167], v[188:191], v[120:123]
	v_mfma_f32_16x16x32_bf16 v[108:111], v[156:159], v[196:199], v[108:111]
	v_mfma_f32_16x16x32_bf16 v[104:107], v[164:167], v[196:199], v[104:107]
	v_mfma_f32_16x16x32_bf16 v[92:95], v[156:159], v[204:207], v[92:95]
	v_mfma_f32_16x16x32_bf16 v[88:91], v[164:167], v[204:207], v[88:91]
	v_mfma_f32_16x16x32_bf16 v[76:79], v[156:159], v[212:215], v[76:79]
	v_mfma_f32_16x16x32_bf16 v[72:75], v[164:167], v[212:215], v[72:75]
	v_mfma_f32_16x16x32_bf16 v[116:119], v[168:171], v[184:187], v[116:119]
	v_mfma_f32_16x16x32_bf16 v[112:115], v[176:179], v[184:187], v[112:115]
	v_mfma_f32_16x16x32_bf16 v[100:103], v[168:171], v[192:195], v[100:103]
	v_mfma_f32_16x16x32_bf16 v[96:99], v[176:179], v[192:195], v[96:99]
	v_mfma_f32_16x16x32_bf16 v[84:87], v[168:171], v[200:203], v[84:87]
	v_mfma_f32_16x16x32_bf16 v[80:83], v[176:179], v[200:203], v[80:83]
	v_mfma_f32_16x16x32_bf16 v[68:71], v[168:171], v[208:211], v[68:71]
	v_mfma_f32_16x16x32_bf16 v[64:67], v[176:179], v[208:211], v[64:67]
	v_mfma_f32_16x16x32_bf16 v[116:119], v[172:175], v[188:191], v[116:119]
	v_mfma_f32_16x16x32_bf16 v[112:115], v[180:183], v[188:191], v[112:115]
	v_mfma_f32_16x16x32_bf16 v[100:103], v[172:175], v[196:199], v[100:103]
	v_mfma_f32_16x16x32_bf16 v[96:99], v[180:183], v[196:199], v[96:99]
	v_mfma_f32_16x16x32_bf16 v[84:87], v[172:175], v[204:207], v[84:87]
	v_mfma_f32_16x16x32_bf16 v[80:83], v[180:183], v[204:207], v[80:83]
	v_mfma_f32_16x16x32_bf16 v[68:71], v[172:175], v[212:215], v[68:71]
	v_mfma_f32_16x16x32_bf16 v[64:67], v[180:183], v[212:215], v[64:67]
	s_barrier
	s_setprio 0
	s_add_i32 s44, s44, s33
	v_lshl_add_u64 v[148:149], v[148:149], 0, s[22:23]
	s_mov_b32 m0, s44
	ds_read_b128 v[184:187], v155 offset:49152
	ds_read_b128 v[188:191], v155 offset:50176
	ds_read_b128 v[192:195], v155 offset:51200
	ds_read_b128 v[196:199], v155 offset:52224
	ds_read_b128 v[200:203], v155 offset:53248
	ds_read_b128 v[204:207], v155 offset:54272
	ds_read_b128 v[208:211], v155 offset:55296
	ds_read_b128 v[212:215], v155 offset:56320
	global_load_lds_dwordx4 v[148:149], off
	s_add_i32 m0, s44, 0x2000
	s_add_u32 s44, s48, 0x20080
	v_lshl_add_u64 v[148:149], v[216:217], 0, s[22:23]
	s_addc_u32 s45, s49, 0
	s_add_i32 s48, s68, s33
	global_load_lds_dwordx4 v[148:149], off
	s_mov_b32 m0, s48
	v_lshl_add_u64 v[148:149], s[44:45], 0, v[132:133]
	global_load_lds_dwordx4 v[148:149], off
	s_add_i32 m0, s48, 0x2000
	v_lshl_add_u64 v[148:149], s[44:45], 0, v[128:129]
	global_load_lds_dwordx4 v[148:149], off
	s_mov_b32 m0, s57
	v_lshl_add_u64 v[148:149], v[220:221], 0, s[22:23]
	global_load_lds_dwordx4 v[148:149], off
	s_mov_b32 m0, s58
	v_lshl_add_u64 v[148:149], v[224:225], 0, s[24:25]
	global_load_lds_dwordx4 v[148:149], off
	s_waitcnt vmcnt(8) lgkmcnt(0)
	s_setprio 1
	s_barrier
	v_mfma_f32_16x16x32_bf16 v[60:63], v[144:147], v[184:187], v[60:63]
	v_mfma_f32_16x16x32_bf16 v[56:59], v[160:163], v[184:187], v[56:59]
	v_mfma_f32_16x16x32_bf16 v[44:47], v[144:147], v[192:195], v[44:47]
	v_mfma_f32_16x16x32_bf16 v[40:43], v[160:163], v[192:195], v[40:43]
	v_mfma_f32_16x16x32_bf16 v[28:31], v[144:147], v[200:203], v[28:31]
	v_mfma_f32_16x16x32_bf16 v[24:27], v[160:163], v[200:203], v[24:27]
	v_mfma_f32_16x16x32_bf16 v[12:15], v[144:147], v[208:211], v[12:15]
	v_mfma_f32_16x16x32_bf16 v[8:11], v[160:163], v[208:211], v[8:11]
	v_mfma_f32_16x16x32_bf16 v[60:63], v[156:159], v[188:191], v[60:63]
	v_mfma_f32_16x16x32_bf16 v[56:59], v[164:167], v[188:191], v[56:59]
	v_mfma_f32_16x16x32_bf16 v[44:47], v[156:159], v[196:199], v[44:47]
	v_mfma_f32_16x16x32_bf16 v[40:43], v[164:167], v[196:199], v[40:43]
	v_mfma_f32_16x16x32_bf16 v[28:31], v[156:159], v[204:207], v[28:31]
	v_mfma_f32_16x16x32_bf16 v[24:27], v[164:167], v[204:207], v[24:27]
	v_mfma_f32_16x16x32_bf16 v[12:15], v[156:159], v[212:215], v[12:15]
	v_mfma_f32_16x16x32_bf16 v[8:11], v[164:167], v[212:215], v[8:11]
	v_mfma_f32_16x16x32_bf16 v[52:55], v[168:171], v[184:187], v[52:55]
	v_mfma_f32_16x16x32_bf16 v[48:51], v[176:179], v[184:187], v[48:51]
	v_mfma_f32_16x16x32_bf16 v[36:39], v[168:171], v[192:195], v[36:39]
	v_mfma_f32_16x16x32_bf16 v[32:35], v[176:179], v[192:195], v[32:35]
	v_mfma_f32_16x16x32_bf16 v[20:23], v[168:171], v[200:203], v[20:23]
	v_mfma_f32_16x16x32_bf16 v[16:19], v[176:179], v[200:203], v[16:19]
	v_mfma_f32_16x16x32_bf16 v[4:7], v[168:171], v[208:211], v[4:7]
	v_mfma_f32_16x16x32_bf16 v[0:3], v[176:179], v[208:211], v[0:3]
	v_mfma_f32_16x16x32_bf16 v[52:55], v[172:175], v[188:191], v[52:55]
	v_mfma_f32_16x16x32_bf16 v[48:51], v[180:183], v[188:191], v[48:51]
	v_mfma_f32_16x16x32_bf16 v[36:39], v[172:175], v[196:199], v[36:39]
	v_mfma_f32_16x16x32_bf16 v[32:35], v[180:183], v[196:199], v[32:35]
	v_mfma_f32_16x16x32_bf16 v[20:23], v[172:175], v[204:207], v[20:23]
	v_mfma_f32_16x16x32_bf16 v[16:19], v[180:183], v[204:207], v[16:19]
	v_mfma_f32_16x16x32_bf16 v[4:7], v[172:175], v[212:215], v[4:7]
	v_mfma_f32_16x16x32_bf16 v[0:3], v[180:183], v[212:215], v[0:3]
	s_barrier
	s_setprio 0
	s_add_i32 s74, s74, 2
	s_add_u32 s51, s51, 0x100
	s_addc_u32 s73, s73, 0
	s_cmp_gt_u32 s74, 5
	s_mov_b64 s[44:45], s[46:47]
.LBB0_393:
	ds_read_b128 v[144:147], v153
	ds_read_b128 v[156:159], v153 offset:1024
	ds_read_b128 v[160:163], v153 offset:2048
	ds_read_b128 v[164:167], v153 offset:3072
	ds_read_b128 v[168:171], v154
	ds_read_b128 v[172:175], v154 offset:1024
	ds_read_b128 v[176:179], v154 offset:2048
	ds_read_b128 v[180:183], v154 offset:3072
	ds_read_b128 v[184:187], v155
	ds_read_b128 v[188:191], v155 offset:1024
	ds_read_b128 v[192:195], v155 offset:2048
	ds_read_b128 v[196:199], v155 offset:3072
	ds_read_b128 v[200:203], v155 offset:4096
	ds_read_b128 v[204:207], v155 offset:5120
	ds_read_b128 v[208:211], v155 offset:6144
	ds_read_b128 v[212:215], v155 offset:7168
	s_add_u32 s46, s44, 0x100
	s_addc_u32 s47, s45, 0
	s_cmp_eq_u32 s74, 4
	s_cselect_b32 s77, s67, s47
	s_cselect_b32 s76, s72, s46
	s_cselect_b32 s49, s39, s73
	s_cselect_b32 s48, s50, s51
	s_add_i32 m0, s52, 0xc000
	v_lshl_add_u64 v[148:149], s[44:45], 0, v[136:137]
	global_load_lds_dwordx4 v[148:149], off
	s_add_i32 m0, s52, 0xe000
	v_lshl_add_u64 v[148:149], s[44:45], 0, v[138:139]
	global_load_lds_dwordx4 v[148:149], off
	s_waitcnt vmcnt(8) lgkmcnt(0)
	s_setprio 1
	s_barrier
	v_mfma_f32_16x16x32_bf16 v[124:127], v[144:147], v[184:187], v[124:127]
	v_mfma_f32_16x16x32_bf16 v[120:123], v[160:163], v[184:187], v[120:123]
	v_mfma_f32_16x16x32_bf16 v[108:111], v[144:147], v[192:195], v[108:111]
	v_mfma_f32_16x16x32_bf16 v[104:107], v[160:163], v[192:195], v[104:107]
	v_mfma_f32_16x16x32_bf16 v[92:95], v[144:147], v[200:203], v[92:95]
	v_mfma_f32_16x16x32_bf16 v[88:91], v[160:163], v[200:203], v[88:91]
	v_mfma_f32_16x16x32_bf16 v[76:79], v[144:147], v[208:211], v[76:79]
	v_mfma_f32_16x16x32_bf16 v[72:75], v[160:163], v[208:211], v[72:75]
	v_mfma_f32_16x16x32_bf16 v[124:127], v[156:159], v[188:191], v[124:127]
	v_mfma_f32_16x16x32_bf16 v[120:123], v[164:167], v[188:191], v[120:123]
	v_mfma_f32_16x16x32_bf16 v[108:111], v[156:159], v[196:199], v[108:111]
	v_mfma_f32_16x16x32_bf16 v[104:107], v[164:167], v[196:199], v[104:107]
	v_mfma_f32_16x16x32_bf16 v[92:95], v[156:159], v[204:207], v[92:95]
	v_mfma_f32_16x16x32_bf16 v[88:91], v[164:167], v[204:207], v[88:91]
	v_mfma_f32_16x16x32_bf16 v[76:79], v[156:159], v[212:215], v[76:79]
	v_mfma_f32_16x16x32_bf16 v[72:75], v[164:167], v[212:215], v[72:75]
	v_mfma_f32_16x16x32_bf16 v[116:119], v[168:171], v[184:187], v[116:119]
	v_mfma_f32_16x16x32_bf16 v[112:115], v[176:179], v[184:187], v[112:115]
	v_mfma_f32_16x16x32_bf16 v[100:103], v[168:171], v[192:195], v[100:103]
	v_mfma_f32_16x16x32_bf16 v[96:99], v[176:179], v[192:195], v[96:99]
	v_mfma_f32_16x16x32_bf16 v[84:87], v[168:171], v[200:203], v[84:87]
	v_mfma_f32_16x16x32_bf16 v[80:83], v[176:179], v[200:203], v[80:83]
	v_mfma_f32_16x16x32_bf16 v[68:71], v[168:171], v[208:211], v[68:71]
	v_mfma_f32_16x16x32_bf16 v[64:67], v[176:179], v[208:211], v[64:67]
	v_mfma_f32_16x16x32_bf16 v[116:119], v[172:175], v[188:191], v[116:119]
	v_mfma_f32_16x16x32_bf16 v[112:115], v[180:183], v[188:191], v[112:115]
	v_mfma_f32_16x16x32_bf16 v[100:103], v[172:175], v[196:199], v[100:103]
	v_mfma_f32_16x16x32_bf16 v[96:99], v[180:183], v[196:199], v[96:99]
	v_mfma_f32_16x16x32_bf16 v[84:87], v[172:175], v[204:207], v[84:87]
	v_mfma_f32_16x16x32_bf16 v[80:83], v[180:183], v[204:207], v[80:83]
	v_mfma_f32_16x16x32_bf16 v[68:71], v[172:175], v[212:215], v[68:71]
	v_mfma_f32_16x16x32_bf16 v[64:67], v[180:183], v[212:215], v[64:67]
	s_barrier
	s_setprio 0
	s_add_i32 s44, s61, s33
	v_lshl_add_u64 v[148:149], s[48:49], 0, v[132:133]
	s_mov_b32 m0, s44
	ds_read_b128 v[184:187], v155 offset:16384
	ds_read_b128 v[188:191], v155 offset:17408
	ds_read_b128 v[192:195], v155 offset:18432
	ds_read_b128 v[196:199], v155 offset:19456
	ds_read_b128 v[200:203], v155 offset:20480
	ds_read_b128 v[204:207], v155 offset:21504
	ds_read_b128 v[208:211], v155 offset:22528
	ds_read_b128 v[212:215], v155 offset:23552
	global_load_lds_dwordx4 v[148:149], off
	s_add_i32 m0, s44, 0x2000
	s_add_u32 s44, s48, 0x20000
	v_lshl_add_u64 v[216:217], s[48:49], 0, v[128:129]
	s_addc_u32 s45, s49, 0
	s_add_i32 s68, s62, s33
	global_load_lds_dwordx4 v[216:217], off
	v_lshl_add_u64 v[220:221], s[44:45], 0, v[132:133]
	s_mov_b32 m0, s68
	v_lshl_add_u64 v[224:225], s[76:77], 0, v[130:131]
	global_load_lds_dwordx4 v[220:221], off
	v_lshl_add_u64 v[220:221], s[44:45], 0, v[128:129]
	s_add_i32 m0, s68, 0x2000
	v_lshl_add_u64 v[226:227], v[224:225], 0, s[8:9]
	global_load_lds_dwordx4 v[220:221], off
	s_mov_b32 m0, s52
	v_lshl_add_u64 v[220:221], s[76:77], 0, v[134:135]
	global_load_lds_dwordx4 v[220:221], off
	s_mov_b32 m0, s53
	s_nop 0
	global_load_lds_dwordx4 v[226:227], off
	s_waitcnt vmcnt(8) lgkmcnt(0)
	s_setprio 1
	s_barrier
	v_mfma_f32_16x16x32_bf16 v[60:63], v[144:147], v[184:187], v[60:63]
	v_mfma_f32_16x16x32_bf16 v[56:59], v[160:163], v[184:187], v[56:59]
	v_mfma_f32_16x16x32_bf16 v[44:47], v[144:147], v[192:195], v[44:47]
	v_mfma_f32_16x16x32_bf16 v[40:43], v[160:163], v[192:195], v[40:43]
	v_mfma_f32_16x16x32_bf16 v[28:31], v[144:147], v[200:203], v[28:31]
	v_mfma_f32_16x16x32_bf16 v[24:27], v[160:163], v[200:203], v[24:27]
	v_mfma_f32_16x16x32_bf16 v[12:15], v[144:147], v[208:211], v[12:15]
	v_mfma_f32_16x16x32_bf16 v[8:11], v[160:163], v[208:211], v[8:11]
	v_mfma_f32_16x16x32_bf16 v[60:63], v[156:159], v[188:191], v[60:63]
	v_mfma_f32_16x16x32_bf16 v[56:59], v[164:167], v[188:191], v[56:59]
	v_mfma_f32_16x16x32_bf16 v[44:47], v[156:159], v[196:199], v[44:47]
	v_mfma_f32_16x16x32_bf16 v[40:43], v[164:167], v[196:199], v[40:43]
	v_mfma_f32_16x16x32_bf16 v[28:31], v[156:159], v[204:207], v[28:31]
	v_mfma_f32_16x16x32_bf16 v[24:27], v[164:167], v[204:207], v[24:27]
	v_mfma_f32_16x16x32_bf16 v[12:15], v[156:159], v[212:215], v[12:15]
	v_mfma_f32_16x16x32_bf16 v[8:11], v[164:167], v[212:215], v[8:11]
	v_mfma_f32_16x16x32_bf16 v[52:55], v[168:171], v[184:187], v[52:55]
	v_mfma_f32_16x16x32_bf16 v[48:51], v[176:179], v[184:187], v[48:51]
	v_mfma_f32_16x16x32_bf16 v[36:39], v[168:171], v[192:195], v[36:39]
	v_mfma_f32_16x16x32_bf16 v[32:35], v[176:179], v[192:195], v[32:35]
	v_mfma_f32_16x16x32_bf16 v[20:23], v[168:171], v[200:203], v[20:23]
	v_mfma_f32_16x16x32_bf16 v[16:19], v[176:179], v[200:203], v[16:19]
	v_mfma_f32_16x16x32_bf16 v[4:7], v[168:171], v[208:211], v[4:7]
	v_mfma_f32_16x16x32_bf16 v[0:3], v[176:179], v[208:211], v[0:3]
	v_mfma_f32_16x16x32_bf16 v[52:55], v[172:175], v[188:191], v[52:55]
	v_mfma_f32_16x16x32_bf16 v[48:51], v[180:183], v[188:191], v[48:51]
	v_mfma_f32_16x16x32_bf16 v[36:39], v[172:175], v[196:199], v[36:39]
	v_mfma_f32_16x16x32_bf16 v[32:35], v[180:183], v[196:199], v[32:35]
	v_mfma_f32_16x16x32_bf16 v[20:23], v[172:175], v[204:207], v[20:23]
	v_mfma_f32_16x16x32_bf16 v[16:19], v[180:183], v[204:207], v[16:19]
	v_mfma_f32_16x16x32_bf16 v[4:7], v[172:175], v[212:215], v[4:7]
	v_mfma_f32_16x16x32_bf16 v[0:3], v[180:183], v[212:215], v[0:3]
	s_barrier
	s_setprio 0
	s_add_i32 s44, 0, 0x18000
	s_add_i32 s68, 0, 0x1c000
	v_add_u32_e32 v164, s44, v151
	v_add_u32_e32 v180, s68, v151
	ds_read_b128 v[144:147], v164
	ds_read_b128 v[156:159], v164 offset:1024
	ds_read_b128 v[160:163], v164 offset:2048
	ds_read_b128 v[164:167], v164 offset:3072
	ds_read_b128 v[168:171], v180
	ds_read_b128 v[172:175], v180 offset:1024
	ds_read_b128 v[176:179], v180 offset:2048
	ds_read_b128 v[180:183], v180 offset:3072
	s_mov_b32 m0, s54
	v_lshl_add_u64 v[226:227], v[220:221], 0, s[6:7]
	ds_read_b128 v[184:187], v155 offset:32768
	ds_read_b128 v[188:191], v155 offset:33792
	ds_read_b128 v[192:195], v155 offset:34816
	ds_read_b128 v[196:199], v155 offset:35840
	ds_read_b128 v[200:203], v155 offset:36864
	ds_read_b128 v[204:207], v155 offset:37888
	ds_read_b128 v[208:211], v155 offset:38912
	ds_read_b128 v[212:215], v155 offset:39936
	global_load_lds_dwordx4 v[226:227], off
	s_mov_b32 m0, s55
	v_lshl_add_u64 v[226:227], v[224:225], 0, s[12:13]
	global_load_lds_dwordx4 v[226:227], off
	s_waitcnt vmcnt(8) lgkmcnt(0)
	s_setprio 1
	s_barrier
	v_mfma_f32_16x16x32_bf16 v[124:127], v[144:147], v[184:187], v[124:127]
	v_mfma_f32_16x16x32_bf16 v[120:123], v[160:163], v[184:187], v[120:123]
	v_mfma_f32_16x16x32_bf16 v[108:111], v[144:147], v[192:195], v[108:111]
	v_mfma_f32_16x16x32_bf16 v[104:107], v[160:163], v[192:195], v[104:107]
	v_mfma_f32_16x16x32_bf16 v[92:95], v[144:147], v[200:203], v[92:95]
	v_mfma_f32_16x16x32_bf16 v[88:91], v[160:163], v[200:203], v[88:91]
	v_mfma_f32_16x16x32_bf16 v[76:79], v[144:147], v[208:211], v[76:79]
	v_mfma_f32_16x16x32_bf16 v[72:75], v[160:163], v[208:211], v[72:75]
	v_mfma_f32_16x16x32_bf16 v[124:127], v[156:159], v[188:191], v[124:127]
	v_mfma_f32_16x16x32_bf16 v[120:123], v[164:167], v[188:191], v[120:123]
	v_mfma_f32_16x16x32_bf16 v[108:111], v[156:159], v[196:199], v[108:111]
	v_mfma_f32_16x16x32_bf16 v[104:107], v[164:167], v[196:199], v[104:107]
	v_mfma_f32_16x16x32_bf16 v[92:95], v[156:159], v[204:207], v[92:95]
	v_mfma_f32_16x16x32_bf16 v[88:91], v[164:167], v[204:207], v[88:91]
	v_mfma_f32_16x16x32_bf16 v[76:79], v[156:159], v[212:215], v[76:79]
	v_mfma_f32_16x16x32_bf16 v[72:75], v[164:167], v[212:215], v[72:75]
	v_mfma_f32_16x16x32_bf16 v[116:119], v[168:171], v[184:187], v[116:119]
	v_mfma_f32_16x16x32_bf16 v[112:115], v[176:179], v[184:187], v[112:115]
	v_mfma_f32_16x16x32_bf16 v[100:103], v[168:171], v[192:195], v[100:103]
	v_mfma_f32_16x16x32_bf16 v[96:99], v[176:179], v[192:195], v[96:99]
	v_mfma_f32_16x16x32_bf16 v[84:87], v[168:171], v[200:203], v[84:87]
	v_mfma_f32_16x16x32_bf16 v[80:83], v[176:179], v[200:203], v[80:83]
	v_mfma_f32_16x16x32_bf16 v[68:71], v[168:171], v[208:211], v[68:71]
	v_mfma_f32_16x16x32_bf16 v[64:67], v[176:179], v[208:211], v[64:67]
	v_mfma_f32_16x16x32_bf16 v[116:119], v[172:175], v[188:191], v[116:119]
	v_mfma_f32_16x16x32_bf16 v[112:115], v[180:183], v[188:191], v[112:115]
	v_mfma_f32_16x16x32_bf16 v[100:103], v[172:175], v[196:199], v[100:103]
	v_mfma_f32_16x16x32_bf16 v[96:99], v[180:183], v[196:199], v[96:99]
	v_mfma_f32_16x16x32_bf16 v[84:87], v[172:175], v[204:207], v[84:87]
	v_mfma_f32_16x16x32_bf16 v[80:83], v[180:183], v[204:207], v[80:83]
	v_mfma_f32_16x16x32_bf16 v[68:71], v[172:175], v[212:215], v[68:71]
	v_mfma_f32_16x16x32_bf16 v[64:67], v[180:183], v[212:215], v[64:67]
	s_barrier
	s_setprio 0
	s_add_i32 s44, s44, s33
	v_lshl_add_u64 v[148:149], v[148:149], 0, s[22:23]
	s_mov_b32 m0, s44
	ds_read_b128 v[184:187], v155 offset:49152
	ds_read_b128 v[188:191], v155 offset:50176
	ds_read_b128 v[192:195], v155 offset:51200
	ds_read_b128 v[196:199], v155 offset:52224
	ds_read_b128 v[200:203], v155 offset:53248
	ds_read_b128 v[204:207], v155 offset:54272
	ds_read_b128 v[208:211], v155 offset:55296
	ds_read_b128 v[212:215], v155 offset:56320
	global_load_lds_dwordx4 v[148:149], off
	s_add_i32 m0, s44, 0x2000
	s_add_u32 s44, s48, 0x20080
	v_lshl_add_u64 v[148:149], v[216:217], 0, s[22:23]
	s_addc_u32 s45, s49, 0
	s_add_i32 s48, s68, s33
	global_load_lds_dwordx4 v[148:149], off
	s_mov_b32 m0, s48
	v_lshl_add_u64 v[148:149], s[44:45], 0, v[132:133]
	global_load_lds_dwordx4 v[148:149], off
	s_add_i32 m0, s48, 0x2000
	v_lshl_add_u64 v[148:149], s[44:45], 0, v[128:129]
	global_load_lds_dwordx4 v[148:149], off
	s_mov_b32 m0, s57
	v_lshl_add_u64 v[148:149], v[220:221], 0, s[22:23]
	global_load_lds_dwordx4 v[148:149], off
	s_mov_b32 m0, s58
	v_lshl_add_u64 v[148:149], v[224:225], 0, s[24:25]
	global_load_lds_dwordx4 v[148:149], off
	s_waitcnt vmcnt(8) lgkmcnt(0)
	s_setprio 1
	s_barrier
	v_mfma_f32_16x16x32_bf16 v[60:63], v[144:147], v[184:187], v[60:63]
	v_mfma_f32_16x16x32_bf16 v[56:59], v[160:163], v[184:187], v[56:59]
	v_mfma_f32_16x16x32_bf16 v[44:47], v[144:147], v[192:195], v[44:47]
	v_mfma_f32_16x16x32_bf16 v[40:43], v[160:163], v[192:195], v[40:43]
	v_mfma_f32_16x16x32_bf16 v[28:31], v[144:147], v[200:203], v[28:31]
	v_mfma_f32_16x16x32_bf16 v[24:27], v[160:163], v[200:203], v[24:27]
	v_mfma_f32_16x16x32_bf16 v[12:15], v[144:147], v[208:211], v[12:15]
	v_mfma_f32_16x16x32_bf16 v[8:11], v[160:163], v[208:211], v[8:11]
	v_mfma_f32_16x16x32_bf16 v[60:63], v[156:159], v[188:191], v[60:63]
	v_mfma_f32_16x16x32_bf16 v[56:59], v[164:167], v[188:191], v[56:59]
	v_mfma_f32_16x16x32_bf16 v[44:47], v[156:159], v[196:199], v[44:47]
	v_mfma_f32_16x16x32_bf16 v[40:43], v[164:167], v[196:199], v[40:43]
	v_mfma_f32_16x16x32_bf16 v[28:31], v[156:159], v[204:207], v[28:31]
	v_mfma_f32_16x16x32_bf16 v[24:27], v[164:167], v[204:207], v[24:27]
	v_mfma_f32_16x16x32_bf16 v[12:15], v[156:159], v[212:215], v[12:15]
	v_mfma_f32_16x16x32_bf16 v[8:11], v[164:167], v[212:215], v[8:11]
	v_mfma_f32_16x16x32_bf16 v[52:55], v[168:171], v[184:187], v[52:55]
	v_mfma_f32_16x16x32_bf16 v[48:51], v[176:179], v[184:187], v[48:51]
	v_mfma_f32_16x16x32_bf16 v[36:39], v[168:171], v[192:195], v[36:39]
	v_mfma_f32_16x16x32_bf16 v[32:35], v[176:179], v[192:195], v[32:35]
	v_mfma_f32_16x16x32_bf16 v[20:23], v[168:171], v[200:203], v[20:23]
	v_mfma_f32_16x16x32_bf16 v[16:19], v[176:179], v[200:203], v[16:19]
	v_mfma_f32_16x16x32_bf16 v[4:7], v[168:171], v[208:211], v[4:7]
	v_mfma_f32_16x16x32_bf16 v[0:3], v[176:179], v[208:211], v[0:3]
	v_mfma_f32_16x16x32_bf16 v[52:55], v[172:175], v[188:191], v[52:55]
	v_mfma_f32_16x16x32_bf16 v[48:51], v[180:183], v[188:191], v[48:51]
	v_mfma_f32_16x16x32_bf16 v[36:39], v[172:175], v[196:199], v[36:39]
	v_mfma_f32_16x16x32_bf16 v[32:35], v[180:183], v[196:199], v[32:35]
	v_mfma_f32_16x16x32_bf16 v[20:23], v[172:175], v[204:207], v[20:23]
	v_mfma_f32_16x16x32_bf16 v[16:19], v[180:183], v[204:207], v[16:19]
	v_mfma_f32_16x16x32_bf16 v[4:7], v[172:175], v[212:215], v[4:7]
	v_mfma_f32_16x16x32_bf16 v[0:3], v[180:183], v[212:215], v[0:3]
	s_barrier
	s_setprio 0
	s_add_i32 s74, s74, 2
	s_add_u32 s51, s51, 0x100
	s_addc_u32 s73, s73, 0
	s_cmp_gt_u32 s74, 5
	s_mov_b64 s[44:45], s[46:47]
	s_cbranch_scc0 .LBB0_393
	s_and_b64 vcc, exec, s[36:37]
	s_cbranch_vccz .LBB0_396
	s_barrier

.LBB0_465:
	s_lshl_b32 s42, s73, 8
	s_ashr_i32 s43, s42, 31
	s_lshl_b64 s[42:43], s[42:43], 11
	s_add_u32 s42, s10, s42
	s_addc_u32 s43, s11, s43
	s_and_b64 s[44:45], s[4:5], exec
	s_cselect_b32 s47, s43, s49
	s_cselect_b32 s74, s42, s48
	s_ashr_i32 s41, s40, 31
	s_lshl_b64 s[44:45], s[40:41], 19
	s_add_u32 s44, s33, s44
	s_addc_u32 s45, s34, s45
	s_and_b64 s[50:51], s[4:5], exec
	s_cselect_b32 s41, s45, s53
	s_cselect_b32 s50, s44, s52
	s_add_u32 s51, s52, 0x100
	s_addc_u32 s75, s53, 0
	s_mov_b32 s76, -2
	s_waitcnt lgkmcnt(0)
	s_waitcnt vmcnt(0)
	s_waitcnt lgkmcnt(0)
	ds_read_b128 v[144:147], v151
	ds_read_b128 v[156:159], v151 offset:1024
	ds_read_b128 v[160:163], v151 offset:2048
	ds_read_b128 v[164:167], v151 offset:3072
	ds_read_b128 v[168:171], v152
	ds_read_b128 v[172:175], v152 offset:1024
	ds_read_b128 v[176:179], v152 offset:2048
	ds_read_b128 v[180:183], v152 offset:3072
	ds_read_b128 v[184:187], v153
	ds_read_b128 v[188:191], v153 offset:1024
	ds_read_b128 v[192:195], v153 offset:2048
	ds_read_b128 v[196:199], v153 offset:3072
	ds_read_b128 v[200:203], v153 offset:4096
	ds_read_b128 v[204:207], v153 offset:5120
	ds_read_b128 v[208:211], v153 offset:6144
	ds_read_b128 v[212:215], v153 offset:7168
	s_add_u32 s52, s48, 0x100
	s_addc_u32 s53, s49, 0
	s_cmp_eq_u32 s76, 12
	s_cselect_b32 s79, s47, s53
	s_cselect_b32 s78, s74, s52
	s_cselect_b32 s55, s41, s75
	s_cselect_b32 s54, s50, s51
	s_add_i32 m0, s56, 0xc000
	v_lshl_add_u64 v[216:217], s[48:49], 0, v[136:137]
	global_load_lds_dwordx4 v[216:217], off
	s_add_i32 m0, s56, 0xe000
	v_lshl_add_u64 v[216:217], s[48:49], 0, v[138:139]
	global_load_lds_dwordx4 v[216:217], off
	s_waitcnt vmcnt(8) lgkmcnt(0)
	s_setprio 1
	s_barrier
	v_mfma_f32_16x16x32_bf16 v[124:127], v[144:147], v[184:187], 0
	v_mfma_f32_16x16x32_bf16 v[120:123], v[160:163], v[184:187], 0
	v_mfma_f32_16x16x32_bf16 v[108:111], v[144:147], v[192:195], 0
	v_mfma_f32_16x16x32_bf16 v[104:107], v[160:163], v[192:195], 0
	v_mfma_f32_16x16x32_bf16 v[92:95], v[144:147], v[200:203], 0
	v_mfma_f32_16x16x32_bf16 v[88:91], v[160:163], v[200:203], 0
	v_mfma_f32_16x16x32_bf16 v[76:79], v[144:147], v[208:211], 0
	v_mfma_f32_16x16x32_bf16 v[72:75], v[160:163], v[208:211], 0
	v_mfma_f32_16x16x32_bf16 v[124:127], v[156:159], v[188:191], v[124:127]
	v_mfma_f32_16x16x32_bf16 v[120:123], v[164:167], v[188:191], v[120:123]
	v_mfma_f32_16x16x32_bf16 v[108:111], v[156:159], v[196:199], v[108:111]
	v_mfma_f32_16x16x32_bf16 v[104:107], v[164:167], v[196:199], v[104:107]
	v_mfma_f32_16x16x32_bf16 v[92:95], v[156:159], v[204:207], v[92:95]
	v_mfma_f32_16x16x32_bf16 v[88:91], v[164:167], v[204:207], v[88:91]
	v_mfma_f32_16x16x32_bf16 v[76:79], v[156:159], v[212:215], v[76:79]
	v_mfma_f32_16x16x32_bf16 v[72:75], v[164:167], v[212:215], v[72:75]
	v_mfma_f32_16x16x32_bf16 v[116:119], v[168:171], v[184:187], 0
	v_mfma_f32_16x16x32_bf16 v[112:115], v[176:179], v[184:187], 0
	v_mfma_f32_16x16x32_bf16 v[100:103], v[168:171], v[192:195], 0
	v_mfma_f32_16x16x32_bf16 v[96:99], v[176:179], v[192:195], 0
	v_mfma_f32_16x16x32_bf16 v[84:87], v[168:171], v[200:203], 0
	v_mfma_f32_16x16x32_bf16 v[80:83], v[176:179], v[200:203], 0
	v_mfma_f32_16x16x32_bf16 v[68:71], v[168:171], v[208:211], 0
	v_mfma_f32_16x16x32_bf16 v[64:67], v[176:179], v[208:211], 0
	v_mfma_f32_16x16x32_bf16 v[116:119], v[172:175], v[188:191], v[116:119]
	v_mfma_f32_16x16x32_bf16 v[112:115], v[180:183], v[188:191], v[112:115]
	v_mfma_f32_16x16x32_bf16 v[100:103], v[172:175], v[196:199], v[100:103]
	v_mfma_f32_16x16x32_bf16 v[96:99], v[180:183], v[196:199], v[96:99]
	v_mfma_f32_16x16x32_bf16 v[84:87], v[172:175], v[204:207], v[84:87]
	v_mfma_f32_16x16x32_bf16 v[80:83], v[180:183], v[204:207], v[80:83]
	v_mfma_f32_16x16x32_bf16 v[68:71], v[172:175], v[212:215], v[68:71]
	v_mfma_f32_16x16x32_bf16 v[64:67], v[180:183], v[212:215], v[64:67]
	s_barrier
	s_setprio 0
	s_add_i32 s48, s67, s35
	v_lshl_add_u64 v[216:217], s[54:55], 0, v[130:131]
	s_mov_b32 m0, s48
	ds_read_b128 v[184:187], v153 offset:16384
	ds_read_b128 v[188:191], v153 offset:17408
	ds_read_b128 v[192:195], v153 offset:18432
	ds_read_b128 v[196:199], v153 offset:19456
	ds_read_b128 v[200:203], v153 offset:20480
	ds_read_b128 v[204:207], v153 offset:21504
	ds_read_b128 v[208:211], v153 offset:22528
	ds_read_b128 v[212:215], v153 offset:23552
	global_load_lds_dwordx4 v[216:217], off
	s_add_i32 m0, s48, 0x2000
	s_add_u32 s48, s54, 0x40000
	v_lshl_add_u64 v[220:221], s[54:55], 0, v[134:135]
	s_addc_u32 s49, s55, 0
	s_add_i32 s68, s72, s35
	global_load_lds_dwordx4 v[220:221], off
	v_lshl_add_u64 v[224:225], s[48:49], 0, v[130:131]
	s_mov_b32 m0, s68
	v_lshl_add_u64 v[226:227], s[78:79], 0, v[132:133]
	global_load_lds_dwordx4 v[224:225], off
	v_lshl_add_u64 v[224:225], s[48:49], 0, v[134:135]
	s_add_i32 m0, s68, 0x2000
	v_lshl_add_u64 v[228:229], v[226:227], 0, s[12:13]
	global_load_lds_dwordx4 v[224:225], off
	s_mov_b32 m0, s56
	v_lshl_add_u64 v[224:225], s[78:79], 0, v[128:129]
	global_load_lds_dwordx4 v[224:225], off
	s_mov_b32 m0, s57
	s_nop 0
	global_load_lds_dwordx4 v[228:229], off
	s_waitcnt vmcnt(8) lgkmcnt(0)
	s_setprio 1
	s_barrier
	v_mfma_f32_16x16x32_bf16 v[60:63], v[144:147], v[184:187], 0
	v_mfma_f32_16x16x32_bf16 v[56:59], v[160:163], v[184:187], 0
	v_mfma_f32_16x16x32_bf16 v[44:47], v[144:147], v[192:195], 0
	v_mfma_f32_16x16x32_bf16 v[40:43], v[160:163], v[192:195], 0
	v_mfma_f32_16x16x32_bf16 v[28:31], v[144:147], v[200:203], 0
	v_mfma_f32_16x16x32_bf16 v[24:27], v[160:163], v[200:203], 0
	v_mfma_f32_16x16x32_bf16 v[12:15], v[144:147], v[208:211], 0
	v_mfma_f32_16x16x32_bf16 v[8:11], v[160:163], v[208:211], 0
	v_mfma_f32_16x16x32_bf16 v[60:63], v[156:159], v[188:191], v[60:63]
	v_mfma_f32_16x16x32_bf16 v[56:59], v[164:167], v[188:191], v[56:59]
	v_mfma_f32_16x16x32_bf16 v[44:47], v[156:159], v[196:199], v[44:47]
	v_mfma_f32_16x16x32_bf16 v[40:43], v[164:167], v[196:199], v[40:43]
	v_mfma_f32_16x16x32_bf16 v[28:31], v[156:159], v[204:207], v[28:31]
	v_mfma_f32_16x16x32_bf16 v[24:27], v[164:167], v[204:207], v[24:27]
	v_mfma_f32_16x16x32_bf16 v[12:15], v[156:159], v[212:215], v[12:15]
	v_mfma_f32_16x16x32_bf16 v[8:11], v[164:167], v[212:215], v[8:11]
	v_mfma_f32_16x16x32_bf16 v[52:55], v[168:171], v[184:187], 0
	v_mfma_f32_16x16x32_bf16 v[48:51], v[176:179], v[184:187], 0
	v_mfma_f32_16x16x32_bf16 v[36:39], v[168:171], v[192:195], 0
	v_mfma_f32_16x16x32_bf16 v[32:35], v[176:179], v[192:195], 0
	v_mfma_f32_16x16x32_bf16 v[20:23], v[168:171], v[200:203], 0
	v_mfma_f32_16x16x32_bf16 v[16:19], v[176:179], v[200:203], 0
	v_mfma_f32_16x16x32_bf16 v[4:7], v[168:171], v[208:211], 0
	v_mfma_f32_16x16x32_bf16 v[0:3], v[176:179], v[208:211], 0
	v_mfma_f32_16x16x32_bf16 v[52:55], v[172:175], v[188:191], v[52:55]
	v_mfma_f32_16x16x32_bf16 v[48:51], v[180:183], v[188:191], v[48:51]
	v_mfma_f32_16x16x32_bf16 v[36:39], v[172:175], v[196:199], v[36:39]
	v_mfma_f32_16x16x32_bf16 v[32:35], v[180:183], v[196:199], v[32:35]
	v_mfma_f32_16x16x32_bf16 v[20:23], v[172:175], v[204:207], v[20:23]
	v_mfma_f32_16x16x32_bf16 v[16:19], v[180:183], v[204:207], v[16:19]
	v_mfma_f32_16x16x32_bf16 v[4:7], v[172:175], v[212:215], v[4:7]
	v_mfma_f32_16x16x32_bf16 v[0:3], v[180:183], v[212:215], v[0:3]
	s_barrier
	s_setprio 0
	s_add_i32 s48, 0, 0x18000
	v_add_u32_e32 v155, s48, v149
	s_add_i32 s68, 0, 0x1c000
	ds_read_b128 v[144:147], v155
	ds_read_b128 v[156:159], v155 offset:1024
	ds_read_b128 v[160:163], v155 offset:2048
	ds_read_b128 v[164:167], v155 offset:3072
	v_add_u32_e32 v155, s68, v149
	ds_read_b128 v[168:171], v155
	ds_read_b128 v[172:175], v155 offset:1024
	ds_read_b128 v[176:179], v155 offset:2048
	ds_read_b128 v[180:183], v155 offset:3072
	s_mov_b32 m0, s58
	v_lshl_add_u64 v[228:229], v[224:225], 0, s[8:9]
	ds_read_b128 v[184:187], v153 offset:32768
	ds_read_b128 v[188:191], v153 offset:33792
	ds_read_b128 v[192:195], v153 offset:34816
	ds_read_b128 v[196:199], v153 offset:35840
	ds_read_b128 v[200:203], v153 offset:36864
	ds_read_b128 v[204:207], v153 offset:37888
	ds_read_b128 v[208:211], v153 offset:38912
	ds_read_b128 v[212:215], v153 offset:39936
	global_load_lds_dwordx4 v[228:229], off
	s_mov_b32 m0, s59
	v_lshl_add_u64 v[228:229], v[226:227], 0, s[14:15]
	global_load_lds_dwordx4 v[228:229], off
	s_waitcnt vmcnt(8) lgkmcnt(0)
	s_setprio 1
	s_barrier
	v_mfma_f32_16x16x32_bf16 v[124:127], v[144:147], v[184:187], v[124:127]
	v_mfma_f32_16x16x32_bf16 v[120:123], v[160:163], v[184:187], v[120:123]
	v_mfma_f32_16x16x32_bf16 v[108:111], v[144:147], v[192:195], v[108:111]
	v_mfma_f32_16x16x32_bf16 v[104:107], v[160:163], v[192:195], v[104:107]
	v_mfma_f32_16x16x32_bf16 v[92:95], v[144:147], v[200:203], v[92:95]
	v_mfma_f32_16x16x32_bf16 v[88:91], v[160:163], v[200:203], v[88:91]
	v_mfma_f32_16x16x32_bf16 v[76:79], v[144:147], v[208:211], v[76:79]
	v_mfma_f32_16x16x32_bf16 v[72:75], v[160:163], v[208:211], v[72:75]
	v_mfma_f32_16x16x32_bf16 v[124:127], v[156:159], v[188:191], v[124:127]
	v_mfma_f32_16x16x32_bf16 v[120:123], v[164:167], v[188:191], v[120:123]
	v_mfma_f32_16x16x32_bf16 v[108:111], v[156:159], v[196:199], v[108:111]
	v_mfma_f32_16x16x32_bf16 v[104:107], v[164:167], v[196:199], v[104:107]
	v_mfma_f32_16x16x32_bf16 v[92:95], v[156:159], v[204:207], v[92:95]
	v_mfma_f32_16x16x32_bf16 v[88:91], v[164:167], v[204:207], v[88:91]
	v_mfma_f32_16x16x32_bf16 v[76:79], v[156:159], v[212:215], v[76:79]
	v_mfma_f32_16x16x32_bf16 v[72:75], v[164:167], v[212:215], v[72:75]
	v_mfma_f32_16x16x32_bf16 v[116:119], v[168:171], v[184:187], v[116:119]
	v_mfma_f32_16x16x32_bf16 v[112:115], v[176:179], v[184:187], v[112:115]
	v_mfma_f32_16x16x32_bf16 v[100:103], v[168:171], v[192:195], v[100:103]
	v_mfma_f32_16x16x32_bf16 v[96:99], v[176:179], v[192:195], v[96:99]
	v_mfma_f32_16x16x32_bf16 v[84:87], v[168:171], v[200:203], v[84:87]
	v_mfma_f32_16x16x32_bf16 v[80:83], v[176:179], v[200:203], v[80:83]
	v_mfma_f32_16x16x32_bf16 v[68:71], v[168:171], v[208:211], v[68:71]
	v_mfma_f32_16x16x32_bf16 v[64:67], v[176:179], v[208:211], v[64:67]
	v_mfma_f32_16x16x32_bf16 v[116:119], v[172:175], v[188:191], v[116:119]
	v_mfma_f32_16x16x32_bf16 v[112:115], v[180:183], v[188:191], v[112:115]
	v_mfma_f32_16x16x32_bf16 v[100:103], v[172:175], v[196:199], v[100:103]
	v_mfma_f32_16x16x32_bf16 v[96:99], v[180:183], v[196:199], v[96:99]
	v_mfma_f32_16x16x32_bf16 v[84:87], v[172:175], v[204:207], v[84:87]
	v_mfma_f32_16x16x32_bf16 v[80:83], v[180:183], v[204:207], v[80:83]
	v_mfma_f32_16x16x32_bf16 v[68:71], v[172:175], v[212:215], v[68:71]
	v_mfma_f32_16x16x32_bf16 v[64:67], v[180:183], v[212:215], v[64:67]
	s_barrier
	s_setprio 0
	s_add_i32 s48, s48, s35
	v_lshl_add_u64 v[216:217], v[216:217], 0, s[24:25]
	s_mov_b32 m0, s48
	ds_read_b128 v[184:187], v153 offset:49152
	ds_read_b128 v[188:191], v153 offset:50176
	ds_read_b128 v[192:195], v153 offset:51200
	ds_read_b128 v[196:199], v153 offset:52224
	ds_read_b128 v[200:203], v153 offset:53248
	ds_read_b128 v[204:207], v153 offset:54272
	ds_read_b128 v[208:211], v153 offset:55296
	ds_read_b128 v[212:215], v153 offset:56320
	global_load_lds_dwordx4 v[216:217], off
	s_add_i32 m0, s48, 0x2000
	s_add_u32 s48, s54, 0x40080
	v_lshl_add_u64 v[216:217], v[220:221], 0, s[24:25]
	s_addc_u32 s49, s55, 0
	s_add_i32 s54, s68, s35
	global_load_lds_dwordx4 v[216:217], off
	s_mov_b32 m0, s54
	v_lshl_add_u64 v[216:217], s[48:49], 0, v[130:131]
	global_load_lds_dwordx4 v[216:217], off
	s_add_i32 m0, s54, 0x2000
	v_lshl_add_u64 v[216:217], s[48:49], 0, v[134:135]
	global_load_lds_dwordx4 v[216:217], off
	s_mov_b32 m0, s61
	v_lshl_add_u64 v[216:217], v[224:225], 0, s[24:25]
	global_load_lds_dwordx4 v[216:217], off
	s_mov_b32 m0, s62
	v_lshl_add_u64 v[216:217], v[226:227], 0, s[36:37]
	global_load_lds_dwordx4 v[216:217], off
	s_waitcnt vmcnt(8) lgkmcnt(0)
	s_setprio 1
	s_barrier
	v_mfma_f32_16x16x32_bf16 v[60:63], v[144:147], v[184:187], v[60:63]
	v_mfma_f32_16x16x32_bf16 v[56:59], v[160:163], v[184:187], v[56:59]
	v_mfma_f32_16x16x32_bf16 v[44:47], v[144:147], v[192:195], v[44:47]
	v_mfma_f32_16x16x32_bf16 v[40:43], v[160:163], v[192:195], v[40:43]
	v_mfma_f32_16x16x32_bf16 v[28:31], v[144:147], v[200:203], v[28:31]
	v_mfma_f32_16x16x32_bf16 v[24:27], v[160:163], v[200:203], v[24:27]
	v_mfma_f32_16x16x32_bf16 v[12:15], v[144:147], v[208:211], v[12:15]
	v_mfma_f32_16x16x32_bf16 v[8:11], v[160:163], v[208:211], v[8:11]
	v_mfma_f32_16x16x32_bf16 v[60:63], v[156:159], v[188:191], v[60:63]
	v_mfma_f32_16x16x32_bf16 v[56:59], v[164:167], v[188:191], v[56:59]
	v_mfma_f32_16x16x32_bf16 v[44:47], v[156:159], v[196:199], v[44:47]
	v_mfma_f32_16x16x32_bf16 v[40:43], v[164:167], v[196:199], v[40:43]
	v_mfma_f32_16x16x32_bf16 v[28:31], v[156:159], v[204:207], v[28:31]
	v_mfma_f32_16x16x32_bf16 v[24:27], v[164:167], v[204:207], v[24:27]
	v_mfma_f32_16x16x32_bf16 v[12:15], v[156:159], v[212:215], v[12:15]
	v_mfma_f32_16x16x32_bf16 v[8:11], v[164:167], v[212:215], v[8:11]
	v_mfma_f32_16x16x32_bf16 v[52:55], v[168:171], v[184:187], v[52:55]
	v_mfma_f32_16x16x32_bf16 v[48:51], v[176:179], v[184:187], v[48:51]
	v_mfma_f32_16x16x32_bf16 v[36:39], v[168:171], v[192:195], v[36:39]
	v_mfma_f32_16x16x32_bf16 v[32:35], v[176:179], v[192:195], v[32:35]
	v_mfma_f32_16x16x32_bf16 v[20:23], v[168:171], v[200:203], v[20:23]
	v_mfma_f32_16x16x32_bf16 v[16:19], v[176:179], v[200:203], v[16:19]
	v_mfma_f32_16x16x32_bf16 v[4:7], v[168:171], v[208:211], v[4:7]
	v_mfma_f32_16x16x32_bf16 v[0:3], v[176:179], v[208:211], v[0:3]
	v_mfma_f32_16x16x32_bf16 v[52:55], v[172:175], v[188:191], v[52:55]
	v_mfma_f32_16x16x32_bf16 v[48:51], v[180:183], v[188:191], v[48:51]
	v_mfma_f32_16x16x32_bf16 v[36:39], v[172:175], v[196:199], v[36:39]
	v_mfma_f32_16x16x32_bf16 v[32:35], v[180:183], v[196:199], v[32:35]
	v_mfma_f32_16x16x32_bf16 v[20:23], v[172:175], v[204:207], v[20:23]
	v_mfma_f32_16x16x32_bf16 v[16:19], v[180:183], v[204:207], v[16:19]
	v_mfma_f32_16x16x32_bf16 v[4:7], v[172:175], v[212:215], v[4:7]
	v_mfma_f32_16x16x32_bf16 v[0:3], v[180:183], v[212:215], v[0:3]
	s_barrier
	s_setprio 0
	s_add_i32 s76, s76, 2
	s_add_u32 s51, s51, 0x100
	s_addc_u32 s75, s75, 0
	s_cmp_gt_u32 s76, 13
	s_mov_b64 s[48:49], s[52:53]
.LBB0_466:
	ds_read_b128 v[144:147], v151
	ds_read_b128 v[156:159], v151 offset:1024
	ds_read_b128 v[160:163], v151 offset:2048
	ds_read_b128 v[164:167], v151 offset:3072
	ds_read_b128 v[168:171], v152
	ds_read_b128 v[172:175], v152 offset:1024
	ds_read_b128 v[176:179], v152 offset:2048
	ds_read_b128 v[180:183], v152 offset:3072
	ds_read_b128 v[184:187], v153
	ds_read_b128 v[188:191], v153 offset:1024
	ds_read_b128 v[192:195], v153 offset:2048
	ds_read_b128 v[196:199], v153 offset:3072
	ds_read_b128 v[200:203], v153 offset:4096
	ds_read_b128 v[204:207], v153 offset:5120
	ds_read_b128 v[208:211], v153 offset:6144
	ds_read_b128 v[212:215], v153 offset:7168
	s_add_u32 s52, s48, 0x100
	s_addc_u32 s53, s49, 0
	s_cmp_eq_u32 s76, 12
	s_cselect_b32 s79, s47, s53
	s_cselect_b32 s78, s74, s52
	s_cselect_b32 s55, s41, s75
	s_cselect_b32 s54, s50, s51
	s_add_i32 m0, s56, 0xc000
	v_lshl_add_u64 v[216:217], s[48:49], 0, v[136:137]
	global_load_lds_dwordx4 v[216:217], off
	s_add_i32 m0, s56, 0xe000
	v_lshl_add_u64 v[216:217], s[48:49], 0, v[138:139]
	global_load_lds_dwordx4 v[216:217], off
	s_waitcnt vmcnt(8) lgkmcnt(0)
	s_setprio 1
	s_barrier
	v_mfma_f32_16x16x32_bf16 v[124:127], v[144:147], v[184:187], v[124:127]
	v_mfma_f32_16x16x32_bf16 v[120:123], v[160:163], v[184:187], v[120:123]
	v_mfma_f32_16x16x32_bf16 v[108:111], v[144:147], v[192:195], v[108:111]
	v_mfma_f32_16x16x32_bf16 v[104:107], v[160:163], v[192:195], v[104:107]
	v_mfma_f32_16x16x32_bf16 v[92:95], v[144:147], v[200:203], v[92:95]
	v_mfma_f32_16x16x32_bf16 v[88:91], v[160:163], v[200:203], v[88:91]
	v_mfma_f32_16x16x32_bf16 v[76:79], v[144:147], v[208:211], v[76:79]
	v_mfma_f32_16x16x32_bf16 v[72:75], v[160:163], v[208:211], v[72:75]
	v_mfma_f32_16x16x32_bf16 v[124:127], v[156:159], v[188:191], v[124:127]
	v_mfma_f32_16x16x32_bf16 v[120:123], v[164:167], v[188:191], v[120:123]
	v_mfma_f32_16x16x32_bf16 v[108:111], v[156:159], v[196:199], v[108:111]
	v_mfma_f32_16x16x32_bf16 v[104:107], v[164:167], v[196:199], v[104:107]
	v_mfma_f32_16x16x32_bf16 v[92:95], v[156:159], v[204:207], v[92:95]
	v_mfma_f32_16x16x32_bf16 v[88:91], v[164:167], v[204:207], v[88:91]
	v_mfma_f32_16x16x32_bf16 v[76:79], v[156:159], v[212:215], v[76:79]
	v_mfma_f32_16x16x32_bf16 v[72:75], v[164:167], v[212:215], v[72:75]
	v_mfma_f32_16x16x32_bf16 v[116:119], v[168:171], v[184:187], v[116:119]
	v_mfma_f32_16x16x32_bf16 v[112:115], v[176:179], v[184:187], v[112:115]
	v_mfma_f32_16x16x32_bf16 v[100:103], v[168:171], v[192:195], v[100:103]
	v_mfma_f32_16x16x32_bf16 v[96:99], v[176:179], v[192:195], v[96:99]
	v_mfma_f32_16x16x32_bf16 v[84:87], v[168:171], v[200:203], v[84:87]
	v_mfma_f32_16x16x32_bf16 v[80:83], v[176:179], v[200:203], v[80:83]
	v_mfma_f32_16x16x32_bf16 v[68:71], v[168:171], v[208:211], v[68:71]
	v_mfma_f32_16x16x32_bf16 v[64:67], v[176:179], v[208:211], v[64:67]
	v_mfma_f32_16x16x32_bf16 v[116:119], v[172:175], v[188:191], v[116:119]
	v_mfma_f32_16x16x32_bf16 v[112:115], v[180:183], v[188:191], v[112:115]
	v_mfma_f32_16x16x32_bf16 v[100:103], v[172:175], v[196:199], v[100:103]
	v_mfma_f32_16x16x32_bf16 v[96:99], v[180:183], v[196:199], v[96:99]
	v_mfma_f32_16x16x32_bf16 v[84:87], v[172:175], v[204:207], v[84:87]
	v_mfma_f32_16x16x32_bf16 v[80:83], v[180:183], v[204:207], v[80:83]
	v_mfma_f32_16x16x32_bf16 v[68:71], v[172:175], v[212:215], v[68:71]
	v_mfma_f32_16x16x32_bf16 v[64:67], v[180:183], v[212:215], v[64:67]
	s_barrier
	s_setprio 0
	s_add_i32 s48, s67, s35
	v_lshl_add_u64 v[216:217], s[54:55], 0, v[130:131]
	s_mov_b32 m0, s48
	ds_read_b128 v[184:187], v153 offset:16384
	ds_read_b128 v[188:191], v153 offset:17408
	ds_read_b128 v[192:195], v153 offset:18432
	ds_read_b128 v[196:199], v153 offset:19456
	ds_read_b128 v[200:203], v153 offset:20480
	ds_read_b128 v[204:207], v153 offset:21504
	ds_read_b128 v[208:211], v153 offset:22528
	ds_read_b128 v[212:215], v153 offset:23552
	global_load_lds_dwordx4 v[216:217], off
	s_add_i32 m0, s48, 0x2000
	s_add_u32 s48, s54, 0x40000
	v_lshl_add_u64 v[220:221], s[54:55], 0, v[134:135]
	s_addc_u32 s49, s55, 0
	s_add_i32 s68, s72, s35
	global_load_lds_dwordx4 v[220:221], off
	v_lshl_add_u64 v[224:225], s[48:49], 0, v[130:131]
	s_mov_b32 m0, s68
	v_lshl_add_u64 v[226:227], s[78:79], 0, v[132:133]
	global_load_lds_dwordx4 v[224:225], off
	v_lshl_add_u64 v[224:225], s[48:49], 0, v[134:135]
	s_add_i32 m0, s68, 0x2000
	v_lshl_add_u64 v[228:229], v[226:227], 0, s[12:13]
	global_load_lds_dwordx4 v[224:225], off
	s_mov_b32 m0, s56
	v_lshl_add_u64 v[224:225], s[78:79], 0, v[128:129]
	global_load_lds_dwordx4 v[224:225], off
	s_mov_b32 m0, s57
	s_nop 0
	global_load_lds_dwordx4 v[228:229], off
	s_waitcnt vmcnt(8) lgkmcnt(0)
	s_setprio 1
	s_barrier
	v_mfma_f32_16x16x32_bf16 v[60:63], v[144:147], v[184:187], v[60:63]
	v_mfma_f32_16x16x32_bf16 v[56:59], v[160:163], v[184:187], v[56:59]
	v_mfma_f32_16x16x32_bf16 v[44:47], v[144:147], v[192:195], v[44:47]
	v_mfma_f32_16x16x32_bf16 v[40:43], v[160:163], v[192:195], v[40:43]
	v_mfma_f32_16x16x32_bf16 v[28:31], v[144:147], v[200:203], v[28:31]
	v_mfma_f32_16x16x32_bf16 v[24:27], v[160:163], v[200:203], v[24:27]
	v_mfma_f32_16x16x32_bf16 v[12:15], v[144:147], v[208:211], v[12:15]
	v_mfma_f32_16x16x32_bf16 v[8:11], v[160:163], v[208:211], v[8:11]
	v_mfma_f32_16x16x32_bf16 v[60:63], v[156:159], v[188:191], v[60:63]
	v_mfma_f32_16x16x32_bf16 v[56:59], v[164:167], v[188:191], v[56:59]
	v_mfma_f32_16x16x32_bf16 v[44:47], v[156:159], v[196:199], v[44:47]
	v_mfma_f32_16x16x32_bf16 v[40:43], v[164:167], v[196:199], v[40:43]
	v_mfma_f32_16x16x32_bf16 v[28:31], v[156:159], v[204:207], v[28:31]
	v_mfma_f32_16x16x32_bf16 v[24:27], v[164:167], v[204:207], v[24:27]
	v_mfma_f32_16x16x32_bf16 v[12:15], v[156:159], v[212:215], v[12:15]
	v_mfma_f32_16x16x32_bf16 v[8:11], v[164:167], v[212:215], v[8:11]
	v_mfma_f32_16x16x32_bf16 v[52:55], v[168:171], v[184:187], v[52:55]
	v_mfma_f32_16x16x32_bf16 v[48:51], v[176:179], v[184:187], v[48:51]
	v_mfma_f32_16x16x32_bf16 v[36:39], v[168:171], v[192:195], v[36:39]
	v_mfma_f32_16x16x32_bf16 v[32:35], v[176:179], v[192:195], v[32:35]
	v_mfma_f32_16x16x32_bf16 v[20:23], v[168:171], v[200:203], v[20:23]
	v_mfma_f32_16x16x32_bf16 v[16:19], v[176:179], v[200:203], v[16:19]
	v_mfma_f32_16x16x32_bf16 v[4:7], v[168:171], v[208:211], v[4:7]
	v_mfma_f32_16x16x32_bf16 v[0:3], v[176:179], v[208:211], v[0:3]
	v_mfma_f32_16x16x32_bf16 v[52:55], v[172:175], v[188:191], v[52:55]
	v_mfma_f32_16x16x32_bf16 v[48:51], v[180:183], v[188:191], v[48:51]
	v_mfma_f32_16x16x32_bf16 v[36:39], v[172:175], v[196:199], v[36:39]
	v_mfma_f32_16x16x32_bf16 v[32:35], v[180:183], v[196:199], v[32:35]
	v_mfma_f32_16x16x32_bf16 v[20:23], v[172:175], v[204:207], v[20:23]
	v_mfma_f32_16x16x32_bf16 v[16:19], v[180:183], v[204:207], v[16:19]
	v_mfma_f32_16x16x32_bf16 v[4:7], v[172:175], v[212:215], v[4:7]
	v_mfma_f32_16x16x32_bf16 v[0:3], v[180:183], v[212:215], v[0:3]
	s_barrier
	s_setprio 0
	s_add_i32 s48, 0, 0x18000
	v_add_u32_e32 v155, s48, v149
	s_add_i32 s68, 0, 0x1c000
	ds_read_b128 v[144:147], v155
	ds_read_b128 v[156:159], v155 offset:1024
	ds_read_b128 v[160:163], v155 offset:2048
	ds_read_b128 v[164:167], v155 offset:3072
	v_add_u32_e32 v155, s68, v149
	ds_read_b128 v[168:171], v155
	ds_read_b128 v[172:175], v155 offset:1024
	ds_read_b128 v[176:179], v155 offset:2048
	ds_read_b128 v[180:183], v155 offset:3072
	s_mov_b32 m0, s58
	v_lshl_add_u64 v[228:229], v[224:225], 0, s[8:9]
	ds_read_b128 v[184:187], v153 offset:32768
	ds_read_b128 v[188:191], v153 offset:33792
	ds_read_b128 v[192:195], v153 offset:34816
	ds_read_b128 v[196:199], v153 offset:35840
	ds_read_b128 v[200:203], v153 offset:36864
	ds_read_b128 v[204:207], v153 offset:37888
	ds_read_b128 v[208:211], v153 offset:38912
	ds_read_b128 v[212:215], v153 offset:39936
	global_load_lds_dwordx4 v[228:229], off
	s_mov_b32 m0, s59
	v_lshl_add_u64 v[228:229], v[226:227], 0, s[14:15]
	global_load_lds_dwordx4 v[228:229], off
	s_waitcnt vmcnt(8) lgkmcnt(0)
	s_setprio 1
	s_barrier
	v_mfma_f32_16x16x32_bf16 v[124:127], v[144:147], v[184:187], v[124:127]
	v_mfma_f32_16x16x32_bf16 v[120:123], v[160:163], v[184:187], v[120:123]
	v_mfma_f32_16x16x32_bf16 v[108:111], v[144:147], v[192:195], v[108:111]
	v_mfma_f32_16x16x32_bf16 v[104:107], v[160:163], v[192:195], v[104:107]
	v_mfma_f32_16x16x32_bf16 v[92:95], v[144:147], v[200:203], v[92:95]
	v_mfma_f32_16x16x32_bf16 v[88:91], v[160:163], v[200:203], v[88:91]
	v_mfma_f32_16x16x32_bf16 v[76:79], v[144:147], v[208:211], v[76:79]
	v_mfma_f32_16x16x32_bf16 v[72:75], v[160:163], v[208:211], v[72:75]
	v_mfma_f32_16x16x32_bf16 v[124:127], v[156:159], v[188:191], v[124:127]
	v_mfma_f32_16x16x32_bf16 v[120:123], v[164:167], v[188:191], v[120:123]
	v_mfma_f32_16x16x32_bf16 v[108:111], v[156:159], v[196:199], v[108:111]
	v_mfma_f32_16x16x32_bf16 v[104:107], v[164:167], v[196:199], v[104:107]
	v_mfma_f32_16x16x32_bf16 v[92:95], v[156:159], v[204:207], v[92:95]
	v_mfma_f32_16x16x32_bf16 v[88:91], v[164:167], v[204:207], v[88:91]
	v_mfma_f32_16x16x32_bf16 v[76:79], v[156:159], v[212:215], v[76:79]
	v_mfma_f32_16x16x32_bf16 v[72:75], v[164:167], v[212:215], v[72:75]
	v_mfma_f32_16x16x32_bf16 v[116:119], v[168:171], v[184:187], v[116:119]
	v_mfma_f32_16x16x32_bf16 v[112:115], v[176:179], v[184:187], v[112:115]
	v_mfma_f32_16x16x32_bf16 v[100:103], v[168:171], v[192:195], v[100:103]
	v_mfma_f32_16x16x32_bf16 v[96:99], v[176:179], v[192:195], v[96:99]
	v_mfma_f32_16x16x32_bf16 v[84:87], v[168:171], v[200:203], v[84:87]
	v_mfma_f32_16x16x32_bf16 v[80:83], v[176:179], v[200:203], v[80:83]
	v_mfma_f32_16x16x32_bf16 v[68:71], v[168:171], v[208:211], v[68:71]
	v_mfma_f32_16x16x32_bf16 v[64:67], v[176:179], v[208:211], v[64:67]
	v_mfma_f32_16x16x32_bf16 v[116:119], v[172:175], v[188:191], v[116:119]
	v_mfma_f32_16x16x32_bf16 v[112:115], v[180:183], v[188:191], v[112:115]
	v_mfma_f32_16x16x32_bf16 v[100:103], v[172:175], v[196:199], v[100:103]
	v_mfma_f32_16x16x32_bf16 v[96:99], v[180:183], v[196:199], v[96:99]
	v_mfma_f32_16x16x32_bf16 v[84:87], v[172:175], v[204:207], v[84:87]
	v_mfma_f32_16x16x32_bf16 v[80:83], v[180:183], v[204:207], v[80:83]
	v_mfma_f32_16x16x32_bf16 v[68:71], v[172:175], v[212:215], v[68:71]
	v_mfma_f32_16x16x32_bf16 v[64:67], v[180:183], v[212:215], v[64:67]
	s_barrier
	s_setprio 0
	s_add_i32 s48, s48, s35
	v_lshl_add_u64 v[216:217], v[216:217], 0, s[24:25]
	s_mov_b32 m0, s48
	ds_read_b128 v[184:187], v153 offset:49152
	ds_read_b128 v[188:191], v153 offset:50176
	ds_read_b128 v[192:195], v153 offset:51200
	ds_read_b128 v[196:199], v153 offset:52224
	ds_read_b128 v[200:203], v153 offset:53248
	ds_read_b128 v[204:207], v153 offset:54272
	ds_read_b128 v[208:211], v153 offset:55296
	ds_read_b128 v[212:215], v153 offset:56320
	global_load_lds_dwordx4 v[216:217], off
	s_add_i32 m0, s48, 0x2000
	s_add_u32 s48, s54, 0x40080
	v_lshl_add_u64 v[216:217], v[220:221], 0, s[24:25]
	s_addc_u32 s49, s55, 0
	s_add_i32 s54, s68, s35
	global_load_lds_dwordx4 v[216:217], off
	s_mov_b32 m0, s54
	v_lshl_add_u64 v[216:217], s[48:49], 0, v[130:131]
	global_load_lds_dwordx4 v[216:217], off
	s_add_i32 m0, s54, 0x2000
	v_lshl_add_u64 v[216:217], s[48:49], 0, v[134:135]
	global_load_lds_dwordx4 v[216:217], off
	s_mov_b32 m0, s61
	v_lshl_add_u64 v[216:217], v[224:225], 0, s[24:25]
	global_load_lds_dwordx4 v[216:217], off
	s_mov_b32 m0, s62
	v_lshl_add_u64 v[216:217], v[226:227], 0, s[36:37]
	global_load_lds_dwordx4 v[216:217], off
	s_waitcnt vmcnt(8) lgkmcnt(0)
	s_setprio 1
	s_barrier
	v_mfma_f32_16x16x32_bf16 v[60:63], v[144:147], v[184:187], v[60:63]
	v_mfma_f32_16x16x32_bf16 v[56:59], v[160:163], v[184:187], v[56:59]
	v_mfma_f32_16x16x32_bf16 v[44:47], v[144:147], v[192:195], v[44:47]
	v_mfma_f32_16x16x32_bf16 v[40:43], v[160:163], v[192:195], v[40:43]
	v_mfma_f32_16x16x32_bf16 v[28:31], v[144:147], v[200:203], v[28:31]
	v_mfma_f32_16x16x32_bf16 v[24:27], v[160:163], v[200:203], v[24:27]
	v_mfma_f32_16x16x32_bf16 v[12:15], v[144:147], v[208:211], v[12:15]
	v_mfma_f32_16x16x32_bf16 v[8:11], v[160:163], v[208:211], v[8:11]
	v_mfma_f32_16x16x32_bf16 v[60:63], v[156:159], v[188:191], v[60:63]
	v_mfma_f32_16x16x32_bf16 v[56:59], v[164:167], v[188:191], v[56:59]
	v_mfma_f32_16x16x32_bf16 v[44:47], v[156:159], v[196:199], v[44:47]
	v_mfma_f32_16x16x32_bf16 v[40:43], v[164:167], v[196:199], v[40:43]
	v_mfma_f32_16x16x32_bf16 v[28:31], v[156:159], v[204:207], v[28:31]
	v_mfma_f32_16x16x32_bf16 v[24:27], v[164:167], v[204:207], v[24:27]
	v_mfma_f32_16x16x32_bf16 v[12:15], v[156:159], v[212:215], v[12:15]
	v_mfma_f32_16x16x32_bf16 v[8:11], v[164:167], v[212:215], v[8:11]
	v_mfma_f32_16x16x32_bf16 v[52:55], v[168:171], v[184:187], v[52:55]
	v_mfma_f32_16x16x32_bf16 v[48:51], v[176:179], v[184:187], v[48:51]
	v_mfma_f32_16x16x32_bf16 v[36:39], v[168:171], v[192:195], v[36:39]
	v_mfma_f32_16x16x32_bf16 v[32:35], v[176:179], v[192:195], v[32:35]
	v_mfma_f32_16x16x32_bf16 v[20:23], v[168:171], v[200:203], v[20:23]
	v_mfma_f32_16x16x32_bf16 v[16:19], v[176:179], v[200:203], v[16:19]
	v_mfma_f32_16x16x32_bf16 v[4:7], v[168:171], v[208:211], v[4:7]
	v_mfma_f32_16x16x32_bf16 v[0:3], v[176:179], v[208:211], v[0:3]
	v_mfma_f32_16x16x32_bf16 v[52:55], v[172:175], v[188:191], v[52:55]
	v_mfma_f32_16x16x32_bf16 v[48:51], v[180:183], v[188:191], v[48:51]
	v_mfma_f32_16x16x32_bf16 v[36:39], v[172:175], v[196:199], v[36:39]
	v_mfma_f32_16x16x32_bf16 v[32:35], v[180:183], v[196:199], v[32:35]
	v_mfma_f32_16x16x32_bf16 v[20:23], v[172:175], v[204:207], v[20:23]
	v_mfma_f32_16x16x32_bf16 v[16:19], v[180:183], v[204:207], v[16:19]
	v_mfma_f32_16x16x32_bf16 v[4:7], v[172:175], v[212:215], v[4:7]
	v_mfma_f32_16x16x32_bf16 v[0:3], v[180:183], v[212:215], v[0:3]
	s_barrier
	s_setprio 0
	s_add_i32 s76, s76, 2
	s_add_u32 s51, s51, 0x100
	s_addc_u32 s75, s75, 0
	s_cmp_gt_u32 s76, 13
	s_mov_b64 s[48:49], s[52:53]
	s_cbranch_scc0 .LBB0_466

.LBB0_564:
	s_ashr_i32 s77, s76, 31
	s_lshl_b64 s[50:51], s[76:77], 19
	s_add_u32 s82, s49, s50
	s_addc_u32 s83, s53, s51
	s_and_b64 s[0:1], s[0:1], exec
	s_cselect_b32 s13, s83, s89
	s_cselect_b32 s77, s82, s88
	v_lshl_add_u64 v[92:93], s[84:85], 0, v[168:169]
	s_add_u32 vcc_lo, s88, 0x100
	v_lshl_add_u64 v[130:131], v[92:93], 0, s[86:87]
	s_addc_u32 vcc_hi, s89, 0
	s_mov_b32 s50, -2
	s_mov_b64 s[0:1], 0
	s_waitcnt vmcnt(0)
	ds_read_b128 v[132:135], v207
	ds_read_b128 v[136:139], v207 offset:1024
	ds_read_b128 v[140:143], v207 offset:2048
	ds_read_b128 v[144:147], v207 offset:3072
	ds_read_b128 v[148:151], v208
	ds_read_b128 v[152:155], v208 offset:1024
	ds_read_b128 v[156:159], v208 offset:2048
	ds_read_b128 v[174:177], v208 offset:3072
	s_add_u32 s51, s84, s0
	s_addc_u32 s68, s85, s1
	s_add_u32 s51, s51, 0x100
	s_addc_u32 s68, s68, 0
	s_add_u32 s69, vcc_lo, s0
	s_addc_u32 s70, vcc_hi, s1
	s_cmpk_eq_i32 s0, 0x700
	s_cselect_b32 s91, s79, s68
	s_cselect_b32 s90, s78, s51
	s_cselect_b32 s51, s81, s87
	s_cselect_b32 s71, s80, s86
	s_cselect_b32 s89, s13, s70
	s_cselect_b32 s88, s77, s69
	v_lshl_add_u64 v[160:161], v[92:93], 0, s[0:1]
	s_add_i32 m0, s59, 0xc000
	ds_read_b128 v[194:197], v209
	ds_read_b128 v[198:201], v209 offset:1024
	ds_read_b128 v[212:215], v209 offset:2048
	ds_read_b128 v[224:227], v209 offset:3072
	ds_read_b128 v[228:231], v209 offset:4096
	ds_read_b128 v[232:235], v209 offset:5120
	ds_read_b128 v[236:239], v209 offset:6144
	ds_read_b128 v[240:243], v209 offset:7168
	global_load_lds_dwordx4 v[160:161], off
	s_add_i32 m0, s59, 0xe000
	v_lshl_add_u64 v[160:161], v[130:131], 0, s[0:1]
	global_load_lds_dwordx4 v[160:161], off
	s_waitcnt vmcnt(8) lgkmcnt(0)
	s_setprio 1
	s_barrier
	v_mfma_f32_16x16x32_bf16 v[126:129], v[132:135], v[194:197], 0
	v_mfma_f32_16x16x32_bf16 v[60:63], v[140:143], v[194:197], 0
	v_mfma_f32_16x16x32_bf16 v[118:121], v[132:135], v[212:215], 0
	v_mfma_f32_16x16x32_bf16 v[52:55], v[140:143], v[212:215], 0
	v_mfma_f32_16x16x32_bf16 v[110:113], v[132:135], v[228:231], 0
	v_mfma_f32_16x16x32_bf16 v[44:47], v[140:143], v[228:231], 0
	v_mfma_f32_16x16x32_bf16 v[94:97], v[132:135], v[236:239], 0
	v_mfma_f32_16x16x32_bf16 v[28:31], v[140:143], v[236:239], 0
	v_mfma_f32_16x16x32_bf16 v[126:129], v[136:139], v[198:201], v[126:129]
	v_mfma_f32_16x16x32_bf16 v[60:63], v[144:147], v[198:201], v[60:63]
	v_mfma_f32_16x16x32_bf16 v[118:121], v[136:139], v[224:227], v[118:121]
	v_mfma_f32_16x16x32_bf16 v[52:55], v[144:147], v[224:227], v[52:55]
	v_mfma_f32_16x16x32_bf16 v[110:113], v[136:139], v[232:235], v[110:113]
	v_mfma_f32_16x16x32_bf16 v[44:47], v[144:147], v[232:235], v[44:47]
	v_mfma_f32_16x16x32_bf16 v[94:97], v[136:139], v[240:243], v[94:97]
	v_mfma_f32_16x16x32_bf16 v[28:31], v[144:147], v[240:243], v[28:31]
	v_mfma_f32_16x16x32_bf16 v[122:125], v[148:151], v[194:197], 0
	v_mfma_f32_16x16x32_bf16 v[56:59], v[156:159], v[194:197], 0
	v_mfma_f32_16x16x32_bf16 v[114:117], v[148:151], v[212:215], 0
	v_mfma_f32_16x16x32_bf16 v[48:51], v[156:159], v[212:215], 0
	v_mfma_f32_16x16x32_bf16 v[102:105], v[148:151], v[228:231], 0
	v_mfma_f32_16x16x32_bf16 v[36:39], v[156:159], v[228:231], 0
	v_mfma_f32_16x16x32_bf16 v[88:91], v[148:151], v[236:239], 0
	v_mfma_f32_16x16x32_bf16 v[24:27], v[156:159], v[236:239], 0
	v_mfma_f32_16x16x32_bf16 v[122:125], v[152:155], v[198:201], v[122:125]
	v_mfma_f32_16x16x32_bf16 v[56:59], v[174:177], v[198:201], v[56:59]
	v_mfma_f32_16x16x32_bf16 v[114:117], v[152:155], v[224:227], v[114:117]
	v_mfma_f32_16x16x32_bf16 v[48:51], v[174:177], v[224:227], v[48:51]
	v_mfma_f32_16x16x32_bf16 v[102:105], v[152:155], v[232:235], v[102:105]
	v_mfma_f32_16x16x32_bf16 v[36:39], v[174:177], v[232:235], v[36:39]
	v_mfma_f32_16x16x32_bf16 v[88:91], v[152:155], v[240:243], v[88:91]
	v_mfma_f32_16x16x32_bf16 v[24:27], v[174:177], v[240:243], v[24:27]
	s_barrier
	s_setprio 0
	s_add_i32 s68, s95, s57
	v_lshl_add_u64 v[160:161], s[88:89], 0, v[164:165]
	s_mov_b32 m0, s68
	ds_read_b128 v[194:197], v209 offset:16384
	ds_read_b128 v[198:201], v209 offset:17408
	ds_read_b128 v[212:215], v209 offset:18432
	ds_read_b128 v[224:227], v209 offset:19456
	ds_read_b128 v[228:231], v209 offset:20480
	ds_read_b128 v[232:235], v209 offset:21504
	ds_read_b128 v[236:239], v209 offset:22528
	ds_read_b128 v[240:243], v209 offset:23552
	global_load_lds_dwordx4 v[160:161], off
	s_add_i32 m0, s68, 0x2000
	s_add_u32 s68, s88, 0x40000
	v_lshl_add_u64 v[216:217], s[88:89], 0, v[166:167]
	s_addc_u32 s69, s89, 0
	s_add_i32 s70, s96, s57
	global_load_lds_dwordx4 v[216:217], off
	s_mov_b32 m0, s70
	v_lshl_add_u64 v[220:221], s[68:69], 0, v[164:165]
	global_load_lds_dwordx4 v[220:221], off
	s_add_i32 m0, s70, 0x2000
	v_lshl_add_u64 v[220:221], s[68:69], 0, v[166:167]
	s_add_u32 s68, s90, s71
	global_load_lds_dwordx4 v[220:221], off
	v_lshl_add_u64 v[220:221], s[90:91], 0, v[162:163]
	s_mov_b32 m0, s59
	s_addc_u32 s69, s91, s51
	global_load_lds_dwordx4 v[220:221], off
	s_mov_b32 m0, s61
	v_lshl_add_u64 v[244:245], s[68:69], 0, v[162:163]
	global_load_lds_dwordx4 v[244:245], off
	s_waitcnt vmcnt(8) lgkmcnt(0)
	s_setprio 1
	s_barrier
	v_mfma_f32_16x16x32_bf16 v[84:87], v[132:135], v[194:197], 0
	v_mfma_f32_16x16x32_bf16 v[20:23], v[140:143], v[194:197], 0
	v_mfma_f32_16x16x32_bf16 v[76:79], v[132:135], v[212:215], 0
	v_mfma_f32_16x16x32_bf16 v[12:15], v[140:143], v[212:215], 0
	v_mfma_f32_16x16x32_bf16 v[68:71], v[132:135], v[228:231], 0
	v_mfma_f32_16x16x32_bf16 v[4:7], v[140:143], v[228:231], 0
	v_mfma_f32_16x16x32_bf16 v[106:109], v[132:135], v[236:239], 0
	v_mfma_f32_16x16x32_bf16 v[40:43], v[140:143], v[236:239], 0
	v_mfma_f32_16x16x32_bf16 v[84:87], v[136:139], v[198:201], v[84:87]
	v_mfma_f32_16x16x32_bf16 v[20:23], v[144:147], v[198:201], v[20:23]
	v_mfma_f32_16x16x32_bf16 v[76:79], v[136:139], v[224:227], v[76:79]
	v_mfma_f32_16x16x32_bf16 v[12:15], v[144:147], v[224:227], v[12:15]
	v_mfma_f32_16x16x32_bf16 v[68:71], v[136:139], v[232:235], v[68:71]
	v_mfma_f32_16x16x32_bf16 v[4:7], v[144:147], v[232:235], v[4:7]
	v_mfma_f32_16x16x32_bf16 v[106:109], v[136:139], v[240:243], v[106:109]
	v_mfma_f32_16x16x32_bf16 v[40:43], v[144:147], v[240:243], v[40:43]
	v_mfma_f32_16x16x32_bf16 v[80:83], v[148:151], v[194:197], 0
	v_mfma_f32_16x16x32_bf16 v[16:19], v[156:159], v[194:197], 0
	v_mfma_f32_16x16x32_bf16 v[72:75], v[148:151], v[212:215], 0
	v_mfma_f32_16x16x32_bf16 v[8:11], v[156:159], v[212:215], 0
	v_mfma_f32_16x16x32_bf16 v[64:67], v[148:151], v[228:231], 0
	v_mfma_f32_16x16x32_bf16 v[0:3], v[156:159], v[228:231], 0
	v_mfma_f32_16x16x32_bf16 v[98:101], v[148:151], v[236:239], 0
	v_mfma_f32_16x16x32_bf16 v[32:35], v[156:159], v[236:239], 0
	v_mfma_f32_16x16x32_bf16 v[80:83], v[152:155], v[198:201], v[80:83]
	v_mfma_f32_16x16x32_bf16 v[16:19], v[174:177], v[198:201], v[16:19]
	v_mfma_f32_16x16x32_bf16 v[72:75], v[152:155], v[224:227], v[72:75]
	v_mfma_f32_16x16x32_bf16 v[8:11], v[174:177], v[224:227], v[8:11]
	v_mfma_f32_16x16x32_bf16 v[64:67], v[152:155], v[232:235], v[64:67]
	v_mfma_f32_16x16x32_bf16 v[0:3], v[174:177], v[232:235], v[0:3]
	v_mfma_f32_16x16x32_bf16 v[98:101], v[152:155], v[240:243], v[98:101]
	v_mfma_f32_16x16x32_bf16 v[32:35], v[174:177], v[240:243], v[32:35]
	s_barrier
	s_setprio 0
	s_add_i32 s70, 0, 0x18000
	s_add_i32 s14, 0, 0x1c000
	v_add_u32_e32 v144, s70, v203
	v_add_u32_e32 v174, s14, v203
	ds_read_b128 v[132:135], v144
	ds_read_b128 v[136:139], v144 offset:1024
	ds_read_b128 v[140:143], v144 offset:2048
	ds_read_b128 v[144:147], v144 offset:3072
	ds_read_b128 v[148:151], v174
	ds_read_b128 v[152:155], v174 offset:1024
	ds_read_b128 v[156:159], v174 offset:2048
	ds_read_b128 v[174:177], v174 offset:3072
	ds_read_b128 v[194:197], v209 offset:32768
	ds_read_b128 v[198:201], v209 offset:33792
	ds_read_b128 v[212:215], v209 offset:34816
	ds_read_b128 v[224:227], v209 offset:35840
	ds_read_b128 v[228:231], v209 offset:36864
	ds_read_b128 v[232:235], v209 offset:37888
	ds_read_b128 v[236:239], v209 offset:38912
	ds_read_b128 v[240:243], v209 offset:39936
	s_add_u32 s68, s90, 0x2000
	s_addc_u32 s69, s91, 0
	v_lshl_add_u64 v[246:247], s[68:69], 0, v[162:163]
	s_add_u32 s68, s68, s71
	s_mov_b32 m0, s63
	s_addc_u32 s69, s69, s51
	global_load_lds_dwordx4 v[246:247], off
	s_mov_b32 m0, s67
	v_lshl_add_u64 v[246:247], s[68:69], 0, v[162:163]
	global_load_lds_dwordx4 v[246:247], off
	s_waitcnt vmcnt(8) lgkmcnt(0)
	s_setprio 1
	s_barrier
	v_mfma_f32_16x16x32_bf16 v[126:129], v[132:135], v[194:197], v[126:129]
	v_mfma_f32_16x16x32_bf16 v[60:63], v[140:143], v[194:197], v[60:63]
	v_mfma_f32_16x16x32_bf16 v[118:121], v[132:135], v[212:215], v[118:121]
	v_mfma_f32_16x16x32_bf16 v[52:55], v[140:143], v[212:215], v[52:55]
	v_mfma_f32_16x16x32_bf16 v[110:113], v[132:135], v[228:231], v[110:113]
	v_mfma_f32_16x16x32_bf16 v[44:47], v[140:143], v[228:231], v[44:47]
	v_mfma_f32_16x16x32_bf16 v[94:97], v[132:135], v[236:239], v[94:97]
	v_mfma_f32_16x16x32_bf16 v[28:31], v[140:143], v[236:239], v[28:31]
	v_mfma_f32_16x16x32_bf16 v[126:129], v[136:139], v[198:201], v[126:129]
	v_mfma_f32_16x16x32_bf16 v[60:63], v[144:147], v[198:201], v[60:63]
	v_mfma_f32_16x16x32_bf16 v[118:121], v[136:139], v[224:227], v[118:121]
	v_mfma_f32_16x16x32_bf16 v[52:55], v[144:147], v[224:227], v[52:55]
	v_mfma_f32_16x16x32_bf16 v[110:113], v[136:139], v[232:235], v[110:113]
	v_mfma_f32_16x16x32_bf16 v[44:47], v[144:147], v[232:235], v[44:47]
	v_mfma_f32_16x16x32_bf16 v[94:97], v[136:139], v[240:243], v[94:97]
	v_mfma_f32_16x16x32_bf16 v[28:31], v[144:147], v[240:243], v[28:31]
	v_mfma_f32_16x16x32_bf16 v[122:125], v[148:151], v[194:197], v[122:125]
	v_mfma_f32_16x16x32_bf16 v[56:59], v[156:159], v[194:197], v[56:59]
	v_mfma_f32_16x16x32_bf16 v[114:117], v[148:151], v[212:215], v[114:117]
	v_mfma_f32_16x16x32_bf16 v[48:51], v[156:159], v[212:215], v[48:51]
	v_mfma_f32_16x16x32_bf16 v[102:105], v[148:151], v[228:231], v[102:105]
	v_mfma_f32_16x16x32_bf16 v[36:39], v[156:159], v[228:231], v[36:39]
	v_mfma_f32_16x16x32_bf16 v[88:91], v[148:151], v[236:239], v[88:91]
	v_mfma_f32_16x16x32_bf16 v[24:27], v[156:159], v[236:239], v[24:27]
	v_mfma_f32_16x16x32_bf16 v[122:125], v[152:155], v[198:201], v[122:125]
	v_mfma_f32_16x16x32_bf16 v[56:59], v[174:177], v[198:201], v[56:59]
	v_mfma_f32_16x16x32_bf16 v[114:117], v[152:155], v[224:227], v[114:117]
	v_mfma_f32_16x16x32_bf16 v[48:51], v[174:177], v[224:227], v[48:51]
	v_mfma_f32_16x16x32_bf16 v[102:105], v[152:155], v[232:235], v[102:105]
	v_mfma_f32_16x16x32_bf16 v[36:39], v[174:177], v[232:235], v[36:39]
	v_mfma_f32_16x16x32_bf16 v[88:91], v[152:155], v[240:243], v[88:91]
	v_mfma_f32_16x16x32_bf16 v[24:27], v[174:177], v[240:243], v[24:27]
	s_barrier
	s_setprio 0
	s_add_i32 s15, s70, s57
	v_lshl_add_u64 v[160:161], v[160:161], 0, s[22:23]
	s_mov_b32 m0, s15
	ds_read_b128 v[194:197], v209 offset:49152
	ds_read_b128 v[198:201], v209 offset:50176
	ds_read_b128 v[212:215], v209 offset:51200
	ds_read_b128 v[224:227], v209 offset:52224
	ds_read_b128 v[228:231], v209 offset:53248
	ds_read_b128 v[232:235], v209 offset:54272
	ds_read_b128 v[236:239], v209 offset:55296
	ds_read_b128 v[240:243], v209 offset:56320
	global_load_lds_dwordx4 v[160:161], off
	s_add_i32 m0, s15, 0x2000
	s_add_u32 s68, s88, 0x40080
	v_lshl_add_u64 v[160:161], v[216:217], 0, s[22:23]
	s_addc_u32 s69, s89, 0
	s_add_i32 s14, s14, s57
	global_load_lds_dwordx4 v[160:161], off
	s_mov_b32 m0, s14
	v_lshl_add_u64 v[160:161], s[68:69], 0, v[164:165]
	global_load_lds_dwordx4 v[160:161], off
	s_add_i32 m0, s14, 0x2000
	v_lshl_add_u64 v[160:161], s[68:69], 0, v[166:167]
	global_load_lds_dwordx4 v[160:161], off
	s_mov_b32 m0, s75
	v_lshl_add_u64 v[160:161], v[220:221], 0, s[22:23]
	global_load_lds_dwordx4 v[160:161], off
	s_mov_b32 m0, s92
	v_lshl_add_u64 v[160:161], v[244:245], 0, s[22:23]
	global_load_lds_dwordx4 v[160:161], off
	s_waitcnt vmcnt(8) lgkmcnt(0)
	s_setprio 1
	s_barrier
	v_mfma_f32_16x16x32_bf16 v[84:87], v[132:135], v[194:197], v[84:87]
	v_mfma_f32_16x16x32_bf16 v[20:23], v[140:143], v[194:197], v[20:23]
	v_mfma_f32_16x16x32_bf16 v[76:79], v[132:135], v[212:215], v[76:79]
	v_mfma_f32_16x16x32_bf16 v[12:15], v[140:143], v[212:215], v[12:15]
	v_mfma_f32_16x16x32_bf16 v[68:71], v[132:135], v[228:231], v[68:71]
	v_mfma_f32_16x16x32_bf16 v[4:7], v[140:143], v[228:231], v[4:7]
	v_mfma_f32_16x16x32_bf16 v[106:109], v[132:135], v[236:239], v[106:109]
	v_mfma_f32_16x16x32_bf16 v[40:43], v[140:143], v[236:239], v[40:43]
	v_mfma_f32_16x16x32_bf16 v[84:87], v[136:139], v[198:201], v[84:87]
	v_mfma_f32_16x16x32_bf16 v[20:23], v[144:147], v[198:201], v[20:23]
	v_mfma_f32_16x16x32_bf16 v[76:79], v[136:139], v[224:227], v[76:79]
	v_mfma_f32_16x16x32_bf16 v[12:15], v[144:147], v[224:227], v[12:15]
	v_mfma_f32_16x16x32_bf16 v[68:71], v[136:139], v[232:235], v[68:71]
	v_mfma_f32_16x16x32_bf16 v[4:7], v[144:147], v[232:235], v[4:7]
	v_mfma_f32_16x16x32_bf16 v[106:109], v[136:139], v[240:243], v[106:109]
	v_mfma_f32_16x16x32_bf16 v[40:43], v[144:147], v[240:243], v[40:43]
	v_mfma_f32_16x16x32_bf16 v[80:83], v[148:151], v[194:197], v[80:83]
	v_mfma_f32_16x16x32_bf16 v[16:19], v[156:159], v[194:197], v[16:19]
	v_mfma_f32_16x16x32_bf16 v[72:75], v[148:151], v[212:215], v[72:75]
	v_mfma_f32_16x16x32_bf16 v[8:11], v[156:159], v[212:215], v[8:11]
	v_mfma_f32_16x16x32_bf16 v[64:67], v[148:151], v[228:231], v[64:67]
	v_mfma_f32_16x16x32_bf16 v[0:3], v[156:159], v[228:231], v[0:3]
	v_mfma_f32_16x16x32_bf16 v[98:101], v[148:151], v[236:239], v[98:101]
	v_mfma_f32_16x16x32_bf16 v[32:35], v[156:159], v[236:239], v[32:35]
	v_mfma_f32_16x16x32_bf16 v[80:83], v[152:155], v[198:201], v[80:83]
	v_mfma_f32_16x16x32_bf16 v[16:19], v[174:177], v[198:201], v[16:19]
	v_mfma_f32_16x16x32_bf16 v[72:75], v[152:155], v[224:227], v[72:75]
	v_mfma_f32_16x16x32_bf16 v[8:11], v[174:177], v[224:227], v[8:11]
	v_mfma_f32_16x16x32_bf16 v[64:67], v[152:155], v[232:235], v[64:67]
	v_mfma_f32_16x16x32_bf16 v[0:3], v[174:177], v[232:235], v[0:3]
	v_mfma_f32_16x16x32_bf16 v[98:101], v[152:155], v[240:243], v[98:101]
	v_mfma_f32_16x16x32_bf16 v[32:35], v[174:177], v[240:243], v[32:35]
	s_barrier
	s_setprio 0
	s_add_i32 s50, s50, 2
	s_add_u32 s0, s0, 0x100
	s_addc_u32 s1, s1, 0
	s_cmp_gt_u32 s50, 13
.LBB0_565:
	ds_read_b128 v[132:135], v207
	ds_read_b128 v[136:139], v207 offset:1024
	ds_read_b128 v[140:143], v207 offset:2048
	ds_read_b128 v[144:147], v207 offset:3072
	ds_read_b128 v[148:151], v208
	ds_read_b128 v[152:155], v208 offset:1024
	ds_read_b128 v[156:159], v208 offset:2048
	ds_read_b128 v[174:177], v208 offset:3072
	s_add_u32 s51, s84, s0
	s_addc_u32 s68, s85, s1
	s_add_u32 s51, s51, 0x100
	s_addc_u32 s68, s68, 0
	s_add_u32 s69, vcc_lo, s0
	s_addc_u32 s70, vcc_hi, s1
	s_cmpk_eq_i32 s0, 0x700
	s_cselect_b32 s91, s79, s68
	s_cselect_b32 s90, s78, s51
	s_cselect_b32 s51, s81, s87
	s_cselect_b32 s71, s80, s86
	s_cselect_b32 s89, s13, s70
	s_cselect_b32 s88, s77, s69
	v_lshl_add_u64 v[160:161], v[92:93], 0, s[0:1]
	s_add_i32 m0, s59, 0xc000
	ds_read_b128 v[194:197], v209
	ds_read_b128 v[198:201], v209 offset:1024
	ds_read_b128 v[212:215], v209 offset:2048
	ds_read_b128 v[224:227], v209 offset:3072
	ds_read_b128 v[228:231], v209 offset:4096
	ds_read_b128 v[232:235], v209 offset:5120
	ds_read_b128 v[236:239], v209 offset:6144
	ds_read_b128 v[240:243], v209 offset:7168
	global_load_lds_dwordx4 v[160:161], off
	s_add_i32 m0, s59, 0xe000
	v_lshl_add_u64 v[160:161], v[130:131], 0, s[0:1]
	global_load_lds_dwordx4 v[160:161], off
	s_waitcnt vmcnt(8) lgkmcnt(0)
	s_setprio 1
	s_barrier
	v_mfma_f32_16x16x32_bf16 v[126:129], v[132:135], v[194:197], v[126:129]
	v_mfma_f32_16x16x32_bf16 v[60:63], v[140:143], v[194:197], v[60:63]
	v_mfma_f32_16x16x32_bf16 v[118:121], v[132:135], v[212:215], v[118:121]
	v_mfma_f32_16x16x32_bf16 v[52:55], v[140:143], v[212:215], v[52:55]
	v_mfma_f32_16x16x32_bf16 v[110:113], v[132:135], v[228:231], v[110:113]
	v_mfma_f32_16x16x32_bf16 v[44:47], v[140:143], v[228:231], v[44:47]
	v_mfma_f32_16x16x32_bf16 v[94:97], v[132:135], v[236:239], v[94:97]
	v_mfma_f32_16x16x32_bf16 v[28:31], v[140:143], v[236:239], v[28:31]
	v_mfma_f32_16x16x32_bf16 v[126:129], v[136:139], v[198:201], v[126:129]
	v_mfma_f32_16x16x32_bf16 v[60:63], v[144:147], v[198:201], v[60:63]
	v_mfma_f32_16x16x32_bf16 v[118:121], v[136:139], v[224:227], v[118:121]
	v_mfma_f32_16x16x32_bf16 v[52:55], v[144:147], v[224:227], v[52:55]
	v_mfma_f32_16x16x32_bf16 v[110:113], v[136:139], v[232:235], v[110:113]
	v_mfma_f32_16x16x32_bf16 v[44:47], v[144:147], v[232:235], v[44:47]
	v_mfma_f32_16x16x32_bf16 v[94:97], v[136:139], v[240:243], v[94:97]
	v_mfma_f32_16x16x32_bf16 v[28:31], v[144:147], v[240:243], v[28:31]
	v_mfma_f32_16x16x32_bf16 v[122:125], v[148:151], v[194:197], v[122:125]
	v_mfma_f32_16x16x32_bf16 v[56:59], v[156:159], v[194:197], v[56:59]
	v_mfma_f32_16x16x32_bf16 v[114:117], v[148:151], v[212:215], v[114:117]
	v_mfma_f32_16x16x32_bf16 v[48:51], v[156:159], v[212:215], v[48:51]
	v_mfma_f32_16x16x32_bf16 v[102:105], v[148:151], v[228:231], v[102:105]
	v_mfma_f32_16x16x32_bf16 v[36:39], v[156:159], v[228:231], v[36:39]
	v_mfma_f32_16x16x32_bf16 v[88:91], v[148:151], v[236:239], v[88:91]
	v_mfma_f32_16x16x32_bf16 v[24:27], v[156:159], v[236:239], v[24:27]
	v_mfma_f32_16x16x32_bf16 v[122:125], v[152:155], v[198:201], v[122:125]
	v_mfma_f32_16x16x32_bf16 v[56:59], v[174:177], v[198:201], v[56:59]
	v_mfma_f32_16x16x32_bf16 v[114:117], v[152:155], v[224:227], v[114:117]
	v_mfma_f32_16x16x32_bf16 v[48:51], v[174:177], v[224:227], v[48:51]
	v_mfma_f32_16x16x32_bf16 v[102:105], v[152:155], v[232:235], v[102:105]
	v_mfma_f32_16x16x32_bf16 v[36:39], v[174:177], v[232:235], v[36:39]
	v_mfma_f32_16x16x32_bf16 v[88:91], v[152:155], v[240:243], v[88:91]
	v_mfma_f32_16x16x32_bf16 v[24:27], v[174:177], v[240:243], v[24:27]
	s_barrier
	s_setprio 0
	s_add_i32 s68, s95, s57
	v_lshl_add_u64 v[160:161], s[88:89], 0, v[164:165]
	s_mov_b32 m0, s68
	ds_read_b128 v[194:197], v209 offset:16384
	ds_read_b128 v[198:201], v209 offset:17408
	ds_read_b128 v[212:215], v209 offset:18432
	ds_read_b128 v[224:227], v209 offset:19456
	ds_read_b128 v[228:231], v209 offset:20480
	ds_read_b128 v[232:235], v209 offset:21504
	ds_read_b128 v[236:239], v209 offset:22528
	ds_read_b128 v[240:243], v209 offset:23552
	global_load_lds_dwordx4 v[160:161], off
	s_add_i32 m0, s68, 0x2000
	s_add_u32 s68, s88, 0x40000
	v_lshl_add_u64 v[216:217], s[88:89], 0, v[166:167]
	s_addc_u32 s69, s89, 0
	s_add_i32 s70, s96, s57
	global_load_lds_dwordx4 v[216:217], off
	s_mov_b32 m0, s70
	v_lshl_add_u64 v[220:221], s[68:69], 0, v[164:165]
	global_load_lds_dwordx4 v[220:221], off
	s_add_i32 m0, s70, 0x2000
	v_lshl_add_u64 v[220:221], s[68:69], 0, v[166:167]
	s_add_u32 s68, s90, s71
	global_load_lds_dwordx4 v[220:221], off
	v_lshl_add_u64 v[220:221], s[90:91], 0, v[162:163]
	s_mov_b32 m0, s59
	s_addc_u32 s69, s91, s51
	global_load_lds_dwordx4 v[220:221], off
	s_mov_b32 m0, s61
	v_lshl_add_u64 v[244:245], s[68:69], 0, v[162:163]
	global_load_lds_dwordx4 v[244:245], off
	s_waitcnt vmcnt(8) lgkmcnt(0)
	s_setprio 1
	s_barrier
	v_mfma_f32_16x16x32_bf16 v[84:87], v[132:135], v[194:197], v[84:87]
	v_mfma_f32_16x16x32_bf16 v[20:23], v[140:143], v[194:197], v[20:23]
	v_mfma_f32_16x16x32_bf16 v[76:79], v[132:135], v[212:215], v[76:79]
	v_mfma_f32_16x16x32_bf16 v[12:15], v[140:143], v[212:215], v[12:15]
	v_mfma_f32_16x16x32_bf16 v[68:71], v[132:135], v[228:231], v[68:71]
	v_mfma_f32_16x16x32_bf16 v[4:7], v[140:143], v[228:231], v[4:7]
	v_mfma_f32_16x16x32_bf16 v[106:109], v[132:135], v[236:239], v[106:109]
	v_mfma_f32_16x16x32_bf16 v[40:43], v[140:143], v[236:239], v[40:43]
	v_mfma_f32_16x16x32_bf16 v[84:87], v[136:139], v[198:201], v[84:87]
	v_mfma_f32_16x16x32_bf16 v[20:23], v[144:147], v[198:201], v[20:23]
	v_mfma_f32_16x16x32_bf16 v[76:79], v[136:139], v[224:227], v[76:79]
	v_mfma_f32_16x16x32_bf16 v[12:15], v[144:147], v[224:227], v[12:15]
	v_mfma_f32_16x16x32_bf16 v[68:71], v[136:139], v[232:235], v[68:71]
	v_mfma_f32_16x16x32_bf16 v[4:7], v[144:147], v[232:235], v[4:7]
	v_mfma_f32_16x16x32_bf16 v[106:109], v[136:139], v[240:243], v[106:109]
	v_mfma_f32_16x16x32_bf16 v[40:43], v[144:147], v[240:243], v[40:43]
	v_mfma_f32_16x16x32_bf16 v[80:83], v[148:151], v[194:197], v[80:83]
	v_mfma_f32_16x16x32_bf16 v[16:19], v[156:159], v[194:197], v[16:19]
	v_mfma_f32_16x16x32_bf16 v[72:75], v[148:151], v[212:215], v[72:75]
	v_mfma_f32_16x16x32_bf16 v[8:11], v[156:159], v[212:215], v[8:11]
	v_mfma_f32_16x16x32_bf16 v[64:67], v[148:151], v[228:231], v[64:67]
	v_mfma_f32_16x16x32_bf16 v[0:3], v[156:159], v[228:231], v[0:3]
	v_mfma_f32_16x16x32_bf16 v[98:101], v[148:151], v[236:239], v[98:101]
	v_mfma_f32_16x16x32_bf16 v[32:35], v[156:159], v[236:239], v[32:35]
	v_mfma_f32_16x16x32_bf16 v[80:83], v[152:155], v[198:201], v[80:83]
	v_mfma_f32_16x16x32_bf16 v[16:19], v[174:177], v[198:201], v[16:19]
	v_mfma_f32_16x16x32_bf16 v[72:75], v[152:155], v[224:227], v[72:75]
	v_mfma_f32_16x16x32_bf16 v[8:11], v[174:177], v[224:227], v[8:11]
	v_mfma_f32_16x16x32_bf16 v[64:67], v[152:155], v[232:235], v[64:67]
	v_mfma_f32_16x16x32_bf16 v[0:3], v[174:177], v[232:235], v[0:3]
	v_mfma_f32_16x16x32_bf16 v[98:101], v[152:155], v[240:243], v[98:101]
	v_mfma_f32_16x16x32_bf16 v[32:35], v[174:177], v[240:243], v[32:35]
	s_barrier
	s_setprio 0
	s_add_i32 s70, 0, 0x18000
	s_add_i32 s14, 0, 0x1c000
	v_add_u32_e32 v144, s70, v203
	v_add_u32_e32 v174, s14, v203
	ds_read_b128 v[132:135], v144
	ds_read_b128 v[136:139], v144 offset:1024
	ds_read_b128 v[140:143], v144 offset:2048
	ds_read_b128 v[144:147], v144 offset:3072
	ds_read_b128 v[148:151], v174
	ds_read_b128 v[152:155], v174 offset:1024
	ds_read_b128 v[156:159], v174 offset:2048
	ds_read_b128 v[174:177], v174 offset:3072
	ds_read_b128 v[194:197], v209 offset:32768
	ds_read_b128 v[198:201], v209 offset:33792
	ds_read_b128 v[212:215], v209 offset:34816
	ds_read_b128 v[224:227], v209 offset:35840
	ds_read_b128 v[228:231], v209 offset:36864
	ds_read_b128 v[232:235], v209 offset:37888
	ds_read_b128 v[236:239], v209 offset:38912
	ds_read_b128 v[240:243], v209 offset:39936
	s_add_u32 s68, s90, 0x2000
	s_addc_u32 s69, s91, 0
	v_lshl_add_u64 v[246:247], s[68:69], 0, v[162:163]
	s_add_u32 s68, s68, s71
	s_mov_b32 m0, s63
	s_addc_u32 s69, s69, s51
	global_load_lds_dwordx4 v[246:247], off
	s_mov_b32 m0, s67
	v_lshl_add_u64 v[246:247], s[68:69], 0, v[162:163]
	global_load_lds_dwordx4 v[246:247], off
	s_waitcnt vmcnt(8) lgkmcnt(0)
	s_setprio 1
	s_barrier
	v_mfma_f32_16x16x32_bf16 v[126:129], v[132:135], v[194:197], v[126:129]
	v_mfma_f32_16x16x32_bf16 v[60:63], v[140:143], v[194:197], v[60:63]
	v_mfma_f32_16x16x32_bf16 v[118:121], v[132:135], v[212:215], v[118:121]
	v_mfma_f32_16x16x32_bf16 v[52:55], v[140:143], v[212:215], v[52:55]
	v_mfma_f32_16x16x32_bf16 v[110:113], v[132:135], v[228:231], v[110:113]
	v_mfma_f32_16x16x32_bf16 v[44:47], v[140:143], v[228:231], v[44:47]
	v_mfma_f32_16x16x32_bf16 v[94:97], v[132:135], v[236:239], v[94:97]
	v_mfma_f32_16x16x32_bf16 v[28:31], v[140:143], v[236:239], v[28:31]
	v_mfma_f32_16x16x32_bf16 v[126:129], v[136:139], v[198:201], v[126:129]
	v_mfma_f32_16x16x32_bf16 v[60:63], v[144:147], v[198:201], v[60:63]
	v_mfma_f32_16x16x32_bf16 v[118:121], v[136:139], v[224:227], v[118:121]
	v_mfma_f32_16x16x32_bf16 v[52:55], v[144:147], v[224:227], v[52:55]
	v_mfma_f32_16x16x32_bf16 v[110:113], v[136:139], v[232:235], v[110:113]
	v_mfma_f32_16x16x32_bf16 v[44:47], v[144:147], v[232:235], v[44:47]
	v_mfma_f32_16x16x32_bf16 v[94:97], v[136:139], v[240:243], v[94:97]
	v_mfma_f32_16x16x32_bf16 v[28:31], v[144:147], v[240:243], v[28:31]
	v_mfma_f32_16x16x32_bf16 v[122:125], v[148:151], v[194:197], v[122:125]
	v_mfma_f32_16x16x32_bf16 v[56:59], v[156:159], v[194:197], v[56:59]
	v_mfma_f32_16x16x32_bf16 v[114:117], v[148:151], v[212:215], v[114:117]
	v_mfma_f32_16x16x32_bf16 v[48:51], v[156:159], v[212:215], v[48:51]
	v_mfma_f32_16x16x32_bf16 v[102:105], v[148:151], v[228:231], v[102:105]
	v_mfma_f32_16x16x32_bf16 v[36:39], v[156:159], v[228:231], v[36:39]
	v_mfma_f32_16x16x32_bf16 v[88:91], v[148:151], v[236:239], v[88:91]
	v_mfma_f32_16x16x32_bf16 v[24:27], v[156:159], v[236:239], v[24:27]
	v_mfma_f32_16x16x32_bf16 v[122:125], v[152:155], v[198:201], v[122:125]
	v_mfma_f32_16x16x32_bf16 v[56:59], v[174:177], v[198:201], v[56:59]
	v_mfma_f32_16x16x32_bf16 v[114:117], v[152:155], v[224:227], v[114:117]
	v_mfma_f32_16x16x32_bf16 v[48:51], v[174:177], v[224:227], v[48:51]
	v_mfma_f32_16x16x32_bf16 v[102:105], v[152:155], v[232:235], v[102:105]
	v_mfma_f32_16x16x32_bf16 v[36:39], v[174:177], v[232:235], v[36:39]
	v_mfma_f32_16x16x32_bf16 v[88:91], v[152:155], v[240:243], v[88:91]
	v_mfma_f32_16x16x32_bf16 v[24:27], v[174:177], v[240:243], v[24:27]
	s_barrier
	s_setprio 0
	s_add_i32 s15, s70, s57
	v_lshl_add_u64 v[160:161], v[160:161], 0, s[22:23]
	s_mov_b32 m0, s15
	ds_read_b128 v[194:197], v209 offset:49152
	ds_read_b128 v[198:201], v209 offset:50176
	ds_read_b128 v[212:215], v209 offset:51200
	ds_read_b128 v[224:227], v209 offset:52224
	ds_read_b128 v[228:231], v209 offset:53248
	ds_read_b128 v[232:235], v209 offset:54272
	ds_read_b128 v[236:239], v209 offset:55296
	ds_read_b128 v[240:243], v209 offset:56320
	global_load_lds_dwordx4 v[160:161], off
	s_add_i32 m0, s15, 0x2000
	s_add_u32 s68, s88, 0x40080
	v_lshl_add_u64 v[160:161], v[216:217], 0, s[22:23]
	s_addc_u32 s69, s89, 0
	s_add_i32 s14, s14, s57
	global_load_lds_dwordx4 v[160:161], off
	s_mov_b32 m0, s14
	v_lshl_add_u64 v[160:161], s[68:69], 0, v[164:165]
	global_load_lds_dwordx4 v[160:161], off
	s_add_i32 m0, s14, 0x2000
	v_lshl_add_u64 v[160:161], s[68:69], 0, v[166:167]
	global_load_lds_dwordx4 v[160:161], off
	s_mov_b32 m0, s75
	v_lshl_add_u64 v[160:161], v[220:221], 0, s[22:23]
	global_load_lds_dwordx4 v[160:161], off
	s_mov_b32 m0, s92
	v_lshl_add_u64 v[160:161], v[244:245], 0, s[22:23]
	global_load_lds_dwordx4 v[160:161], off
	s_waitcnt vmcnt(8) lgkmcnt(0)
	s_setprio 1
	s_barrier
	v_mfma_f32_16x16x32_bf16 v[84:87], v[132:135], v[194:197], v[84:87]
	v_mfma_f32_16x16x32_bf16 v[20:23], v[140:143], v[194:197], v[20:23]
	v_mfma_f32_16x16x32_bf16 v[76:79], v[132:135], v[212:215], v[76:79]
	v_mfma_f32_16x16x32_bf16 v[12:15], v[140:143], v[212:215], v[12:15]
	v_mfma_f32_16x16x32_bf16 v[68:71], v[132:135], v[228:231], v[68:71]
	v_mfma_f32_16x16x32_bf16 v[4:7], v[140:143], v[228:231], v[4:7]
	v_mfma_f32_16x16x32_bf16 v[106:109], v[132:135], v[236:239], v[106:109]
	v_mfma_f32_16x16x32_bf16 v[40:43], v[140:143], v[236:239], v[40:43]
	v_mfma_f32_16x16x32_bf16 v[84:87], v[136:139], v[198:201], v[84:87]
	v_mfma_f32_16x16x32_bf16 v[20:23], v[144:147], v[198:201], v[20:23]
	v_mfma_f32_16x16x32_bf16 v[76:79], v[136:139], v[224:227], v[76:79]
	v_mfma_f32_16x16x32_bf16 v[12:15], v[144:147], v[224:227], v[12:15]
	v_mfma_f32_16x16x32_bf16 v[68:71], v[136:139], v[232:235], v[68:71]
	v_mfma_f32_16x16x32_bf16 v[4:7], v[144:147], v[232:235], v[4:7]
	v_mfma_f32_16x16x32_bf16 v[106:109], v[136:139], v[240:243], v[106:109]
	v_mfma_f32_16x16x32_bf16 v[40:43], v[144:147], v[240:243], v[40:43]
	v_mfma_f32_16x16x32_bf16 v[80:83], v[148:151], v[194:197], v[80:83]
	v_mfma_f32_16x16x32_bf16 v[16:19], v[156:159], v[194:197], v[16:19]
	v_mfma_f32_16x16x32_bf16 v[72:75], v[148:151], v[212:215], v[72:75]
	v_mfma_f32_16x16x32_bf16 v[8:11], v[156:159], v[212:215], v[8:11]
	v_mfma_f32_16x16x32_bf16 v[64:67], v[148:151], v[228:231], v[64:67]
	v_mfma_f32_16x16x32_bf16 v[0:3], v[156:159], v[228:231], v[0:3]
	v_mfma_f32_16x16x32_bf16 v[98:101], v[148:151], v[236:239], v[98:101]
	v_mfma_f32_16x16x32_bf16 v[32:35], v[156:159], v[236:239], v[32:35]
	v_mfma_f32_16x16x32_bf16 v[80:83], v[152:155], v[198:201], v[80:83]
	v_mfma_f32_16x16x32_bf16 v[16:19], v[174:177], v[198:201], v[16:19]
	v_mfma_f32_16x16x32_bf16 v[72:75], v[152:155], v[224:227], v[72:75]
	v_mfma_f32_16x16x32_bf16 v[8:11], v[174:177], v[224:227], v[8:11]
	v_mfma_f32_16x16x32_bf16 v[64:67], v[152:155], v[232:235], v[64:67]
	v_mfma_f32_16x16x32_bf16 v[0:3], v[174:177], v[232:235], v[0:3]
	v_mfma_f32_16x16x32_bf16 v[98:101], v[152:155], v[240:243], v[98:101]
	v_mfma_f32_16x16x32_bf16 v[32:35], v[174:177], v[240:243], v[32:35]
	s_barrier
	s_setprio 0
	s_add_i32 s50, s50, 2
	s_add_u32 s0, s0, 0x100
	s_addc_u32 s1, s1, 0
	s_cmp_gt_u32 s50, 13
	s_cbranch_scc0 .LBB0_565

.LBB0_661:
	s_add_u32 s64, s44, 0x100
	s_addc_u32 s65, s45, 0
	s_mov_b32 s66, -2
	s_waitcnt lgkmcnt(0)
	s_waitcnt vmcnt(0)
	ds_read_b128 v[144:147], v151
	ds_read_b128 v[156:159], v151 offset:1024
	ds_read_b128 v[160:163], v151 offset:2048
	ds_read_b128 v[164:167], v151 offset:3072
	ds_read_b128 v[168:171], v152
	ds_read_b128 v[172:175], v152 offset:1024
	ds_read_b128 v[176:179], v152 offset:2048
	ds_read_b128 v[180:183], v152 offset:3072
	ds_read_b128 v[184:187], v153
	ds_read_b128 v[188:191], v153 offset:1024
	ds_read_b128 v[192:195], v153 offset:2048
	ds_read_b128 v[196:199], v153 offset:3072
	ds_read_b128 v[200:203], v153 offset:4096
	ds_read_b128 v[204:207], v153 offset:5120
	ds_read_b128 v[208:211], v153 offset:6144
	ds_read_b128 v[212:215], v153 offset:7168
	s_add_u32 s44, s42, 0x100
	s_addc_u32 s45, s43, 0
	s_cmp_eq_u32 s66, 40
	s_cselect_b32 s69, s1, s45
	s_cselect_b32 s68, s0, s44
	s_cselect_b32 s47, s41, s65
	s_cselect_b32 s46, s40, s64
	s_add_i32 m0, s48, 0xc000
	v_lshl_add_u64 v[216:217], s[42:43], 0, v[136:137]
	global_load_lds_dwordx4 v[216:217], off
	s_add_i32 m0, s48, 0xe000
	v_lshl_add_u64 v[216:217], s[42:43], 0, v[138:139]
	global_load_lds_dwordx4 v[216:217], off
	s_waitcnt vmcnt(8) lgkmcnt(0)
	s_setprio 1
	s_barrier
	v_mfma_f32_16x16x32_bf16 v[124:127], v[144:147], v[184:187], 0
	v_mfma_f32_16x16x32_bf16 v[120:123], v[160:163], v[184:187], 0
	v_mfma_f32_16x16x32_bf16 v[108:111], v[144:147], v[192:195], 0
	v_mfma_f32_16x16x32_bf16 v[104:107], v[160:163], v[192:195], 0
	v_mfma_f32_16x16x32_bf16 v[92:95], v[144:147], v[200:203], 0
	v_mfma_f32_16x16x32_bf16 v[88:91], v[160:163], v[200:203], 0
	v_mfma_f32_16x16x32_bf16 v[76:79], v[144:147], v[208:211], 0
	v_mfma_f32_16x16x32_bf16 v[72:75], v[160:163], v[208:211], 0
	v_mfma_f32_16x16x32_bf16 v[124:127], v[156:159], v[188:191], v[124:127]
	v_mfma_f32_16x16x32_bf16 v[120:123], v[164:167], v[188:191], v[120:123]
	v_mfma_f32_16x16x32_bf16 v[108:111], v[156:159], v[196:199], v[108:111]
	v_mfma_f32_16x16x32_bf16 v[104:107], v[164:167], v[196:199], v[104:107]
	v_mfma_f32_16x16x32_bf16 v[92:95], v[156:159], v[204:207], v[92:95]
	v_mfma_f32_16x16x32_bf16 v[88:91], v[164:167], v[204:207], v[88:91]
	v_mfma_f32_16x16x32_bf16 v[76:79], v[156:159], v[212:215], v[76:79]
	v_mfma_f32_16x16x32_bf16 v[72:75], v[164:167], v[212:215], v[72:75]
	v_mfma_f32_16x16x32_bf16 v[116:119], v[168:171], v[184:187], 0
	v_mfma_f32_16x16x32_bf16 v[112:115], v[176:179], v[184:187], 0
	v_mfma_f32_16x16x32_bf16 v[100:103], v[168:171], v[192:195], 0
	v_mfma_f32_16x16x32_bf16 v[96:99], v[176:179], v[192:195], 0
	v_mfma_f32_16x16x32_bf16 v[84:87], v[168:171], v[200:203], 0
	v_mfma_f32_16x16x32_bf16 v[80:83], v[176:179], v[200:203], 0
	v_mfma_f32_16x16x32_bf16 v[68:71], v[168:171], v[208:211], 0
	v_mfma_f32_16x16x32_bf16 v[64:67], v[176:179], v[208:211], 0
	v_mfma_f32_16x16x32_bf16 v[116:119], v[172:175], v[188:191], v[116:119]
	v_mfma_f32_16x16x32_bf16 v[112:115], v[180:183], v[188:191], v[112:115]
	v_mfma_f32_16x16x32_bf16 v[100:103], v[172:175], v[196:199], v[100:103]
	v_mfma_f32_16x16x32_bf16 v[96:99], v[180:183], v[196:199], v[96:99]
	v_mfma_f32_16x16x32_bf16 v[84:87], v[172:175], v[204:207], v[84:87]
	v_mfma_f32_16x16x32_bf16 v[80:83], v[180:183], v[204:207], v[80:83]
	v_mfma_f32_16x16x32_bf16 v[68:71], v[172:175], v[212:215], v[68:71]
	v_mfma_f32_16x16x32_bf16 v[64:67], v[180:183], v[212:215], v[64:67]
	s_barrier
	s_setprio 0
	s_add_i32 s42, s59, s35
	v_lshl_add_u64 v[216:217], s[46:47], 0, v[130:131]
	s_mov_b32 m0, s42
	ds_read_b128 v[184:187], v153 offset:16384
	ds_read_b128 v[188:191], v153 offset:17408
	ds_read_b128 v[192:195], v153 offset:18432
	ds_read_b128 v[196:199], v153 offset:19456
	ds_read_b128 v[200:203], v153 offset:20480
	ds_read_b128 v[204:207], v153 offset:21504
	ds_read_b128 v[208:211], v153 offset:22528
	ds_read_b128 v[212:215], v153 offset:23552
	global_load_lds_dwordx4 v[216:217], off
	s_add_i32 m0, s42, 0x2000
	s_add_u32 s42, s46, 0xb0000
	v_lshl_add_u64 v[220:221], s[46:47], 0, v[134:135]
	s_addc_u32 s43, s47, 0
	s_add_i32 s67, s60, s35
	global_load_lds_dwordx4 v[220:221], off
	v_lshl_add_u64 v[224:225], s[42:43], 0, v[130:131]
	s_mov_b32 m0, s67
	v_lshl_add_u64 v[226:227], s[68:69], 0, v[132:133]
	global_load_lds_dwordx4 v[224:225], off
	v_lshl_add_u64 v[224:225], s[42:43], 0, v[134:135]
	s_add_i32 m0, s67, 0x2000
	v_lshl_add_u64 v[228:229], v[226:227], 0, s[14:15]
	global_load_lds_dwordx4 v[224:225], off
	s_mov_b32 m0, s48
	v_lshl_add_u64 v[224:225], s[68:69], 0, v[128:129]
	global_load_lds_dwordx4 v[224:225], off
	s_mov_b32 m0, s49
	s_nop 0
	global_load_lds_dwordx4 v[228:229], off
	s_waitcnt vmcnt(8) lgkmcnt(0)
	s_setprio 1
	s_barrier
	v_mfma_f32_16x16x32_bf16 v[60:63], v[144:147], v[184:187], 0
	v_mfma_f32_16x16x32_bf16 v[56:59], v[160:163], v[184:187], 0
	v_mfma_f32_16x16x32_bf16 v[44:47], v[144:147], v[192:195], 0
	v_mfma_f32_16x16x32_bf16 v[40:43], v[160:163], v[192:195], 0
	v_mfma_f32_16x16x32_bf16 v[28:31], v[144:147], v[200:203], 0
	v_mfma_f32_16x16x32_bf16 v[24:27], v[160:163], v[200:203], 0
	v_mfma_f32_16x16x32_bf16 v[12:15], v[144:147], v[208:211], 0
	v_mfma_f32_16x16x32_bf16 v[8:11], v[160:163], v[208:211], 0
	v_mfma_f32_16x16x32_bf16 v[60:63], v[156:159], v[188:191], v[60:63]
	v_mfma_f32_16x16x32_bf16 v[56:59], v[164:167], v[188:191], v[56:59]
	v_mfma_f32_16x16x32_bf16 v[44:47], v[156:159], v[196:199], v[44:47]
	v_mfma_f32_16x16x32_bf16 v[40:43], v[164:167], v[196:199], v[40:43]
	v_mfma_f32_16x16x32_bf16 v[28:31], v[156:159], v[204:207], v[28:31]
	v_mfma_f32_16x16x32_bf16 v[24:27], v[164:167], v[204:207], v[24:27]
	v_mfma_f32_16x16x32_bf16 v[12:15], v[156:159], v[212:215], v[12:15]
	v_mfma_f32_16x16x32_bf16 v[8:11], v[164:167], v[212:215], v[8:11]
	v_mfma_f32_16x16x32_bf16 v[52:55], v[168:171], v[184:187], 0
	v_mfma_f32_16x16x32_bf16 v[48:51], v[176:179], v[184:187], 0
	v_mfma_f32_16x16x32_bf16 v[36:39], v[168:171], v[192:195], 0
	v_mfma_f32_16x16x32_bf16 v[32:35], v[176:179], v[192:195], 0
	v_mfma_f32_16x16x32_bf16 v[20:23], v[168:171], v[200:203], 0
	v_mfma_f32_16x16x32_bf16 v[16:19], v[176:179], v[200:203], 0
	v_mfma_f32_16x16x32_bf16 v[4:7], v[168:171], v[208:211], 0
	v_mfma_f32_16x16x32_bf16 v[0:3], v[176:179], v[208:211], 0
	v_mfma_f32_16x16x32_bf16 v[52:55], v[172:175], v[188:191], v[52:55]
	v_mfma_f32_16x16x32_bf16 v[48:51], v[180:183], v[188:191], v[48:51]
	v_mfma_f32_16x16x32_bf16 v[36:39], v[172:175], v[196:199], v[36:39]
	v_mfma_f32_16x16x32_bf16 v[32:35], v[180:183], v[196:199], v[32:35]
	v_mfma_f32_16x16x32_bf16 v[20:23], v[172:175], v[204:207], v[20:23]
	v_mfma_f32_16x16x32_bf16 v[16:19], v[180:183], v[204:207], v[16:19]
	v_mfma_f32_16x16x32_bf16 v[4:7], v[172:175], v[212:215], v[4:7]
	v_mfma_f32_16x16x32_bf16 v[0:3], v[180:183], v[212:215], v[0:3]
	s_barrier
	s_setprio 0
	s_add_i32 s42, 0, 0x18000
	v_add_u32_e32 v155, s42, v149
	s_add_i32 s67, 0, 0x1c000
	ds_read_b128 v[144:147], v155
	ds_read_b128 v[156:159], v155 offset:1024
	ds_read_b128 v[160:163], v155 offset:2048
	ds_read_b128 v[164:167], v155 offset:3072
	v_add_u32_e32 v155, s67, v149
	ds_read_b128 v[168:171], v155
	ds_read_b128 v[172:175], v155 offset:1024
	ds_read_b128 v[176:179], v155 offset:2048
	ds_read_b128 v[180:183], v155 offset:3072
	s_mov_b32 m0, s50
	v_lshl_add_u64 v[228:229], v[224:225], 0, s[12:13]
	ds_read_b128 v[184:187], v153 offset:32768
	ds_read_b128 v[188:191], v153 offset:33792
	ds_read_b128 v[192:195], v153 offset:34816
	ds_read_b128 v[196:199], v153 offset:35840
	ds_read_b128 v[200:203], v153 offset:36864
	ds_read_b128 v[204:207], v153 offset:37888
	ds_read_b128 v[208:211], v153 offset:38912
	ds_read_b128 v[212:215], v153 offset:39936
	global_load_lds_dwordx4 v[228:229], off
	s_mov_b32 m0, s51
	v_lshl_add_u64 v[228:229], v[226:227], 0, s[16:17]
	global_load_lds_dwordx4 v[228:229], off
	s_waitcnt vmcnt(8) lgkmcnt(0)
	s_setprio 1
	s_barrier
	v_mfma_f32_16x16x32_bf16 v[124:127], v[144:147], v[184:187], v[124:127]
	v_mfma_f32_16x16x32_bf16 v[120:123], v[160:163], v[184:187], v[120:123]
	v_mfma_f32_16x16x32_bf16 v[108:111], v[144:147], v[192:195], v[108:111]
	v_mfma_f32_16x16x32_bf16 v[104:107], v[160:163], v[192:195], v[104:107]
	v_mfma_f32_16x16x32_bf16 v[92:95], v[144:147], v[200:203], v[92:95]
	v_mfma_f32_16x16x32_bf16 v[88:91], v[160:163], v[200:203], v[88:91]
	v_mfma_f32_16x16x32_bf16 v[76:79], v[144:147], v[208:211], v[76:79]
	v_mfma_f32_16x16x32_bf16 v[72:75], v[160:163], v[208:211], v[72:75]
	v_mfma_f32_16x16x32_bf16 v[124:127], v[156:159], v[188:191], v[124:127]
	v_mfma_f32_16x16x32_bf16 v[120:123], v[164:167], v[188:191], v[120:123]
	v_mfma_f32_16x16x32_bf16 v[108:111], v[156:159], v[196:199], v[108:111]
	v_mfma_f32_16x16x32_bf16 v[104:107], v[164:167], v[196:199], v[104:107]
	v_mfma_f32_16x16x32_bf16 v[92:95], v[156:159], v[204:207], v[92:95]
	v_mfma_f32_16x16x32_bf16 v[88:91], v[164:167], v[204:207], v[88:91]
	v_mfma_f32_16x16x32_bf16 v[76:79], v[156:159], v[212:215], v[76:79]
	v_mfma_f32_16x16x32_bf16 v[72:75], v[164:167], v[212:215], v[72:75]
	v_mfma_f32_16x16x32_bf16 v[116:119], v[168:171], v[184:187], v[116:119]
	v_mfma_f32_16x16x32_bf16 v[112:115], v[176:179], v[184:187], v[112:115]
	v_mfma_f32_16x16x32_bf16 v[100:103], v[168:171], v[192:195], v[100:103]
	v_mfma_f32_16x16x32_bf16 v[96:99], v[176:179], v[192:195], v[96:99]
	v_mfma_f32_16x16x32_bf16 v[84:87], v[168:171], v[200:203], v[84:87]
	v_mfma_f32_16x16x32_bf16 v[80:83], v[176:179], v[200:203], v[80:83]
	v_mfma_f32_16x16x32_bf16 v[68:71], v[168:171], v[208:211], v[68:71]
	v_mfma_f32_16x16x32_bf16 v[64:67], v[176:179], v[208:211], v[64:67]
	v_mfma_f32_16x16x32_bf16 v[116:119], v[172:175], v[188:191], v[116:119]
	v_mfma_f32_16x16x32_bf16 v[112:115], v[180:183], v[188:191], v[112:115]
	v_mfma_f32_16x16x32_bf16 v[100:103], v[172:175], v[196:199], v[100:103]
	v_mfma_f32_16x16x32_bf16 v[96:99], v[180:183], v[196:199], v[96:99]
	v_mfma_f32_16x16x32_bf16 v[84:87], v[172:175], v[204:207], v[84:87]
	v_mfma_f32_16x16x32_bf16 v[80:83], v[180:183], v[204:207], v[80:83]
	v_mfma_f32_16x16x32_bf16 v[68:71], v[172:175], v[212:215], v[68:71]
	v_mfma_f32_16x16x32_bf16 v[64:67], v[180:183], v[212:215], v[64:67]
	s_barrier
	s_setprio 0
	s_add_i32 s42, s42, s35
	v_lshl_add_u64 v[216:217], v[216:217], 0, s[24:25]
	s_mov_b32 m0, s42
	ds_read_b128 v[184:187], v153 offset:49152
	ds_read_b128 v[188:191], v153 offset:50176
	ds_read_b128 v[192:195], v153 offset:51200
	ds_read_b128 v[196:199], v153 offset:52224
	ds_read_b128 v[200:203], v153 offset:53248
	ds_read_b128 v[204:207], v153 offset:54272
	ds_read_b128 v[208:211], v153 offset:55296
	ds_read_b128 v[212:215], v153 offset:56320
	global_load_lds_dwordx4 v[216:217], off
	s_add_i32 m0, s42, 0x2000
	s_add_u32 s42, s46, 0xb0080
	v_lshl_add_u64 v[216:217], v[220:221], 0, s[24:25]
	s_addc_u32 s43, s47, 0
	s_add_i32 s46, s67, s35
	global_load_lds_dwordx4 v[216:217], off
	s_mov_b32 m0, s46
	v_lshl_add_u64 v[216:217], s[42:43], 0, v[130:131]
	global_load_lds_dwordx4 v[216:217], off
	s_add_i32 m0, s46, 0x2000
	v_lshl_add_u64 v[216:217], s[42:43], 0, v[134:135]
	global_load_lds_dwordx4 v[216:217], off
	s_mov_b32 m0, s53
	v_lshl_add_u64 v[216:217], v[224:225], 0, s[24:25]
	global_load_lds_dwordx4 v[216:217], off
	s_mov_b32 m0, s54
	v_lshl_add_u64 v[216:217], v[226:227], 0, s[36:37]
	global_load_lds_dwordx4 v[216:217], off
	s_waitcnt vmcnt(8) lgkmcnt(0)
	s_setprio 1
	s_barrier
	v_mfma_f32_16x16x32_bf16 v[60:63], v[144:147], v[184:187], v[60:63]
	v_mfma_f32_16x16x32_bf16 v[56:59], v[160:163], v[184:187], v[56:59]
	v_mfma_f32_16x16x32_bf16 v[44:47], v[144:147], v[192:195], v[44:47]
	v_mfma_f32_16x16x32_bf16 v[40:43], v[160:163], v[192:195], v[40:43]
	v_mfma_f32_16x16x32_bf16 v[28:31], v[144:147], v[200:203], v[28:31]
	v_mfma_f32_16x16x32_bf16 v[24:27], v[160:163], v[200:203], v[24:27]
	v_mfma_f32_16x16x32_bf16 v[12:15], v[144:147], v[208:211], v[12:15]
	v_mfma_f32_16x16x32_bf16 v[8:11], v[160:163], v[208:211], v[8:11]
	v_mfma_f32_16x16x32_bf16 v[60:63], v[156:159], v[188:191], v[60:63]
	v_mfma_f32_16x16x32_bf16 v[56:59], v[164:167], v[188:191], v[56:59]
	v_mfma_f32_16x16x32_bf16 v[44:47], v[156:159], v[196:199], v[44:47]
	v_mfma_f32_16x16x32_bf16 v[40:43], v[164:167], v[196:199], v[40:43]
	v_mfma_f32_16x16x32_bf16 v[28:31], v[156:159], v[204:207], v[28:31]
	v_mfma_f32_16x16x32_bf16 v[24:27], v[164:167], v[204:207], v[24:27]
	v_mfma_f32_16x16x32_bf16 v[12:15], v[156:159], v[212:215], v[12:15]
	v_mfma_f32_16x16x32_bf16 v[8:11], v[164:167], v[212:215], v[8:11]
	v_mfma_f32_16x16x32_bf16 v[52:55], v[168:171], v[184:187], v[52:55]
	v_mfma_f32_16x16x32_bf16 v[48:51], v[176:179], v[184:187], v[48:51]
	v_mfma_f32_16x16x32_bf16 v[36:39], v[168:171], v[192:195], v[36:39]
	v_mfma_f32_16x16x32_bf16 v[32:35], v[176:179], v[192:195], v[32:35]
	v_mfma_f32_16x16x32_bf16 v[20:23], v[168:171], v[200:203], v[20:23]
	v_mfma_f32_16x16x32_bf16 v[16:19], v[176:179], v[200:203], v[16:19]
	v_mfma_f32_16x16x32_bf16 v[4:7], v[168:171], v[208:211], v[4:7]
	v_mfma_f32_16x16x32_bf16 v[0:3], v[176:179], v[208:211], v[0:3]
	v_mfma_f32_16x16x32_bf16 v[52:55], v[172:175], v[188:191], v[52:55]
	v_mfma_f32_16x16x32_bf16 v[48:51], v[180:183], v[188:191], v[48:51]
	v_mfma_f32_16x16x32_bf16 v[36:39], v[172:175], v[196:199], v[36:39]
	v_mfma_f32_16x16x32_bf16 v[32:35], v[180:183], v[196:199], v[32:35]
	v_mfma_f32_16x16x32_bf16 v[20:23], v[172:175], v[204:207], v[20:23]
	v_mfma_f32_16x16x32_bf16 v[16:19], v[180:183], v[204:207], v[16:19]
	v_mfma_f32_16x16x32_bf16 v[4:7], v[172:175], v[212:215], v[4:7]
	v_mfma_f32_16x16x32_bf16 v[0:3], v[180:183], v[212:215], v[0:3]
	s_barrier
	s_setprio 0
	s_add_i32 s66, s66, 2
	s_add_u32 s64, s64, 0x100
	s_addc_u32 s65, s65, 0
	s_cmp_gt_u32 s66, 41
	s_mov_b64 s[42:43], s[44:45]
.LBB0_662:
	ds_read_b128 v[144:147], v151
	ds_read_b128 v[156:159], v151 offset:1024
	ds_read_b128 v[160:163], v151 offset:2048
	ds_read_b128 v[164:167], v151 offset:3072
	ds_read_b128 v[168:171], v152
	ds_read_b128 v[172:175], v152 offset:1024
	ds_read_b128 v[176:179], v152 offset:2048
	ds_read_b128 v[180:183], v152 offset:3072
	ds_read_b128 v[184:187], v153
	ds_read_b128 v[188:191], v153 offset:1024
	ds_read_b128 v[192:195], v153 offset:2048
	ds_read_b128 v[196:199], v153 offset:3072
	ds_read_b128 v[200:203], v153 offset:4096
	ds_read_b128 v[204:207], v153 offset:5120
	ds_read_b128 v[208:211], v153 offset:6144
	ds_read_b128 v[212:215], v153 offset:7168
	s_add_u32 s44, s42, 0x100
	s_addc_u32 s45, s43, 0
	s_cmp_eq_u32 s66, 40
	s_cselect_b32 s69, s1, s45
	s_cselect_b32 s68, s0, s44
	s_cselect_b32 s47, s41, s65
	s_cselect_b32 s46, s40, s64
	s_add_i32 m0, s48, 0xc000
	v_lshl_add_u64 v[216:217], s[42:43], 0, v[136:137]
	global_load_lds_dwordx4 v[216:217], off
	s_add_i32 m0, s48, 0xe000
	v_lshl_add_u64 v[216:217], s[42:43], 0, v[138:139]
	global_load_lds_dwordx4 v[216:217], off
	s_waitcnt vmcnt(8) lgkmcnt(0)
	s_setprio 1
	s_barrier
	v_mfma_f32_16x16x32_bf16 v[124:127], v[144:147], v[184:187], v[124:127]
	v_mfma_f32_16x16x32_bf16 v[120:123], v[160:163], v[184:187], v[120:123]
	v_mfma_f32_16x16x32_bf16 v[108:111], v[144:147], v[192:195], v[108:111]
	v_mfma_f32_16x16x32_bf16 v[104:107], v[160:163], v[192:195], v[104:107]
	v_mfma_f32_16x16x32_bf16 v[92:95], v[144:147], v[200:203], v[92:95]
	v_mfma_f32_16x16x32_bf16 v[88:91], v[160:163], v[200:203], v[88:91]
	v_mfma_f32_16x16x32_bf16 v[76:79], v[144:147], v[208:211], v[76:79]
	v_mfma_f32_16x16x32_bf16 v[72:75], v[160:163], v[208:211], v[72:75]
	v_mfma_f32_16x16x32_bf16 v[124:127], v[156:159], v[188:191], v[124:127]
	v_mfma_f32_16x16x32_bf16 v[120:123], v[164:167], v[188:191], v[120:123]
	v_mfma_f32_16x16x32_bf16 v[108:111], v[156:159], v[196:199], v[108:111]
	v_mfma_f32_16x16x32_bf16 v[104:107], v[164:167], v[196:199], v[104:107]
	v_mfma_f32_16x16x32_bf16 v[92:95], v[156:159], v[204:207], v[92:95]
	v_mfma_f32_16x16x32_bf16 v[88:91], v[164:167], v[204:207], v[88:91]
	v_mfma_f32_16x16x32_bf16 v[76:79], v[156:159], v[212:215], v[76:79]
	v_mfma_f32_16x16x32_bf16 v[72:75], v[164:167], v[212:215], v[72:75]
	v_mfma_f32_16x16x32_bf16 v[116:119], v[168:171], v[184:187], v[116:119]
	v_mfma_f32_16x16x32_bf16 v[112:115], v[176:179], v[184:187], v[112:115]
	v_mfma_f32_16x16x32_bf16 v[100:103], v[168:171], v[192:195], v[100:103]
	v_mfma_f32_16x16x32_bf16 v[96:99], v[176:179], v[192:195], v[96:99]
	v_mfma_f32_16x16x32_bf16 v[84:87], v[168:171], v[200:203], v[84:87]
	v_mfma_f32_16x16x32_bf16 v[80:83], v[176:179], v[200:203], v[80:83]
	v_mfma_f32_16x16x32_bf16 v[68:71], v[168:171], v[208:211], v[68:71]
	v_mfma_f32_16x16x32_bf16 v[64:67], v[176:179], v[208:211], v[64:67]
	v_mfma_f32_16x16x32_bf16 v[116:119], v[172:175], v[188:191], v[116:119]
	v_mfma_f32_16x16x32_bf16 v[112:115], v[180:183], v[188:191], v[112:115]
	v_mfma_f32_16x16x32_bf16 v[100:103], v[172:175], v[196:199], v[100:103]
	v_mfma_f32_16x16x32_bf16 v[96:99], v[180:183], v[196:199], v[96:99]
	v_mfma_f32_16x16x32_bf16 v[84:87], v[172:175], v[204:207], v[84:87]
	v_mfma_f32_16x16x32_bf16 v[80:83], v[180:183], v[204:207], v[80:83]
	v_mfma_f32_16x16x32_bf16 v[68:71], v[172:175], v[212:215], v[68:71]
	v_mfma_f32_16x16x32_bf16 v[64:67], v[180:183], v[212:215], v[64:67]
	s_barrier
	s_setprio 0
	s_add_i32 s42, s59, s35
	v_lshl_add_u64 v[216:217], s[46:47], 0, v[130:131]
	s_mov_b32 m0, s42
	ds_read_b128 v[184:187], v153 offset:16384
	ds_read_b128 v[188:191], v153 offset:17408
	ds_read_b128 v[192:195], v153 offset:18432
	ds_read_b128 v[196:199], v153 offset:19456
	ds_read_b128 v[200:203], v153 offset:20480
	ds_read_b128 v[204:207], v153 offset:21504
	ds_read_b128 v[208:211], v153 offset:22528
	ds_read_b128 v[212:215], v153 offset:23552
	global_load_lds_dwordx4 v[216:217], off
	s_add_i32 m0, s42, 0x2000
	s_add_u32 s42, s46, 0xb0000
	v_lshl_add_u64 v[220:221], s[46:47], 0, v[134:135]
	s_addc_u32 s43, s47, 0
	s_add_i32 s67, s60, s35
	global_load_lds_dwordx4 v[220:221], off
	v_lshl_add_u64 v[224:225], s[42:43], 0, v[130:131]
	s_mov_b32 m0, s67
	v_lshl_add_u64 v[226:227], s[68:69], 0, v[132:133]
	global_load_lds_dwordx4 v[224:225], off
	v_lshl_add_u64 v[224:225], s[42:43], 0, v[134:135]
	s_add_i32 m0, s67, 0x2000
	v_lshl_add_u64 v[228:229], v[226:227], 0, s[14:15]
	global_load_lds_dwordx4 v[224:225], off
	s_mov_b32 m0, s48
	v_lshl_add_u64 v[224:225], s[68:69], 0, v[128:129]
	global_load_lds_dwordx4 v[224:225], off
	s_mov_b32 m0, s49
	s_nop 0
	global_load_lds_dwordx4 v[228:229], off
	s_waitcnt vmcnt(8) lgkmcnt(0)
	s_setprio 1
	s_barrier
	v_mfma_f32_16x16x32_bf16 v[60:63], v[144:147], v[184:187], v[60:63]
	v_mfma_f32_16x16x32_bf16 v[56:59], v[160:163], v[184:187], v[56:59]
	v_mfma_f32_16x16x32_bf16 v[44:47], v[144:147], v[192:195], v[44:47]
	v_mfma_f32_16x16x32_bf16 v[40:43], v[160:163], v[192:195], v[40:43]
	v_mfma_f32_16x16x32_bf16 v[28:31], v[144:147], v[200:203], v[28:31]
	v_mfma_f32_16x16x32_bf16 v[24:27], v[160:163], v[200:203], v[24:27]
	v_mfma_f32_16x16x32_bf16 v[12:15], v[144:147], v[208:211], v[12:15]
	v_mfma_f32_16x16x32_bf16 v[8:11], v[160:163], v[208:211], v[8:11]
	v_mfma_f32_16x16x32_bf16 v[60:63], v[156:159], v[188:191], v[60:63]
	v_mfma_f32_16x16x32_bf16 v[56:59], v[164:167], v[188:191], v[56:59]
	v_mfma_f32_16x16x32_bf16 v[44:47], v[156:159], v[196:199], v[44:47]
	v_mfma_f32_16x16x32_bf16 v[40:43], v[164:167], v[196:199], v[40:43]
	v_mfma_f32_16x16x32_bf16 v[28:31], v[156:159], v[204:207], v[28:31]
	v_mfma_f32_16x16x32_bf16 v[24:27], v[164:167], v[204:207], v[24:27]
	v_mfma_f32_16x16x32_bf16 v[12:15], v[156:159], v[212:215], v[12:15]
	v_mfma_f32_16x16x32_bf16 v[8:11], v[164:167], v[212:215], v[8:11]
	v_mfma_f32_16x16x32_bf16 v[52:55], v[168:171], v[184:187], v[52:55]
	v_mfma_f32_16x16x32_bf16 v[48:51], v[176:179], v[184:187], v[48:51]
	v_mfma_f32_16x16x32_bf16 v[36:39], v[168:171], v[192:195], v[36:39]
	v_mfma_f32_16x16x32_bf16 v[32:35], v[176:179], v[192:195], v[32:35]
	v_mfma_f32_16x16x32_bf16 v[20:23], v[168:171], v[200:203], v[20:23]
	v_mfma_f32_16x16x32_bf16 v[16:19], v[176:179], v[200:203], v[16:19]
	v_mfma_f32_16x16x32_bf16 v[4:7], v[168:171], v[208:211], v[4:7]
	v_mfma_f32_16x16x32_bf16 v[0:3], v[176:179], v[208:211], v[0:3]
	v_mfma_f32_16x16x32_bf16 v[52:55], v[172:175], v[188:191], v[52:55]
	v_mfma_f32_16x16x32_bf16 v[48:51], v[180:183], v[188:191], v[48:51]
	v_mfma_f32_16x16x32_bf16 v[36:39], v[172:175], v[196:199], v[36:39]
	v_mfma_f32_16x16x32_bf16 v[32:35], v[180:183], v[196:199], v[32:35]
	v_mfma_f32_16x16x32_bf16 v[20:23], v[172:175], v[204:207], v[20:23]
	v_mfma_f32_16x16x32_bf16 v[16:19], v[180:183], v[204:207], v[16:19]
	v_mfma_f32_16x16x32_bf16 v[4:7], v[172:175], v[212:215], v[4:7]
	v_mfma_f32_16x16x32_bf16 v[0:3], v[180:183], v[212:215], v[0:3]
	s_barrier
	s_setprio 0
	s_add_i32 s42, 0, 0x18000
	v_add_u32_e32 v155, s42, v149
	s_add_i32 s67, 0, 0x1c000
	ds_read_b128 v[144:147], v155
	ds_read_b128 v[156:159], v155 offset:1024
	ds_read_b128 v[160:163], v155 offset:2048
	ds_read_b128 v[164:167], v155 offset:3072
	v_add_u32_e32 v155, s67, v149
	ds_read_b128 v[168:171], v155
	ds_read_b128 v[172:175], v155 offset:1024
	ds_read_b128 v[176:179], v155 offset:2048
	ds_read_b128 v[180:183], v155 offset:3072
	s_mov_b32 m0, s50
	v_lshl_add_u64 v[228:229], v[224:225], 0, s[12:13]
	ds_read_b128 v[184:187], v153 offset:32768
	ds_read_b128 v[188:191], v153 offset:33792
	ds_read_b128 v[192:195], v153 offset:34816
	ds_read_b128 v[196:199], v153 offset:35840
	ds_read_b128 v[200:203], v153 offset:36864
	ds_read_b128 v[204:207], v153 offset:37888
	ds_read_b128 v[208:211], v153 offset:38912
	ds_read_b128 v[212:215], v153 offset:39936
	global_load_lds_dwordx4 v[228:229], off
	s_mov_b32 m0, s51
	v_lshl_add_u64 v[228:229], v[226:227], 0, s[16:17]
	global_load_lds_dwordx4 v[228:229], off
	s_waitcnt vmcnt(8) lgkmcnt(0)
	s_setprio 1
	s_barrier
	v_mfma_f32_16x16x32_bf16 v[124:127], v[144:147], v[184:187], v[124:127]
	v_mfma_f32_16x16x32_bf16 v[120:123], v[160:163], v[184:187], v[120:123]
	v_mfma_f32_16x16x32_bf16 v[108:111], v[144:147], v[192:195], v[108:111]
	v_mfma_f32_16x16x32_bf16 v[104:107], v[160:163], v[192:195], v[104:107]
	v_mfma_f32_16x16x32_bf16 v[92:95], v[144:147], v[200:203], v[92:95]
	v_mfma_f32_16x16x32_bf16 v[88:91], v[160:163], v[200:203], v[88:91]
	v_mfma_f32_16x16x32_bf16 v[76:79], v[144:147], v[208:211], v[76:79]
	v_mfma_f32_16x16x32_bf16 v[72:75], v[160:163], v[208:211], v[72:75]
	v_mfma_f32_16x16x32_bf16 v[124:127], v[156:159], v[188:191], v[124:127]
	v_mfma_f32_16x16x32_bf16 v[120:123], v[164:167], v[188:191], v[120:123]
	v_mfma_f32_16x16x32_bf16 v[108:111], v[156:159], v[196:199], v[108:111]
	v_mfma_f32_16x16x32_bf16 v[104:107], v[164:167], v[196:199], v[104:107]
	v_mfma_f32_16x16x32_bf16 v[92:95], v[156:159], v[204:207], v[92:95]
	v_mfma_f32_16x16x32_bf16 v[88:91], v[164:167], v[204:207], v[88:91]
	v_mfma_f32_16x16x32_bf16 v[76:79], v[156:159], v[212:215], v[76:79]
	v_mfma_f32_16x16x32_bf16 v[72:75], v[164:167], v[212:215], v[72:75]
	v_mfma_f32_16x16x32_bf16 v[116:119], v[168:171], v[184:187], v[116:119]
	v_mfma_f32_16x16x32_bf16 v[112:115], v[176:179], v[184:187], v[112:115]
	v_mfma_f32_16x16x32_bf16 v[100:103], v[168:171], v[192:195], v[100:103]
	v_mfma_f32_16x16x32_bf16 v[96:99], v[176:179], v[192:195], v[96:99]
	v_mfma_f32_16x16x32_bf16 v[84:87], v[168:171], v[200:203], v[84:87]
	v_mfma_f32_16x16x32_bf16 v[80:83], v[176:179], v[200:203], v[80:83]
	v_mfma_f32_16x16x32_bf16 v[68:71], v[168:171], v[208:211], v[68:71]
	v_mfma_f32_16x16x32_bf16 v[64:67], v[176:179], v[208:211], v[64:67]
	v_mfma_f32_16x16x32_bf16 v[116:119], v[172:175], v[188:191], v[116:119]
	v_mfma_f32_16x16x32_bf16 v[112:115], v[180:183], v[188:191], v[112:115]
	v_mfma_f32_16x16x32_bf16 v[100:103], v[172:175], v[196:199], v[100:103]
	v_mfma_f32_16x16x32_bf16 v[96:99], v[180:183], v[196:199], v[96:99]
	v_mfma_f32_16x16x32_bf16 v[84:87], v[172:175], v[204:207], v[84:87]
	v_mfma_f32_16x16x32_bf16 v[80:83], v[180:183], v[204:207], v[80:83]
	v_mfma_f32_16x16x32_bf16 v[68:71], v[172:175], v[212:215], v[68:71]
	v_mfma_f32_16x16x32_bf16 v[64:67], v[180:183], v[212:215], v[64:67]
	s_barrier
	s_setprio 0
	s_add_i32 s42, s42, s35
	v_lshl_add_u64 v[216:217], v[216:217], 0, s[24:25]
	s_mov_b32 m0, s42
	ds_read_b128 v[184:187], v153 offset:49152
	ds_read_b128 v[188:191], v153 offset:50176
	ds_read_b128 v[192:195], v153 offset:51200
	ds_read_b128 v[196:199], v153 offset:52224
	ds_read_b128 v[200:203], v153 offset:53248
	ds_read_b128 v[204:207], v153 offset:54272
	ds_read_b128 v[208:211], v153 offset:55296
	ds_read_b128 v[212:215], v153 offset:56320
	global_load_lds_dwordx4 v[216:217], off
	s_add_i32 m0, s42, 0x2000
	s_add_u32 s42, s46, 0xb0080
	v_lshl_add_u64 v[216:217], v[220:221], 0, s[24:25]
	s_addc_u32 s43, s47, 0
	s_add_i32 s46, s67, s35
	global_load_lds_dwordx4 v[216:217], off
	s_mov_b32 m0, s46
	v_lshl_add_u64 v[216:217], s[42:43], 0, v[130:131]
	global_load_lds_dwordx4 v[216:217], off
	s_add_i32 m0, s46, 0x2000
	v_lshl_add_u64 v[216:217], s[42:43], 0, v[134:135]
	global_load_lds_dwordx4 v[216:217], off
	s_mov_b32 m0, s53
	v_lshl_add_u64 v[216:217], v[224:225], 0, s[24:25]
	global_load_lds_dwordx4 v[216:217], off
	s_mov_b32 m0, s54
	v_lshl_add_u64 v[216:217], v[226:227], 0, s[36:37]
	global_load_lds_dwordx4 v[216:217], off
	s_waitcnt vmcnt(8) lgkmcnt(0)
	s_setprio 1
	s_barrier
	v_mfma_f32_16x16x32_bf16 v[60:63], v[144:147], v[184:187], v[60:63]
	v_mfma_f32_16x16x32_bf16 v[56:59], v[160:163], v[184:187], v[56:59]
	v_mfma_f32_16x16x32_bf16 v[44:47], v[144:147], v[192:195], v[44:47]
	v_mfma_f32_16x16x32_bf16 v[40:43], v[160:163], v[192:195], v[40:43]
	v_mfma_f32_16x16x32_bf16 v[28:31], v[144:147], v[200:203], v[28:31]
	v_mfma_f32_16x16x32_bf16 v[24:27], v[160:163], v[200:203], v[24:27]
	v_mfma_f32_16x16x32_bf16 v[12:15], v[144:147], v[208:211], v[12:15]
	v_mfma_f32_16x16x32_bf16 v[8:11], v[160:163], v[208:211], v[8:11]
	v_mfma_f32_16x16x32_bf16 v[60:63], v[156:159], v[188:191], v[60:63]
	v_mfma_f32_16x16x32_bf16 v[56:59], v[164:167], v[188:191], v[56:59]
	v_mfma_f32_16x16x32_bf16 v[44:47], v[156:159], v[196:199], v[44:47]
	v_mfma_f32_16x16x32_bf16 v[40:43], v[164:167], v[196:199], v[40:43]
	v_mfma_f32_16x16x32_bf16 v[28:31], v[156:159], v[204:207], v[28:31]
	v_mfma_f32_16x16x32_bf16 v[24:27], v[164:167], v[204:207], v[24:27]
	v_mfma_f32_16x16x32_bf16 v[12:15], v[156:159], v[212:215], v[12:15]
	v_mfma_f32_16x16x32_bf16 v[8:11], v[164:167], v[212:215], v[8:11]
	v_mfma_f32_16x16x32_bf16 v[52:55], v[168:171], v[184:187], v[52:55]
	v_mfma_f32_16x16x32_bf16 v[48:51], v[176:179], v[184:187], v[48:51]
	v_mfma_f32_16x16x32_bf16 v[36:39], v[168:171], v[192:195], v[36:39]
	v_mfma_f32_16x16x32_bf16 v[32:35], v[176:179], v[192:195], v[32:35]
	v_mfma_f32_16x16x32_bf16 v[20:23], v[168:171], v[200:203], v[20:23]
	v_mfma_f32_16x16x32_bf16 v[16:19], v[176:179], v[200:203], v[16:19]
	v_mfma_f32_16x16x32_bf16 v[4:7], v[168:171], v[208:211], v[4:7]
	v_mfma_f32_16x16x32_bf16 v[0:3], v[176:179], v[208:211], v[0:3]
	v_mfma_f32_16x16x32_bf16 v[52:55], v[172:175], v[188:191], v[52:55]
	v_mfma_f32_16x16x32_bf16 v[48:51], v[180:183], v[188:191], v[48:51]
	v_mfma_f32_16x16x32_bf16 v[36:39], v[172:175], v[196:199], v[36:39]
	v_mfma_f32_16x16x32_bf16 v[32:35], v[180:183], v[196:199], v[32:35]
	v_mfma_f32_16x16x32_bf16 v[20:23], v[172:175], v[204:207], v[20:23]
	v_mfma_f32_16x16x32_bf16 v[16:19], v[180:183], v[204:207], v[16:19]
	v_mfma_f32_16x16x32_bf16 v[4:7], v[172:175], v[212:215], v[4:7]
	v_mfma_f32_16x16x32_bf16 v[0:3], v[180:183], v[212:215], v[0:3]
	s_barrier
	s_setprio 0
	s_add_i32 s66, s66, 2
	s_add_u32 s64, s64, 0x100
	s_addc_u32 s65, s65, 0
	s_cmp_gt_u32 s66, 41
	s_mov_b64 s[42:43], s[44:45]
	s_cbranch_scc0 .LBB0_662

.LBB0_750:
	s_lshl_b32 s38, s65, 8
	s_ashr_i32 s39, s38, 31
	s_lshl_b64 s[38:39], s[38:39], 11
	s_add_u32 s38, s8, s38
	s_addc_u32 s39, s9, s39
	s_and_b64 s[40:41], s[4:5], exec
	s_cselect_b32 s43, s39, s45
	s_cselect_b32 s67, s38, s44
	s_ashr_i32 s37, s36, 31
	s_lshl_b64 s[40:41], s[36:37], 19
	s_add_u32 s40, s3, s40
	s_addc_u32 s41, s33, s41
	s_and_b64 s[48:49], s[4:5], exec
	s_cselect_b32 s37, s41, s47
	s_cselect_b32 s68, s40, s46
	s_add_u32 s69, s46, 0x100
	s_addc_u32 s71, s47, 0
	s_mov_b32 s72, -2
	s_waitcnt vmcnt(0)
	ds_read_b128 v[144:147], v189
	ds_read_b128 v[148:151], v189 offset:1024
	ds_read_b128 v[152:155], v189 offset:2048
	ds_read_b128 v[156:159], v189 offset:3072
	ds_read_b128 v[160:163], v190
	ds_read_b128 v[164:167], v190 offset:1024
	ds_read_b128 v[168:171], v190 offset:2048
	ds_read_b128 v[172:175], v190 offset:3072
	ds_read_b128 v[176:179], v191
	ds_read_b128 v[180:183], v191 offset:1024
	ds_read_b128 v[194:197], v191 offset:2048
	ds_read_b128 v[198:201], v191 offset:3072
	ds_read_b128 v[202:205], v191 offset:4096
	ds_read_b128 v[206:209], v191 offset:5120
	ds_read_b128 v[210:213], v191 offset:6144
	ds_read_b128 v[214:217], v191 offset:7168
	s_add_u32 s46, s44, 0x100
	s_addc_u32 s47, s45, 0
	s_cmp_eq_u32 s72, 12
	s_cselect_b32 s75, s43, s47
	s_cselect_b32 s74, s67, s46
	s_cselect_b32 s49, s37, s71
	s_cselect_b32 s48, s68, s69
	s_add_i32 m0, s51, 0xc000
	v_lshl_add_u64 v[184:185], s[44:45], 0, v[136:137]
	global_load_lds_dwordx4 v[184:185], off
	s_add_i32 m0, s51, 0xe000
	v_lshl_add_u64 v[184:185], s[44:45], 0, v[138:139]
	global_load_lds_dwordx4 v[184:185], off
	s_waitcnt vmcnt(8) lgkmcnt(0)
	s_setprio 1
	s_barrier
	v_mfma_f32_16x16x32_bf16 v[124:127], v[144:147], v[176:179], 0
	v_mfma_f32_16x16x32_bf16 v[120:123], v[152:155], v[176:179], 0
	v_mfma_f32_16x16x32_bf16 v[108:111], v[144:147], v[194:197], 0
	v_mfma_f32_16x16x32_bf16 v[104:107], v[152:155], v[194:197], 0
	v_mfma_f32_16x16x32_bf16 v[92:95], v[144:147], v[202:205], 0
	v_mfma_f32_16x16x32_bf16 v[88:91], v[152:155], v[202:205], 0
	v_mfma_f32_16x16x32_bf16 v[76:79], v[144:147], v[210:213], 0
	v_mfma_f32_16x16x32_bf16 v[72:75], v[152:155], v[210:213], 0
	v_mfma_f32_16x16x32_bf16 v[124:127], v[148:151], v[180:183], v[124:127]
	v_mfma_f32_16x16x32_bf16 v[120:123], v[156:159], v[180:183], v[120:123]
	v_mfma_f32_16x16x32_bf16 v[108:111], v[148:151], v[198:201], v[108:111]
	v_mfma_f32_16x16x32_bf16 v[104:107], v[156:159], v[198:201], v[104:107]
	v_mfma_f32_16x16x32_bf16 v[92:95], v[148:151], v[206:209], v[92:95]
	v_mfma_f32_16x16x32_bf16 v[88:91], v[156:159], v[206:209], v[88:91]
	v_mfma_f32_16x16x32_bf16 v[76:79], v[148:151], v[214:217], v[76:79]
	v_mfma_f32_16x16x32_bf16 v[72:75], v[156:159], v[214:217], v[72:75]
	v_mfma_f32_16x16x32_bf16 v[116:119], v[160:163], v[176:179], 0
	v_mfma_f32_16x16x32_bf16 v[112:115], v[168:171], v[176:179], 0
	v_mfma_f32_16x16x32_bf16 v[100:103], v[160:163], v[194:197], 0
	v_mfma_f32_16x16x32_bf16 v[96:99], v[168:171], v[194:197], 0
	v_mfma_f32_16x16x32_bf16 v[84:87], v[160:163], v[202:205], 0
	v_mfma_f32_16x16x32_bf16 v[80:83], v[168:171], v[202:205], 0
	v_mfma_f32_16x16x32_bf16 v[68:71], v[160:163], v[210:213], 0
	v_mfma_f32_16x16x32_bf16 v[64:67], v[168:171], v[210:213], 0
	v_mfma_f32_16x16x32_bf16 v[116:119], v[164:167], v[180:183], v[116:119]
	v_mfma_f32_16x16x32_bf16 v[112:115], v[172:175], v[180:183], v[112:115]
	v_mfma_f32_16x16x32_bf16 v[100:103], v[164:167], v[198:201], v[100:103]
	v_mfma_f32_16x16x32_bf16 v[96:99], v[172:175], v[198:201], v[96:99]
	v_mfma_f32_16x16x32_bf16 v[84:87], v[164:167], v[206:209], v[84:87]
	v_mfma_f32_16x16x32_bf16 v[80:83], v[172:175], v[206:209], v[80:83]
	v_mfma_f32_16x16x32_bf16 v[68:71], v[164:167], v[214:217], v[68:71]
	v_mfma_f32_16x16x32_bf16 v[64:67], v[172:175], v[214:217], v[64:67]
	s_barrier
	s_setprio 0
	s_add_i32 s44, s63, s50
	v_lshl_add_u64 v[184:185], s[48:49], 0, v[130:131]
	s_mov_b32 m0, s44
	ds_read_b128 v[176:179], v191 offset:16384
	ds_read_b128 v[180:183], v191 offset:17408
	ds_read_b128 v[194:197], v191 offset:18432
	ds_read_b128 v[198:201], v191 offset:19456
	ds_read_b128 v[202:205], v191 offset:20480
	ds_read_b128 v[206:209], v191 offset:21504
	ds_read_b128 v[210:213], v191 offset:22528
	ds_read_b128 v[214:217], v191 offset:23552
	global_load_lds_dwordx4 v[184:185], off
	s_add_i32 m0, s44, 0x2000
	s_add_u32 s44, s48, 0x40000
	v_lshl_add_u64 v[218:219], s[48:49], 0, v[134:135]
	s_addc_u32 s45, s49, 0
	s_add_i32 s70, s64, s50
	global_load_lds_dwordx4 v[218:219], off
	v_lshl_add_u64 v[220:221], s[44:45], 0, v[130:131]
	s_mov_b32 m0, s70
	v_lshl_add_u64 v[222:223], s[74:75], 0, v[132:133]
	global_load_lds_dwordx4 v[220:221], off
	v_lshl_add_u64 v[220:221], s[44:45], 0, v[134:135]
	s_add_i32 m0, s70, 0x2000
	v_lshl_add_u64 v[224:225], v[222:223], 0, s[12:13]
	global_load_lds_dwordx4 v[220:221], off
	s_mov_b32 m0, s51
	v_lshl_add_u64 v[220:221], s[74:75], 0, v[128:129]
	global_load_lds_dwordx4 v[220:221], off
	s_mov_b32 m0, s52
	s_nop 0
	global_load_lds_dwordx4 v[224:225], off
	s_waitcnt vmcnt(8) lgkmcnt(0)
	s_setprio 1
	s_barrier
	v_mfma_f32_16x16x32_bf16 v[60:63], v[144:147], v[176:179], 0
	v_mfma_f32_16x16x32_bf16 v[56:59], v[152:155], v[176:179], 0
	v_mfma_f32_16x16x32_bf16 v[44:47], v[144:147], v[194:197], 0
	v_mfma_f32_16x16x32_bf16 v[40:43], v[152:155], v[194:197], 0
	v_mfma_f32_16x16x32_bf16 v[28:31], v[144:147], v[202:205], 0
	v_mfma_f32_16x16x32_bf16 v[24:27], v[152:155], v[202:205], 0
	v_mfma_f32_16x16x32_bf16 v[12:15], v[144:147], v[210:213], 0
	v_mfma_f32_16x16x32_bf16 v[8:11], v[152:155], v[210:213], 0
	v_mfma_f32_16x16x32_bf16 v[60:63], v[148:151], v[180:183], v[60:63]
	v_mfma_f32_16x16x32_bf16 v[56:59], v[156:159], v[180:183], v[56:59]
	v_mfma_f32_16x16x32_bf16 v[44:47], v[148:151], v[198:201], v[44:47]
	v_mfma_f32_16x16x32_bf16 v[40:43], v[156:159], v[198:201], v[40:43]
	v_mfma_f32_16x16x32_bf16 v[28:31], v[148:151], v[206:209], v[28:31]
	v_mfma_f32_16x16x32_bf16 v[24:27], v[156:159], v[206:209], v[24:27]
	v_mfma_f32_16x16x32_bf16 v[12:15], v[148:151], v[214:217], v[12:15]
	v_mfma_f32_16x16x32_bf16 v[8:11], v[156:159], v[214:217], v[8:11]
	v_mfma_f32_16x16x32_bf16 v[52:55], v[160:163], v[176:179], 0
	v_mfma_f32_16x16x32_bf16 v[48:51], v[168:171], v[176:179], 0
	v_mfma_f32_16x16x32_bf16 v[36:39], v[160:163], v[194:197], 0
	v_mfma_f32_16x16x32_bf16 v[32:35], v[168:171], v[194:197], 0
	v_mfma_f32_16x16x32_bf16 v[20:23], v[160:163], v[202:205], 0
	v_mfma_f32_16x16x32_bf16 v[16:19], v[168:171], v[202:205], 0
	v_mfma_f32_16x16x32_bf16 v[4:7], v[160:163], v[210:213], 0
	v_mfma_f32_16x16x32_bf16 v[0:3], v[168:171], v[210:213], 0
	v_mfma_f32_16x16x32_bf16 v[52:55], v[164:167], v[180:183], v[52:55]
	v_mfma_f32_16x16x32_bf16 v[48:51], v[172:175], v[180:183], v[48:51]
	v_mfma_f32_16x16x32_bf16 v[36:39], v[164:167], v[198:201], v[36:39]
	v_mfma_f32_16x16x32_bf16 v[32:35], v[172:175], v[198:201], v[32:35]
	v_mfma_f32_16x16x32_bf16 v[20:23], v[164:167], v[206:209], v[20:23]
	v_mfma_f32_16x16x32_bf16 v[16:19], v[172:175], v[206:209], v[16:19]
	v_mfma_f32_16x16x32_bf16 v[4:7], v[164:167], v[214:217], v[4:7]
	v_mfma_f32_16x16x32_bf16 v[0:3], v[172:175], v[214:217], v[0:3]
	s_barrier
	s_setprio 0
	s_add_i32 s44, 0, 0x18000
	s_add_i32 s70, 0, 0x1c000
	v_add_u32_e32 v156, s44, v187
	v_add_u32_e32 v172, s70, v187
	ds_read_b128 v[144:147], v156
	ds_read_b128 v[148:151], v156 offset:1024
	ds_read_b128 v[152:155], v156 offset:2048
	ds_read_b128 v[156:159], v156 offset:3072
	ds_read_b128 v[160:163], v172
	ds_read_b128 v[164:167], v172 offset:1024
	ds_read_b128 v[168:171], v172 offset:2048
	ds_read_b128 v[172:175], v172 offset:3072
	s_mov_b32 m0, s53
	v_lshl_add_u64 v[224:225], v[220:221], 0, s[10:11]
	ds_read_b128 v[176:179], v191 offset:32768
	ds_read_b128 v[180:183], v191 offset:33792
	ds_read_b128 v[194:197], v191 offset:34816
	ds_read_b128 v[198:201], v191 offset:35840
	ds_read_b128 v[202:205], v191 offset:36864
	ds_read_b128 v[206:209], v191 offset:37888
	ds_read_b128 v[210:213], v191 offset:38912
	ds_read_b128 v[214:217], v191 offset:39936
	global_load_lds_dwordx4 v[224:225], off
	s_mov_b32 m0, s54
	v_lshl_add_u64 v[224:225], v[222:223], 0, s[14:15]
	global_load_lds_dwordx4 v[224:225], off
	s_waitcnt vmcnt(8) lgkmcnt(0)
	s_setprio 1
	s_barrier
	v_mfma_f32_16x16x32_bf16 v[124:127], v[144:147], v[176:179], v[124:127]
	v_mfma_f32_16x16x32_bf16 v[120:123], v[152:155], v[176:179], v[120:123]
	v_mfma_f32_16x16x32_bf16 v[108:111], v[144:147], v[194:197], v[108:111]
	v_mfma_f32_16x16x32_bf16 v[104:107], v[152:155], v[194:197], v[104:107]
	v_mfma_f32_16x16x32_bf16 v[92:95], v[144:147], v[202:205], v[92:95]
	v_mfma_f32_16x16x32_bf16 v[88:91], v[152:155], v[202:205], v[88:91]
	v_mfma_f32_16x16x32_bf16 v[76:79], v[144:147], v[210:213], v[76:79]
	v_mfma_f32_16x16x32_bf16 v[72:75], v[152:155], v[210:213], v[72:75]
	v_mfma_f32_16x16x32_bf16 v[124:127], v[148:151], v[180:183], v[124:127]
	v_mfma_f32_16x16x32_bf16 v[120:123], v[156:159], v[180:183], v[120:123]
	v_mfma_f32_16x16x32_bf16 v[108:111], v[148:151], v[198:201], v[108:111]
	v_mfma_f32_16x16x32_bf16 v[104:107], v[156:159], v[198:201], v[104:107]
	v_mfma_f32_16x16x32_bf16 v[92:95], v[148:151], v[206:209], v[92:95]
	v_mfma_f32_16x16x32_bf16 v[88:91], v[156:159], v[206:209], v[88:91]
	v_mfma_f32_16x16x32_bf16 v[76:79], v[148:151], v[214:217], v[76:79]
	v_mfma_f32_16x16x32_bf16 v[72:75], v[156:159], v[214:217], v[72:75]
	v_mfma_f32_16x16x32_bf16 v[116:119], v[160:163], v[176:179], v[116:119]
	v_mfma_f32_16x16x32_bf16 v[112:115], v[168:171], v[176:179], v[112:115]
	v_mfma_f32_16x16x32_bf16 v[100:103], v[160:163], v[194:197], v[100:103]
	v_mfma_f32_16x16x32_bf16 v[96:99], v[168:171], v[194:197], v[96:99]
	v_mfma_f32_16x16x32_bf16 v[84:87], v[160:163], v[202:205], v[84:87]
	v_mfma_f32_16x16x32_bf16 v[80:83], v[168:171], v[202:205], v[80:83]
	v_mfma_f32_16x16x32_bf16 v[68:71], v[160:163], v[210:213], v[68:71]
	v_mfma_f32_16x16x32_bf16 v[64:67], v[168:171], v[210:213], v[64:67]
	v_mfma_f32_16x16x32_bf16 v[116:119], v[164:167], v[180:183], v[116:119]
	v_mfma_f32_16x16x32_bf16 v[112:115], v[172:175], v[180:183], v[112:115]
	v_mfma_f32_16x16x32_bf16 v[100:103], v[164:167], v[198:201], v[100:103]
	v_mfma_f32_16x16x32_bf16 v[96:99], v[172:175], v[198:201], v[96:99]
	v_mfma_f32_16x16x32_bf16 v[84:87], v[164:167], v[206:209], v[84:87]
	v_mfma_f32_16x16x32_bf16 v[80:83], v[172:175], v[206:209], v[80:83]
	v_mfma_f32_16x16x32_bf16 v[68:71], v[164:167], v[214:217], v[68:71]
	v_mfma_f32_16x16x32_bf16 v[64:67], v[172:175], v[214:217], v[64:67]
	s_barrier
	s_setprio 0
	s_add_i32 s44, s44, s50
	v_lshl_add_u64 v[184:185], v[184:185], 0, s[24:25]
	s_mov_b32 m0, s44
	ds_read_b128 v[176:179], v191 offset:49152
	ds_read_b128 v[180:183], v191 offset:50176
	ds_read_b128 v[194:197], v191 offset:51200
	ds_read_b128 v[198:201], v191 offset:52224
	ds_read_b128 v[202:205], v191 offset:53248
	ds_read_b128 v[206:209], v191 offset:54272
	ds_read_b128 v[210:213], v191 offset:55296
	ds_read_b128 v[214:217], v191 offset:56320
	global_load_lds_dwordx4 v[184:185], off
	s_add_i32 m0, s44, 0x2000
	s_add_u32 s44, s48, 0x40080
	v_lshl_add_u64 v[184:185], v[218:219], 0, s[24:25]
	s_addc_u32 s45, s49, 0
	s_add_i32 s48, s70, s50
	global_load_lds_dwordx4 v[184:185], off
	s_mov_b32 m0, s48
	v_lshl_add_u64 v[184:185], s[44:45], 0, v[130:131]
	global_load_lds_dwordx4 v[184:185], off
	s_add_i32 m0, s48, 0x2000
	v_lshl_add_u64 v[184:185], s[44:45], 0, v[134:135]
	global_load_lds_dwordx4 v[184:185], off
	s_mov_b32 m0, s58
	v_lshl_add_u64 v[184:185], v[220:221], 0, s[24:25]
	global_load_lds_dwordx4 v[184:185], off
	s_mov_b32 m0, s59
	v_lshl_add_u64 v[184:185], v[222:223], 0, s[30:31]
	global_load_lds_dwordx4 v[184:185], off
	s_waitcnt vmcnt(8) lgkmcnt(0)
	s_setprio 1
	s_barrier
	v_mfma_f32_16x16x32_bf16 v[60:63], v[144:147], v[176:179], v[60:63]
	v_mfma_f32_16x16x32_bf16 v[56:59], v[152:155], v[176:179], v[56:59]
	v_mfma_f32_16x16x32_bf16 v[44:47], v[144:147], v[194:197], v[44:47]
	v_mfma_f32_16x16x32_bf16 v[40:43], v[152:155], v[194:197], v[40:43]
	v_mfma_f32_16x16x32_bf16 v[28:31], v[144:147], v[202:205], v[28:31]
	v_mfma_f32_16x16x32_bf16 v[24:27], v[152:155], v[202:205], v[24:27]
	v_mfma_f32_16x16x32_bf16 v[12:15], v[144:147], v[210:213], v[12:15]
	v_mfma_f32_16x16x32_bf16 v[8:11], v[152:155], v[210:213], v[8:11]
	v_mfma_f32_16x16x32_bf16 v[60:63], v[148:151], v[180:183], v[60:63]
	v_mfma_f32_16x16x32_bf16 v[56:59], v[156:159], v[180:183], v[56:59]
	v_mfma_f32_16x16x32_bf16 v[44:47], v[148:151], v[198:201], v[44:47]
	v_mfma_f32_16x16x32_bf16 v[40:43], v[156:159], v[198:201], v[40:43]
	v_mfma_f32_16x16x32_bf16 v[28:31], v[148:151], v[206:209], v[28:31]
	v_mfma_f32_16x16x32_bf16 v[24:27], v[156:159], v[206:209], v[24:27]
	v_mfma_f32_16x16x32_bf16 v[12:15], v[148:151], v[214:217], v[12:15]
	v_mfma_f32_16x16x32_bf16 v[8:11], v[156:159], v[214:217], v[8:11]
	v_mfma_f32_16x16x32_bf16 v[52:55], v[160:163], v[176:179], v[52:55]
	v_mfma_f32_16x16x32_bf16 v[48:51], v[168:171], v[176:179], v[48:51]
	v_mfma_f32_16x16x32_bf16 v[36:39], v[160:163], v[194:197], v[36:39]
	v_mfma_f32_16x16x32_bf16 v[32:35], v[168:171], v[194:197], v[32:35]
	v_mfma_f32_16x16x32_bf16 v[20:23], v[160:163], v[202:205], v[20:23]
	v_mfma_f32_16x16x32_bf16 v[16:19], v[168:171], v[202:205], v[16:19]
	v_mfma_f32_16x16x32_bf16 v[4:7], v[160:163], v[210:213], v[4:7]
	v_mfma_f32_16x16x32_bf16 v[0:3], v[168:171], v[210:213], v[0:3]
	v_mfma_f32_16x16x32_bf16 v[52:55], v[164:167], v[180:183], v[52:55]
	v_mfma_f32_16x16x32_bf16 v[48:51], v[172:175], v[180:183], v[48:51]
	v_mfma_f32_16x16x32_bf16 v[36:39], v[164:167], v[198:201], v[36:39]
	v_mfma_f32_16x16x32_bf16 v[32:35], v[172:175], v[198:201], v[32:35]
	v_mfma_f32_16x16x32_bf16 v[20:23], v[164:167], v[206:209], v[20:23]
	v_mfma_f32_16x16x32_bf16 v[16:19], v[172:175], v[206:209], v[16:19]
	v_mfma_f32_16x16x32_bf16 v[4:7], v[164:167], v[214:217], v[4:7]
	v_mfma_f32_16x16x32_bf16 v[0:3], v[172:175], v[214:217], v[0:3]
	s_barrier
	s_setprio 0
	s_add_i32 s72, s72, 2
	s_add_u32 s69, s69, 0x100
	s_addc_u32 s71, s71, 0
	s_cmp_gt_u32 s72, 13
	s_mov_b64 s[44:45], s[46:47]
.LBB0_751:
	ds_read_b128 v[144:147], v189
	ds_read_b128 v[148:151], v189 offset:1024
	ds_read_b128 v[152:155], v189 offset:2048
	ds_read_b128 v[156:159], v189 offset:3072
	ds_read_b128 v[160:163], v190
	ds_read_b128 v[164:167], v190 offset:1024
	ds_read_b128 v[168:171], v190 offset:2048
	ds_read_b128 v[172:175], v190 offset:3072
	ds_read_b128 v[176:179], v191
	ds_read_b128 v[180:183], v191 offset:1024
	ds_read_b128 v[194:197], v191 offset:2048
	ds_read_b128 v[198:201], v191 offset:3072
	ds_read_b128 v[202:205], v191 offset:4096
	ds_read_b128 v[206:209], v191 offset:5120
	ds_read_b128 v[210:213], v191 offset:6144
	ds_read_b128 v[214:217], v191 offset:7168
	s_add_u32 s46, s44, 0x100
	s_addc_u32 s47, s45, 0
	s_cmp_eq_u32 s72, 12
	s_cselect_b32 s75, s43, s47
	s_cselect_b32 s74, s67, s46
	s_cselect_b32 s49, s37, s71
	s_cselect_b32 s48, s68, s69
	s_add_i32 m0, s51, 0xc000
	v_lshl_add_u64 v[184:185], s[44:45], 0, v[136:137]
	global_load_lds_dwordx4 v[184:185], off
	s_add_i32 m0, s51, 0xe000
	v_lshl_add_u64 v[184:185], s[44:45], 0, v[138:139]
	global_load_lds_dwordx4 v[184:185], off
	s_waitcnt vmcnt(8) lgkmcnt(0)
	s_setprio 1
	s_barrier
	v_mfma_f32_16x16x32_bf16 v[124:127], v[144:147], v[176:179], v[124:127]
	v_mfma_f32_16x16x32_bf16 v[120:123], v[152:155], v[176:179], v[120:123]
	v_mfma_f32_16x16x32_bf16 v[108:111], v[144:147], v[194:197], v[108:111]
	v_mfma_f32_16x16x32_bf16 v[104:107], v[152:155], v[194:197], v[104:107]
	v_mfma_f32_16x16x32_bf16 v[92:95], v[144:147], v[202:205], v[92:95]
	v_mfma_f32_16x16x32_bf16 v[88:91], v[152:155], v[202:205], v[88:91]
	v_mfma_f32_16x16x32_bf16 v[76:79], v[144:147], v[210:213], v[76:79]
	v_mfma_f32_16x16x32_bf16 v[72:75], v[152:155], v[210:213], v[72:75]
	v_mfma_f32_16x16x32_bf16 v[124:127], v[148:151], v[180:183], v[124:127]
	v_mfma_f32_16x16x32_bf16 v[120:123], v[156:159], v[180:183], v[120:123]
	v_mfma_f32_16x16x32_bf16 v[108:111], v[148:151], v[198:201], v[108:111]
	v_mfma_f32_16x16x32_bf16 v[104:107], v[156:159], v[198:201], v[104:107]
	v_mfma_f32_16x16x32_bf16 v[92:95], v[148:151], v[206:209], v[92:95]
	v_mfma_f32_16x16x32_bf16 v[88:91], v[156:159], v[206:209], v[88:91]
	v_mfma_f32_16x16x32_bf16 v[76:79], v[148:151], v[214:217], v[76:79]
	v_mfma_f32_16x16x32_bf16 v[72:75], v[156:159], v[214:217], v[72:75]
	v_mfma_f32_16x16x32_bf16 v[116:119], v[160:163], v[176:179], v[116:119]
	v_mfma_f32_16x16x32_bf16 v[112:115], v[168:171], v[176:179], v[112:115]
	v_mfma_f32_16x16x32_bf16 v[100:103], v[160:163], v[194:197], v[100:103]
	v_mfma_f32_16x16x32_bf16 v[96:99], v[168:171], v[194:197], v[96:99]
	v_mfma_f32_16x16x32_bf16 v[84:87], v[160:163], v[202:205], v[84:87]
	v_mfma_f32_16x16x32_bf16 v[80:83], v[168:171], v[202:205], v[80:83]
	v_mfma_f32_16x16x32_bf16 v[68:71], v[160:163], v[210:213], v[68:71]
	v_mfma_f32_16x16x32_bf16 v[64:67], v[168:171], v[210:213], v[64:67]
	v_mfma_f32_16x16x32_bf16 v[116:119], v[164:167], v[180:183], v[116:119]
	v_mfma_f32_16x16x32_bf16 v[112:115], v[172:175], v[180:183], v[112:115]
	v_mfma_f32_16x16x32_bf16 v[100:103], v[164:167], v[198:201], v[100:103]
	v_mfma_f32_16x16x32_bf16 v[96:99], v[172:175], v[198:201], v[96:99]
	v_mfma_f32_16x16x32_bf16 v[84:87], v[164:167], v[206:209], v[84:87]
	v_mfma_f32_16x16x32_bf16 v[80:83], v[172:175], v[206:209], v[80:83]
	v_mfma_f32_16x16x32_bf16 v[68:71], v[164:167], v[214:217], v[68:71]
	v_mfma_f32_16x16x32_bf16 v[64:67], v[172:175], v[214:217], v[64:67]
	s_barrier
	s_setprio 0
	s_add_i32 s44, s63, s50
	v_lshl_add_u64 v[184:185], s[48:49], 0, v[130:131]
	s_mov_b32 m0, s44
	ds_read_b128 v[176:179], v191 offset:16384
	ds_read_b128 v[180:183], v191 offset:17408
	ds_read_b128 v[194:197], v191 offset:18432
	ds_read_b128 v[198:201], v191 offset:19456
	ds_read_b128 v[202:205], v191 offset:20480
	ds_read_b128 v[206:209], v191 offset:21504
	ds_read_b128 v[210:213], v191 offset:22528
	ds_read_b128 v[214:217], v191 offset:23552
	global_load_lds_dwordx4 v[184:185], off
	s_add_i32 m0, s44, 0x2000
	s_add_u32 s44, s48, 0x40000
	v_lshl_add_u64 v[218:219], s[48:49], 0, v[134:135]
	s_addc_u32 s45, s49, 0
	s_add_i32 s70, s64, s50
	global_load_lds_dwordx4 v[218:219], off
	v_lshl_add_u64 v[220:221], s[44:45], 0, v[130:131]
	s_mov_b32 m0, s70
	v_lshl_add_u64 v[222:223], s[74:75], 0, v[132:133]
	global_load_lds_dwordx4 v[220:221], off
	v_lshl_add_u64 v[220:221], s[44:45], 0, v[134:135]
	s_add_i32 m0, s70, 0x2000
	v_lshl_add_u64 v[224:225], v[222:223], 0, s[12:13]
	global_load_lds_dwordx4 v[220:221], off
	s_mov_b32 m0, s51
	v_lshl_add_u64 v[220:221], s[74:75], 0, v[128:129]
	global_load_lds_dwordx4 v[220:221], off
	s_mov_b32 m0, s52
	s_nop 0
	global_load_lds_dwordx4 v[224:225], off
	s_waitcnt vmcnt(8) lgkmcnt(0)
	s_setprio 1
	s_barrier
	v_mfma_f32_16x16x32_bf16 v[60:63], v[144:147], v[176:179], v[60:63]
	v_mfma_f32_16x16x32_bf16 v[56:59], v[152:155], v[176:179], v[56:59]
	v_mfma_f32_16x16x32_bf16 v[44:47], v[144:147], v[194:197], v[44:47]
	v_mfma_f32_16x16x32_bf16 v[40:43], v[152:155], v[194:197], v[40:43]
	v_mfma_f32_16x16x32_bf16 v[28:31], v[144:147], v[202:205], v[28:31]
	v_mfma_f32_16x16x32_bf16 v[24:27], v[152:155], v[202:205], v[24:27]
	v_mfma_f32_16x16x32_bf16 v[12:15], v[144:147], v[210:213], v[12:15]
	v_mfma_f32_16x16x32_bf16 v[8:11], v[152:155], v[210:213], v[8:11]
	v_mfma_f32_16x16x32_bf16 v[60:63], v[148:151], v[180:183], v[60:63]
	v_mfma_f32_16x16x32_bf16 v[56:59], v[156:159], v[180:183], v[56:59]
	v_mfma_f32_16x16x32_bf16 v[44:47], v[148:151], v[198:201], v[44:47]
	v_mfma_f32_16x16x32_bf16 v[40:43], v[156:159], v[198:201], v[40:43]
	v_mfma_f32_16x16x32_bf16 v[28:31], v[148:151], v[206:209], v[28:31]
	v_mfma_f32_16x16x32_bf16 v[24:27], v[156:159], v[206:209], v[24:27]
	v_mfma_f32_16x16x32_bf16 v[12:15], v[148:151], v[214:217], v[12:15]
	v_mfma_f32_16x16x32_bf16 v[8:11], v[156:159], v[214:217], v[8:11]
	v_mfma_f32_16x16x32_bf16 v[52:55], v[160:163], v[176:179], v[52:55]
	v_mfma_f32_16x16x32_bf16 v[48:51], v[168:171], v[176:179], v[48:51]
	v_mfma_f32_16x16x32_bf16 v[36:39], v[160:163], v[194:197], v[36:39]
	v_mfma_f32_16x16x32_bf16 v[32:35], v[168:171], v[194:197], v[32:35]
	v_mfma_f32_16x16x32_bf16 v[20:23], v[160:163], v[202:205], v[20:23]
	v_mfma_f32_16x16x32_bf16 v[16:19], v[168:171], v[202:205], v[16:19]
	v_mfma_f32_16x16x32_bf16 v[4:7], v[160:163], v[210:213], v[4:7]
	v_mfma_f32_16x16x32_bf16 v[0:3], v[168:171], v[210:213], v[0:3]
	v_mfma_f32_16x16x32_bf16 v[52:55], v[164:167], v[180:183], v[52:55]
	v_mfma_f32_16x16x32_bf16 v[48:51], v[172:175], v[180:183], v[48:51]
	v_mfma_f32_16x16x32_bf16 v[36:39], v[164:167], v[198:201], v[36:39]
	v_mfma_f32_16x16x32_bf16 v[32:35], v[172:175], v[198:201], v[32:35]
	v_mfma_f32_16x16x32_bf16 v[20:23], v[164:167], v[206:209], v[20:23]
	v_mfma_f32_16x16x32_bf16 v[16:19], v[172:175], v[206:209], v[16:19]
	v_mfma_f32_16x16x32_bf16 v[4:7], v[164:167], v[214:217], v[4:7]
	v_mfma_f32_16x16x32_bf16 v[0:3], v[172:175], v[214:217], v[0:3]
	s_barrier
	s_setprio 0
	s_add_i32 s44, 0, 0x18000
	s_add_i32 s70, 0, 0x1c000
	v_add_u32_e32 v156, s44, v187
	v_add_u32_e32 v172, s70, v187
	ds_read_b128 v[144:147], v156
	ds_read_b128 v[148:151], v156 offset:1024
	ds_read_b128 v[152:155], v156 offset:2048
	ds_read_b128 v[156:159], v156 offset:3072
	ds_read_b128 v[160:163], v172
	ds_read_b128 v[164:167], v172 offset:1024
	ds_read_b128 v[168:171], v172 offset:2048
	ds_read_b128 v[172:175], v172 offset:3072
	s_mov_b32 m0, s53
	v_lshl_add_u64 v[224:225], v[220:221], 0, s[10:11]
	ds_read_b128 v[176:179], v191 offset:32768
	ds_read_b128 v[180:183], v191 offset:33792
	ds_read_b128 v[194:197], v191 offset:34816
	ds_read_b128 v[198:201], v191 offset:35840
	ds_read_b128 v[202:205], v191 offset:36864
	ds_read_b128 v[206:209], v191 offset:37888
	ds_read_b128 v[210:213], v191 offset:38912
	ds_read_b128 v[214:217], v191 offset:39936
	global_load_lds_dwordx4 v[224:225], off
	s_mov_b32 m0, s54
	v_lshl_add_u64 v[224:225], v[222:223], 0, s[14:15]
	global_load_lds_dwordx4 v[224:225], off
	s_waitcnt vmcnt(8) lgkmcnt(0)
	s_setprio 1
	s_barrier
	v_mfma_f32_16x16x32_bf16 v[124:127], v[144:147], v[176:179], v[124:127]
	v_mfma_f32_16x16x32_bf16 v[120:123], v[152:155], v[176:179], v[120:123]
	v_mfma_f32_16x16x32_bf16 v[108:111], v[144:147], v[194:197], v[108:111]
	v_mfma_f32_16x16x32_bf16 v[104:107], v[152:155], v[194:197], v[104:107]
	v_mfma_f32_16x16x32_bf16 v[92:95], v[144:147], v[202:205], v[92:95]
	v_mfma_f32_16x16x32_bf16 v[88:91], v[152:155], v[202:205], v[88:91]
	v_mfma_f32_16x16x32_bf16 v[76:79], v[144:147], v[210:213], v[76:79]
	v_mfma_f32_16x16x32_bf16 v[72:75], v[152:155], v[210:213], v[72:75]
	v_mfma_f32_16x16x32_bf16 v[124:127], v[148:151], v[180:183], v[124:127]
	v_mfma_f32_16x16x32_bf16 v[120:123], v[156:159], v[180:183], v[120:123]
	v_mfma_f32_16x16x32_bf16 v[108:111], v[148:151], v[198:201], v[108:111]
	v_mfma_f32_16x16x32_bf16 v[104:107], v[156:159], v[198:201], v[104:107]
	v_mfma_f32_16x16x32_bf16 v[92:95], v[148:151], v[206:209], v[92:95]
	v_mfma_f32_16x16x32_bf16 v[88:91], v[156:159], v[206:209], v[88:91]
	v_mfma_f32_16x16x32_bf16 v[76:79], v[148:151], v[214:217], v[76:79]
	v_mfma_f32_16x16x32_bf16 v[72:75], v[156:159], v[214:217], v[72:75]
	v_mfma_f32_16x16x32_bf16 v[116:119], v[160:163], v[176:179], v[116:119]
	v_mfma_f32_16x16x32_bf16 v[112:115], v[168:171], v[176:179], v[112:115]
	v_mfma_f32_16x16x32_bf16 v[100:103], v[160:163], v[194:197], v[100:103]
	v_mfma_f32_16x16x32_bf16 v[96:99], v[168:171], v[194:197], v[96:99]
	v_mfma_f32_16x16x32_bf16 v[84:87], v[160:163], v[202:205], v[84:87]
	v_mfma_f32_16x16x32_bf16 v[80:83], v[168:171], v[202:205], v[80:83]
	v_mfma_f32_16x16x32_bf16 v[68:71], v[160:163], v[210:213], v[68:71]
	v_mfma_f32_16x16x32_bf16 v[64:67], v[168:171], v[210:213], v[64:67]
	v_mfma_f32_16x16x32_bf16 v[116:119], v[164:167], v[180:183], v[116:119]
	v_mfma_f32_16x16x32_bf16 v[112:115], v[172:175], v[180:183], v[112:115]
	v_mfma_f32_16x16x32_bf16 v[100:103], v[164:167], v[198:201], v[100:103]
	v_mfma_f32_16x16x32_bf16 v[96:99], v[172:175], v[198:201], v[96:99]
	v_mfma_f32_16x16x32_bf16 v[84:87], v[164:167], v[206:209], v[84:87]
	v_mfma_f32_16x16x32_bf16 v[80:83], v[172:175], v[206:209], v[80:83]
	v_mfma_f32_16x16x32_bf16 v[68:71], v[164:167], v[214:217], v[68:71]
	v_mfma_f32_16x16x32_bf16 v[64:67], v[172:175], v[214:217], v[64:67]
	s_barrier
	s_setprio 0
	s_add_i32 s44, s44, s50
	v_lshl_add_u64 v[184:185], v[184:185], 0, s[24:25]
	s_mov_b32 m0, s44
	ds_read_b128 v[176:179], v191 offset:49152
	ds_read_b128 v[180:183], v191 offset:50176
	ds_read_b128 v[194:197], v191 offset:51200
	ds_read_b128 v[198:201], v191 offset:52224
	ds_read_b128 v[202:205], v191 offset:53248
	ds_read_b128 v[206:209], v191 offset:54272
	ds_read_b128 v[210:213], v191 offset:55296
	ds_read_b128 v[214:217], v191 offset:56320
	global_load_lds_dwordx4 v[184:185], off
	s_add_i32 m0, s44, 0x2000
	s_add_u32 s44, s48, 0x40080
	v_lshl_add_u64 v[184:185], v[218:219], 0, s[24:25]
	s_addc_u32 s45, s49, 0
	s_add_i32 s48, s70, s50
	global_load_lds_dwordx4 v[184:185], off
	s_mov_b32 m0, s48
	v_lshl_add_u64 v[184:185], s[44:45], 0, v[130:131]
	global_load_lds_dwordx4 v[184:185], off
	s_add_i32 m0, s48, 0x2000
	v_lshl_add_u64 v[184:185], s[44:45], 0, v[134:135]
	global_load_lds_dwordx4 v[184:185], off
	s_mov_b32 m0, s58
	v_lshl_add_u64 v[184:185], v[220:221], 0, s[24:25]
	global_load_lds_dwordx4 v[184:185], off
	s_mov_b32 m0, s59
	v_lshl_add_u64 v[184:185], v[222:223], 0, s[30:31]
	global_load_lds_dwordx4 v[184:185], off
	s_waitcnt vmcnt(8) lgkmcnt(0)
	s_setprio 1
	s_barrier
	v_mfma_f32_16x16x32_bf16 v[60:63], v[144:147], v[176:179], v[60:63]
	v_mfma_f32_16x16x32_bf16 v[56:59], v[152:155], v[176:179], v[56:59]
	v_mfma_f32_16x16x32_bf16 v[44:47], v[144:147], v[194:197], v[44:47]
	v_mfma_f32_16x16x32_bf16 v[40:43], v[152:155], v[194:197], v[40:43]
	v_mfma_f32_16x16x32_bf16 v[28:31], v[144:147], v[202:205], v[28:31]
	v_mfma_f32_16x16x32_bf16 v[24:27], v[152:155], v[202:205], v[24:27]
	v_mfma_f32_16x16x32_bf16 v[12:15], v[144:147], v[210:213], v[12:15]
	v_mfma_f32_16x16x32_bf16 v[8:11], v[152:155], v[210:213], v[8:11]
	v_mfma_f32_16x16x32_bf16 v[60:63], v[148:151], v[180:183], v[60:63]
	v_mfma_f32_16x16x32_bf16 v[56:59], v[156:159], v[180:183], v[56:59]
	v_mfma_f32_16x16x32_bf16 v[44:47], v[148:151], v[198:201], v[44:47]
	v_mfma_f32_16x16x32_bf16 v[40:43], v[156:159], v[198:201], v[40:43]
	v_mfma_f32_16x16x32_bf16 v[28:31], v[148:151], v[206:209], v[28:31]
	v_mfma_f32_16x16x32_bf16 v[24:27], v[156:159], v[206:209], v[24:27]
	v_mfma_f32_16x16x32_bf16 v[12:15], v[148:151], v[214:217], v[12:15]
	v_mfma_f32_16x16x32_bf16 v[8:11], v[156:159], v[214:217], v[8:11]
	v_mfma_f32_16x16x32_bf16 v[52:55], v[160:163], v[176:179], v[52:55]
	v_mfma_f32_16x16x32_bf16 v[48:51], v[168:171], v[176:179], v[48:51]
	v_mfma_f32_16x16x32_bf16 v[36:39], v[160:163], v[194:197], v[36:39]
	v_mfma_f32_16x16x32_bf16 v[32:35], v[168:171], v[194:197], v[32:35]
	v_mfma_f32_16x16x32_bf16 v[20:23], v[160:163], v[202:205], v[20:23]
	v_mfma_f32_16x16x32_bf16 v[16:19], v[168:171], v[202:205], v[16:19]
	v_mfma_f32_16x16x32_bf16 v[4:7], v[160:163], v[210:213], v[4:7]
	v_mfma_f32_16x16x32_bf16 v[0:3], v[168:171], v[210:213], v[0:3]
	v_mfma_f32_16x16x32_bf16 v[52:55], v[164:167], v[180:183], v[52:55]
	v_mfma_f32_16x16x32_bf16 v[48:51], v[172:175], v[180:183], v[48:51]
	v_mfma_f32_16x16x32_bf16 v[36:39], v[164:167], v[198:201], v[36:39]
	v_mfma_f32_16x16x32_bf16 v[32:35], v[172:175], v[198:201], v[32:35]
	v_mfma_f32_16x16x32_bf16 v[20:23], v[164:167], v[206:209], v[20:23]
	v_mfma_f32_16x16x32_bf16 v[16:19], v[172:175], v[206:209], v[16:19]
	v_mfma_f32_16x16x32_bf16 v[4:7], v[164:167], v[214:217], v[4:7]
	v_mfma_f32_16x16x32_bf16 v[0:3], v[172:175], v[214:217], v[0:3]
	s_barrier
	s_setprio 0
	s_add_i32 s72, s72, 2
	s_add_u32 s69, s69, 0x100
	s_addc_u32 s71, s71, 0
	s_cmp_gt_u32 s72, 13
	s_mov_b64 s[44:45], s[46:47]
	s_cbranch_scc0 .LBB0_751
	s_and_b64 vcc, exec, s[34:35]
	s_cbranch_vccz .LBB0_754
	s_barrier
